# non-temporal (nt) cache policy on read-once streaming loads: P0 LN_in input rows and weight-transpose source loads, P6/P9 residual loads
# speedup vs baseline: 1.0167x; 1.0167x over previous
.LBB0_11:
	s_cmpk_gt_i32 s39, 0xaff
	s_mov_b64 s[4:5], -1
	s_cbranch_scc0 .LBB0_37
	s_cmpk_gt_u32 s39, 0x114f
	s_cbranch_scc0 .LBB0_34
	s_cmpk_gt_u32 s39, 0x16cf
	s_cbranch_scc0 .LBB0_31
	s_cmpk_gt_u32 s39, 0x18cf
	s_cbranch_scc0 .LBB0_28
	s_cmpk_gt_u32 s39, 0x19cf
	s_cbranch_scc0 .LBB0_25
	s_cmpk_gt_u32 s39, 0x1a5f
	s_cbranch_scc0 .LBB0_22
	s_and_b32 s6, s28, 0x1e0
	s_cmpk_gt_u32 s39, 0x1a9f
	s_cbranch_scc0 .LBB0_19
	s_and_b32 s4, s30, 0x3c0
	s_lshl_b32 s0, s6, 2
	v_or_b32_e32 v2, s4, v1
	v_lshl_add_u64 v[34:35], v[18:19], 0, s[0:1]
	v_lshlrev_b32_e32 v2, 11, v2
	v_lshl_add_u64 v[78:79], v[34:35], 0, v[2:3]
	v_or_b32_e32 v2, s4, v38
	v_lshlrev_b32_e32 v2, 11, v2
	v_lshl_add_u64 v[80:81], v[34:35], 0, v[2:3]
	v_or_b32_e32 v2, s4, v39
	v_lshlrev_b32_e32 v2, 11, v2
	v_lshl_add_u64 v[82:83], v[34:35], 0, v[2:3]
	v_or_b32_e32 v2, s4, v40
	v_lshlrev_b32_e32 v2, 11, v2
	v_lshl_add_u64 v[84:85], v[34:35], 0, v[2:3]
	v_or_b32_e32 v2, s4, v41
	v_lshlrev_b32_e32 v2, 11, v2
	v_lshl_add_u64 v[86:87], v[34:35], 0, v[2:3]
	v_or_b32_e32 v2, s4, v42
	v_lshlrev_b32_e32 v2, 11, v2
	v_lshl_add_u64 v[88:89], v[34:35], 0, v[2:3]
	v_or_b32_e32 v2, s4, v43
	v_lshlrev_b32_e32 v2, 11, v2
	v_lshl_add_u64 v[90:91], v[34:35], 0, v[2:3]
	v_or_b32_e32 v2, s4, v45
	v_lshlrev_b32_e32 v2, 11, v2
	v_lshl_add_u64 v[92:93], v[34:35], 0, v[2:3]
	v_or_b32_e32 v2, s4, v46
	v_lshlrev_b32_e32 v2, 11, v2
	global_load_dword v94, v[78:79], off nt
	global_load_dword v95, v[80:81], off nt
	global_load_dword v96, v[82:83], off nt
	global_load_dword v97, v[84:85], off nt
	global_load_dword v98, v[86:87], off nt
	global_load_dword v99, v[88:89], off nt
	global_load_dword v100, v[90:91], off nt
	global_load_dword v101, v[92:93], off nt
	v_lshl_add_u64 v[78:79], v[34:35], 0, v[2:3]
	v_or_b32_e32 v2, s4, v47
	v_lshlrev_b32_e32 v2, 11, v2
	v_lshl_add_u64 v[80:81], v[34:35], 0, v[2:3]
	v_or_b32_e32 v2, s4, v48
	v_lshlrev_b32_e32 v2, 11, v2
	v_lshl_add_u64 v[82:83], v[34:35], 0, v[2:3]
	v_or_b32_e32 v2, s4, v49
	v_lshlrev_b32_e32 v2, 11, v2
	v_lshl_add_u64 v[84:85], v[34:35], 0, v[2:3]
	v_or_b32_e32 v2, s4, v50
	v_lshlrev_b32_e32 v2, 11, v2
	v_lshl_add_u64 v[86:87], v[34:35], 0, v[2:3]
	v_or_b32_e32 v2, s4, v52
	v_lshlrev_b32_e32 v2, 11, v2
	v_lshl_add_u64 v[88:89], v[34:35], 0, v[2:3]
	v_or_b32_e32 v2, s4, v53
	v_lshlrev_b32_e32 v2, 11, v2
	v_lshl_add_u64 v[90:91], v[34:35], 0, v[2:3]
	v_or_b32_e32 v2, s4, v54
	v_lshlrev_b32_e32 v2, 11, v2
	v_lshl_add_u64 v[92:93], v[34:35], 0, v[2:3]
	v_or_b32_e32 v2, s4, v55
	v_lshlrev_b32_e32 v2, 11, v2
	global_load_dword v102, v[78:79], off nt
	global_load_dword v103, v[80:81], off nt
	global_load_dword v104, v[82:83], off nt
	global_load_dword v105, v[84:85], off nt
	global_load_dword v106, v[86:87], off nt
	global_load_dword v107, v[88:89], off nt
	global_load_dword v108, v[90:91], off nt
	global_load_dword v109, v[92:93], off nt
	v_lshl_add_u64 v[78:79], v[34:35], 0, v[2:3]
	v_or_b32_e32 v2, s4, v56
	v_lshlrev_b32_e32 v2, 11, v2
	v_lshl_add_u64 v[80:81], v[34:35], 0, v[2:3]
	v_or_b32_e32 v2, s4, v57
	v_lshlrev_b32_e32 v2, 11, v2
	v_lshl_add_u64 v[82:83], v[34:35], 0, v[2:3]
	v_or_b32_e32 v2, s4, v59
	v_lshlrev_b32_e32 v2, 11, v2
	v_lshl_add_u64 v[84:85], v[34:35], 0, v[2:3]
	v_or_b32_e32 v2, s4, v60
	v_lshlrev_b32_e32 v2, 11, v2
	v_lshl_add_u64 v[86:87], v[34:35], 0, v[2:3]
	v_or_b32_e32 v2, s4, v61
	v_lshlrev_b32_e32 v2, 11, v2
	v_lshl_add_u64 v[88:89], v[34:35], 0, v[2:3]
	v_or_b32_e32 v2, s4, v62
	v_lshlrev_b32_e32 v2, 11, v2
	v_lshl_add_u64 v[90:91], v[34:35], 0, v[2:3]
	v_or_b32_e32 v2, s4, v63
	v_lshlrev_b32_e32 v2, 11, v2
	v_lshl_add_u64 v[92:93], v[34:35], 0, v[2:3]
	v_or_b32_e32 v2, s4, v64
	v_lshlrev_b32_e32 v2, 11, v2
	global_load_dword v110, v[78:79], off nt
	global_load_dword v111, v[80:81], off nt
	global_load_dword v112, v[82:83], off nt
	global_load_dword v113, v[84:85], off nt
	global_load_dword v114, v[86:87], off nt
	global_load_dword v115, v[88:89], off nt
	global_load_dword v116, v[90:91], off nt
	s_nop 0
	global_load_dword v92, v[92:93], off nt
	v_lshl_add_u64 v[78:79], v[34:35], 0, v[2:3]
	v_or_b32_e32 v2, s4, v66
	v_lshlrev_b32_e32 v2, 11, v2
	v_lshl_add_u64 v[80:81], v[34:35], 0, v[2:3]
	v_or_b32_e32 v2, s4, v67
	v_lshlrev_b32_e32 v2, 11, v2
	v_lshl_add_u64 v[82:83], v[34:35], 0, v[2:3]
	v_or_b32_e32 v2, s4, v68
	v_lshlrev_b32_e32 v2, 11, v2
	v_lshl_add_u64 v[84:85], v[34:35], 0, v[2:3]
	v_or_b32_e32 v2, s4, v69
	v_lshlrev_b32_e32 v2, 11, v2
	v_lshl_add_u64 v[86:87], v[34:35], 0, v[2:3]
	v_or_b32_e32 v2, s4, v70
	v_lshlrev_b32_e32 v2, 11, v2
	v_lshl_add_u64 v[88:89], v[34:35], 0, v[2:3]
	v_or_b32_e32 v2, s4, v71
	v_lshlrev_b32_e32 v2, 11, v2
	v_lshl_add_u64 v[90:91], v[34:35], 0, v[2:3]
	v_or_b32_e32 v2, s4, v72
	v_lshlrev_b32_e32 v2, 11, v2
	v_lshl_add_u64 v[34:35], v[34:35], 0, v[2:3]
	global_load_dword v2, v[78:79], off nt
	s_nop 0
	global_load_dword v78, v[80:81], off nt
	global_load_dword v79, v[82:83], off nt
	s_nop 0
	global_load_dword v80, v[84:85], off nt
	global_load_dword v81, v[86:87], off nt
	global_load_dword v82, v[88:89], off nt
	global_load_dword v83, v[90:91], off nt
	s_nop 0
	global_load_dword v34, v[34:35], off nt
	v_add_u32_e32 v35, v36, v37
	s_waitcnt vmcnt(30)
	ds_write2_b32 v35, v94, v95 offset1:66
	s_waitcnt vmcnt(28)
	ds_write2_b32 v35, v96, v97 offset0:132 offset1:198
	v_add_u32_e32 v35, 0x400, v35
	s_waitcnt vmcnt(26)
	ds_write2_b32 v35, v98, v99 offset0:8 offset1:74
	v_add_u32_e32 v35, v36, v44
	s_waitcnt vmcnt(24)
	ds_write2_b32 v35, v100, v101 offset1:66
	s_waitcnt vmcnt(22)
	ds_write2_b32 v35, v102, v103 offset0:132 offset1:198
	v_add_u32_e32 v35, 0x400, v35
	s_waitcnt vmcnt(20)
	ds_write2_b32 v35, v104, v105 offset0:8 offset1:74
	v_add_u32_e32 v35, v36, v51
	s_waitcnt vmcnt(18)
	ds_write2_b32 v35, v106, v107 offset1:66
	s_waitcnt vmcnt(16)
	ds_write2_b32 v35, v108, v109 offset0:132 offset1:198
	v_add_u32_e32 v35, 0x400, v35
	s_or_b32 s5, s6, 0x200
	s_lshl_b32 s0, s4, 1
	s_waitcnt vmcnt(14)
	ds_write2_b32 v35, v110, v111 offset0:8 offset1:74
	v_add_u32_e32 v35, v36, v58
	s_waitcnt vmcnt(12)
	ds_write2_b32 v35, v112, v113 offset1:66
	s_waitcnt vmcnt(10)
	ds_write2_b32 v35, v114, v115 offset0:132 offset1:198
	v_add_u32_e32 v35, 0x400, v35
	s_waitcnt vmcnt(8)
	ds_write2_b32 v35, v116, v92 offset0:8 offset1:74
	v_add_u32_e32 v35, v36, v65
	s_waitcnt vmcnt(6)
	ds_write2_b32 v35, v2, v78 offset1:66
	s_waitcnt vmcnt(4)
	ds_write2_b32 v35, v79, v80 offset0:132 offset1:198
	v_add_u32_e32 v2, 0x400, v35
	s_waitcnt vmcnt(2)
	ds_write2_b32 v2, v81, v82 offset0:8 offset1:74
	s_waitcnt vmcnt(0)
	ds_write2_b32 v2, v83, v34 offset0:140 offset1:206
	s_waitcnt lgkmcnt(0)
	ds_read2_b32 v[34:35], v74 offset1:8
	ds_read2_b32 v[84:85], v74 offset0:33 offset1:41
	ds_read2_b32 v[86:87], v74 offset0:66 offset1:74
	ds_read2_b32 v[88:89], v74 offset0:99 offset1:107
	ds_read2_b32 v[90:91], v74 offset0:132 offset1:140
	s_waitcnt lgkmcnt(4)
	v_bfe_u32 v2, v34, 16, 1
	v_add3_u32 v2, v34, v2, s35
	s_waitcnt lgkmcnt(3)
	v_bfe_u32 v34, v84, 16, 1
	v_lshrrev_b32_e32 v2, 16, v2
	v_add3_u32 v34, v84, v34, s35
	ds_read2_b32 v[92:93], v74 offset0:165 offset1:173
	v_and_or_b32 v78, v34, s36, v2
	s_waitcnt lgkmcnt(3)
	v_bfe_u32 v2, v86, 16, 1
	v_add3_u32 v2, v86, v2, s35
	s_waitcnt lgkmcnt(2)
	v_bfe_u32 v34, v88, 16, 1
	ds_read2_b32 v[94:95], v74 offset0:198 offset1:206
	v_lshrrev_b32_e32 v2, 16, v2
	v_add3_u32 v34, v88, v34, s35
	ds_read2_b32 v[96:97], v74 offset0:231 offset1:239
	v_and_or_b32 v79, v34, s36, v2
	s_waitcnt lgkmcnt(3)
	v_bfe_u32 v2, v90, 16, 1
	v_add3_u32 v2, v90, v2, s35
	s_waitcnt lgkmcnt(2)
	v_bfe_u32 v34, v92, 16, 1
	v_lshrrev_b32_e32 v2, 16, v2
	v_add3_u32 v34, v92, v34, s35
	v_and_or_b32 v80, v34, s36, v2
	s_waitcnt lgkmcnt(1)
	v_bfe_u32 v2, v94, 16, 1
	v_add3_u32 v2, v94, v2, s35
	s_waitcnt lgkmcnt(0)
	v_bfe_u32 v34, v96, 16, 1
	v_lshrrev_b32_e32 v2, 16, v2
	v_add3_u32 v34, v96, v34, s35
	v_and_or_b32 v81, v34, s36, v2
	v_or_b32_e32 v2, s5, v73
	v_lshl_add_u64 v[82:83], v[4:5], 0, s[0:1]
	v_lshlrev_b32_e32 v2, 9, v2
	v_lshl_add_u64 v[98:99], v[82:83], 0, v[2:3]
	v_bfe_u32 v2, v35, 16, 1
	v_add3_u32 v2, v35, v2, s35
	v_bfe_u32 v34, v85, 16, 1
	v_lshrrev_b32_e32 v2, 16, v2
	v_add3_u32 v34, v85, v34, s35
	global_store_dwordx4 v[98:99], v[78:81], off
	s_nop 1
	v_and_or_b32 v78, v34, s36, v2
	v_bfe_u32 v2, v87, 16, 1
	v_add3_u32 v2, v87, v2, s35
	v_bfe_u32 v34, v89, 16, 1
	v_lshrrev_b32_e32 v2, 16, v2
	v_add3_u32 v34, v89, v34, s35
	v_and_or_b32 v79, v34, s36, v2
	v_bfe_u32 v2, v91, 16, 1
	v_add3_u32 v2, v91, v2, s35
	v_bfe_u32 v34, v93, 16, 1
	v_lshrrev_b32_e32 v2, 16, v2
	v_add3_u32 v34, v93, v34, s35
	v_and_or_b32 v80, v34, s36, v2
	v_bfe_u32 v2, v95, 16, 1
	v_add3_u32 v2, v95, v2, s35
	v_bfe_u32 v34, v97, 16, 1
	v_lshrrev_b32_e32 v2, 16, v2
	v_add3_u32 v34, v97, v34, s35
	v_and_or_b32 v81, v34, s36, v2
	v_or_b32_e32 v2, s5, v75
	v_lshlrev_b32_e32 v2, 9, v2
	ds_read2_b32 v[34:35], v74 offset0:16 offset1:24
	v_lshl_add_u64 v[84:85], v[82:83], 0, v[2:3]
	global_store_dwordx4 v[84:85], v[78:81], off
	ds_read2_b32 v[84:85], v74 offset0:49 offset1:57
	ds_read2_b32 v[86:87], v74 offset0:82 offset1:90
	ds_read2_b32 v[88:89], v74 offset0:115 offset1:123
	s_waitcnt lgkmcnt(3)
	v_bfe_u32 v2, v34, 16, 1
	v_add3_u32 v2, v34, v2, s35
	s_waitcnt lgkmcnt(2)
	v_bfe_u32 v34, v84, 16, 1
	ds_read2_b32 v[90:91], v74 offset0:148 offset1:156
	v_lshrrev_b32_e32 v2, 16, v2
	v_add3_u32 v34, v84, v34, s35
	ds_read2_b32 v[92:93], v74 offset0:181 offset1:189
	v_and_or_b32 v78, v34, s36, v2
	s_waitcnt lgkmcnt(3)
	v_bfe_u32 v2, v86, 16, 1
	v_add3_u32 v2, v86, v2, s35
	s_waitcnt lgkmcnt(2)
	v_bfe_u32 v34, v88, 16, 1
	ds_read2_b32 v[94:95], v74 offset0:214 offset1:222
	v_lshrrev_b32_e32 v2, 16, v2
	v_add3_u32 v34, v88, v34, s35
	ds_read2_b32 v[96:97], v74 offset0:247 offset1:255
	v_and_or_b32 v79, v34, s36, v2
	s_waitcnt lgkmcnt(3)
	v_bfe_u32 v2, v90, 16, 1
	v_add3_u32 v2, v90, v2, s35
	s_waitcnt lgkmcnt(2)
	v_bfe_u32 v34, v92, 16, 1
	v_lshrrev_b32_e32 v2, 16, v2
	v_add3_u32 v34, v92, v34, s35
	v_and_or_b32 v80, v34, s36, v2
	s_waitcnt lgkmcnt(1)
	v_bfe_u32 v2, v94, 16, 1
	v_add3_u32 v2, v94, v2, s35
	s_waitcnt lgkmcnt(0)
	v_bfe_u32 v34, v96, 16, 1
	v_lshrrev_b32_e32 v2, 16, v2
	v_add3_u32 v34, v96, v34, s35
	v_and_or_b32 v81, v34, s36, v2
	v_or_b32_e32 v2, s5, v76
	v_lshlrev_b32_e32 v2, 9, v2
	v_lshl_add_u64 v[98:99], v[82:83], 0, v[2:3]
	v_bfe_u32 v2, v35, 16, 1
	v_add3_u32 v2, v35, v2, s35
	v_bfe_u32 v34, v85, 16, 1
	v_lshrrev_b32_e32 v2, 16, v2
	v_add3_u32 v34, v85, v34, s35
	global_store_dwordx4 v[98:99], v[78:81], off
	s_nop 1
	v_and_or_b32 v78, v34, s36, v2
	v_bfe_u32 v2, v87, 16, 1
	v_add3_u32 v2, v87, v2, s35
	v_bfe_u32 v34, v89, 16, 1
	v_lshrrev_b32_e32 v2, 16, v2
	v_add3_u32 v34, v89, v34, s35
	v_and_or_b32 v79, v34, s36, v2
	v_bfe_u32 v2, v91, 16, 1
	v_add3_u32 v2, v91, v2, s35
	v_bfe_u32 v34, v93, 16, 1
	v_lshrrev_b32_e32 v2, 16, v2
	v_add3_u32 v34, v93, v34, s35
	v_and_or_b32 v80, v34, s36, v2
	v_bfe_u32 v2, v95, 16, 1
	v_add3_u32 v2, v95, v2, s35
	v_bfe_u32 v34, v97, 16, 1
	v_lshrrev_b32_e32 v2, 16, v2
	v_add3_u32 v34, v97, v34, s35
	v_and_or_b32 v81, v34, s36, v2
	v_or_b32_e32 v2, s5, v77
	v_lshlrev_b32_e32 v2, 9, v2
	v_lshl_add_u64 v[34:35], v[82:83], 0, v[2:3]
	global_store_dwordx4 v[34:35], v[78:81], off
	s_waitcnt lgkmcnt(0)
	s_mov_b64 s[4:5], 0
.LBB0_19:
	s_andn2_b64 vcc, exec, s[4:5]
	s_cbranch_vccnz .LBB0_21
	s_add_i32 s0, s30, 0x100
	s_and_b32 s4, s0, 0x3c0
	s_lshl_b32 s0, s6, 2
	v_or_b32_e32 v2, s4, v1
	v_lshl_add_u64 v[34:35], v[20:21], 0, s[0:1]
	v_lshlrev_b32_e32 v2, 11, v2
	v_lshl_add_u64 v[78:79], v[34:35], 0, v[2:3]
	v_or_b32_e32 v2, s4, v38
	v_lshlrev_b32_e32 v2, 11, v2
	v_lshl_add_u64 v[80:81], v[34:35], 0, v[2:3]
	v_or_b32_e32 v2, s4, v39
	v_lshlrev_b32_e32 v2, 11, v2
	v_lshl_add_u64 v[82:83], v[34:35], 0, v[2:3]
	v_or_b32_e32 v2, s4, v40
	v_lshlrev_b32_e32 v2, 11, v2
	v_lshl_add_u64 v[84:85], v[34:35], 0, v[2:3]
	v_or_b32_e32 v2, s4, v41
	v_lshlrev_b32_e32 v2, 11, v2
	v_lshl_add_u64 v[86:87], v[34:35], 0, v[2:3]
	v_or_b32_e32 v2, s4, v42
	v_lshlrev_b32_e32 v2, 11, v2
	v_lshl_add_u64 v[88:89], v[34:35], 0, v[2:3]
	v_or_b32_e32 v2, s4, v43
	v_lshlrev_b32_e32 v2, 11, v2
	v_lshl_add_u64 v[90:91], v[34:35], 0, v[2:3]
	v_or_b32_e32 v2, s4, v45
	v_lshlrev_b32_e32 v2, 11, v2
	v_lshl_add_u64 v[92:93], v[34:35], 0, v[2:3]
	v_or_b32_e32 v2, s4, v46
	v_lshlrev_b32_e32 v2, 11, v2
	global_load_dword v94, v[78:79], off nt
	global_load_dword v95, v[80:81], off nt
	global_load_dword v96, v[82:83], off nt
	global_load_dword v97, v[84:85], off nt
	global_load_dword v98, v[86:87], off nt
	global_load_dword v99, v[88:89], off nt
	global_load_dword v100, v[90:91], off nt
	global_load_dword v101, v[92:93], off nt
	v_lshl_add_u64 v[78:79], v[34:35], 0, v[2:3]
	v_or_b32_e32 v2, s4, v47
	v_lshlrev_b32_e32 v2, 11, v2
	v_lshl_add_u64 v[80:81], v[34:35], 0, v[2:3]
	v_or_b32_e32 v2, s4, v48
	v_lshlrev_b32_e32 v2, 11, v2
	v_lshl_add_u64 v[82:83], v[34:35], 0, v[2:3]
	v_or_b32_e32 v2, s4, v49
	v_lshlrev_b32_e32 v2, 11, v2
	v_lshl_add_u64 v[84:85], v[34:35], 0, v[2:3]
	v_or_b32_e32 v2, s4, v50
	v_lshlrev_b32_e32 v2, 11, v2
	v_lshl_add_u64 v[86:87], v[34:35], 0, v[2:3]
	v_or_b32_e32 v2, s4, v52
	v_lshlrev_b32_e32 v2, 11, v2
	v_lshl_add_u64 v[88:89], v[34:35], 0, v[2:3]
	v_or_b32_e32 v2, s4, v53
	v_lshlrev_b32_e32 v2, 11, v2
	v_lshl_add_u64 v[90:91], v[34:35], 0, v[2:3]
	v_or_b32_e32 v2, s4, v54
	v_lshlrev_b32_e32 v2, 11, v2
	v_lshl_add_u64 v[92:93], v[34:35], 0, v[2:3]
	v_or_b32_e32 v2, s4, v55
	v_lshlrev_b32_e32 v2, 11, v2
	global_load_dword v102, v[78:79], off nt
	global_load_dword v103, v[80:81], off nt
	global_load_dword v104, v[82:83], off nt
	global_load_dword v105, v[84:85], off nt
	global_load_dword v106, v[86:87], off nt
	global_load_dword v107, v[88:89], off nt
	global_load_dword v108, v[90:91], off nt
	global_load_dword v109, v[92:93], off nt
	v_lshl_add_u64 v[78:79], v[34:35], 0, v[2:3]
	v_or_b32_e32 v2, s4, v56
	v_lshlrev_b32_e32 v2, 11, v2
	v_lshl_add_u64 v[80:81], v[34:35], 0, v[2:3]
	v_or_b32_e32 v2, s4, v57
	v_lshlrev_b32_e32 v2, 11, v2
	v_lshl_add_u64 v[82:83], v[34:35], 0, v[2:3]
	v_or_b32_e32 v2, s4, v59
	v_lshlrev_b32_e32 v2, 11, v2
	v_lshl_add_u64 v[84:85], v[34:35], 0, v[2:3]
	v_or_b32_e32 v2, s4, v60
	v_lshlrev_b32_e32 v2, 11, v2
	v_lshl_add_u64 v[86:87], v[34:35], 0, v[2:3]
	v_or_b32_e32 v2, s4, v61
	v_lshlrev_b32_e32 v2, 11, v2
	v_lshl_add_u64 v[88:89], v[34:35], 0, v[2:3]
	v_or_b32_e32 v2, s4, v62
	v_lshlrev_b32_e32 v2, 11, v2
	v_lshl_add_u64 v[90:91], v[34:35], 0, v[2:3]
	v_or_b32_e32 v2, s4, v63
	v_lshlrev_b32_e32 v2, 11, v2
	v_lshl_add_u64 v[92:93], v[34:35], 0, v[2:3]
	v_or_b32_e32 v2, s4, v64
	v_lshlrev_b32_e32 v2, 11, v2
	global_load_dword v110, v[78:79], off nt
	global_load_dword v111, v[80:81], off nt
	global_load_dword v112, v[82:83], off nt
	global_load_dword v113, v[84:85], off nt
	global_load_dword v114, v[86:87], off nt
	global_load_dword v115, v[88:89], off nt
	global_load_dword v116, v[90:91], off nt
	s_nop 0
	global_load_dword v92, v[92:93], off nt
	v_lshl_add_u64 v[78:79], v[34:35], 0, v[2:3]
	v_or_b32_e32 v2, s4, v66
	v_lshlrev_b32_e32 v2, 11, v2
	v_lshl_add_u64 v[80:81], v[34:35], 0, v[2:3]
	v_or_b32_e32 v2, s4, v67
	v_lshlrev_b32_e32 v2, 11, v2
	v_lshl_add_u64 v[82:83], v[34:35], 0, v[2:3]
	v_or_b32_e32 v2, s4, v68
	v_lshlrev_b32_e32 v2, 11, v2
	v_lshl_add_u64 v[84:85], v[34:35], 0, v[2:3]
	v_or_b32_e32 v2, s4, v69
	v_lshlrev_b32_e32 v2, 11, v2
	v_lshl_add_u64 v[86:87], v[34:35], 0, v[2:3]
	v_or_b32_e32 v2, s4, v70
	v_lshlrev_b32_e32 v2, 11, v2
	v_lshl_add_u64 v[88:89], v[34:35], 0, v[2:3]
	v_or_b32_e32 v2, s4, v71
	v_lshlrev_b32_e32 v2, 11, v2
	v_lshl_add_u64 v[90:91], v[34:35], 0, v[2:3]
	v_or_b32_e32 v2, s4, v72
	v_lshlrev_b32_e32 v2, 11, v2
	v_lshl_add_u64 v[34:35], v[34:35], 0, v[2:3]
	global_load_dword v2, v[78:79], off nt
	s_nop 0
	global_load_dword v78, v[80:81], off nt
	global_load_dword v79, v[82:83], off nt
	s_nop 0
	global_load_dword v80, v[84:85], off nt
	global_load_dword v81, v[86:87], off nt
	global_load_dword v82, v[88:89], off nt
	global_load_dword v83, v[90:91], off nt
	s_nop 0
	global_load_dword v34, v[34:35], off nt
	v_add_u32_e32 v35, v36, v37
	s_waitcnt vmcnt(30)
	ds_write2_b32 v35, v94, v95 offset1:66
	s_waitcnt vmcnt(28)
	ds_write2_b32 v35, v96, v97 offset0:132 offset1:198
	v_add_u32_e32 v35, 0x400, v35
	s_waitcnt vmcnt(26)
	ds_write2_b32 v35, v98, v99 offset0:8 offset1:74
	v_add_u32_e32 v35, v36, v44
	s_waitcnt vmcnt(24)
	ds_write2_b32 v35, v100, v101 offset1:66
	s_waitcnt vmcnt(22)
	ds_write2_b32 v35, v102, v103 offset0:132 offset1:198
	v_add_u32_e32 v35, 0x400, v35
	s_waitcnt vmcnt(20)
	ds_write2_b32 v35, v104, v105 offset0:8 offset1:74
	v_add_u32_e32 v35, v36, v51
	s_waitcnt vmcnt(18)
	ds_write2_b32 v35, v106, v107 offset1:66
	s_waitcnt vmcnt(16)
	ds_write2_b32 v35, v108, v109 offset0:132 offset1:198
	v_add_u32_e32 v35, 0x400, v35
	s_lshl_b32 s0, s4, 1
	s_waitcnt vmcnt(14)
	ds_write2_b32 v35, v110, v111 offset0:8 offset1:74
	v_add_u32_e32 v35, v36, v58
	s_waitcnt vmcnt(12)
	ds_write2_b32 v35, v112, v113 offset1:66
	s_waitcnt vmcnt(10)
	ds_write2_b32 v35, v114, v115 offset0:132 offset1:198
	v_add_u32_e32 v35, 0x400, v35
	s_waitcnt vmcnt(8)
	ds_write2_b32 v35, v116, v92 offset0:8 offset1:74
	v_add_u32_e32 v35, v36, v65
	s_waitcnt vmcnt(6)
	ds_write2_b32 v35, v2, v78 offset1:66
	s_waitcnt vmcnt(4)
	ds_write2_b32 v35, v79, v80 offset0:132 offset1:198
	v_add_u32_e32 v2, 0x400, v35
	s_waitcnt vmcnt(2)
	ds_write2_b32 v2, v81, v82 offset0:8 offset1:74
	s_waitcnt vmcnt(0)
	ds_write2_b32 v2, v83, v34 offset0:140 offset1:206
	s_waitcnt lgkmcnt(0)
	ds_read2_b32 v[34:35], v74 offset1:8
	ds_read2_b32 v[84:85], v74 offset0:33 offset1:41
	ds_read2_b32 v[86:87], v74 offset0:66 offset1:74
	ds_read2_b32 v[88:89], v74 offset0:99 offset1:107
	ds_read2_b32 v[90:91], v74 offset0:132 offset1:140
	s_waitcnt lgkmcnt(4)
	v_bfe_u32 v2, v34, 16, 1
	v_add3_u32 v2, v34, v2, s35
	s_waitcnt lgkmcnt(3)
	v_bfe_u32 v34, v84, 16, 1
	v_lshrrev_b32_e32 v2, 16, v2
	v_add3_u32 v34, v84, v34, s35
	ds_read2_b32 v[92:93], v74 offset0:165 offset1:173
	v_and_or_b32 v78, v34, s36, v2
	s_waitcnt lgkmcnt(3)
	v_bfe_u32 v2, v86, 16, 1
	v_add3_u32 v2, v86, v2, s35
	s_waitcnt lgkmcnt(2)
	v_bfe_u32 v34, v88, 16, 1
	ds_read2_b32 v[94:95], v74 offset0:198 offset1:206
	v_lshrrev_b32_e32 v2, 16, v2
	v_add3_u32 v34, v88, v34, s35
	ds_read2_b32 v[96:97], v74 offset0:231 offset1:239
	v_and_or_b32 v79, v34, s36, v2
	s_waitcnt lgkmcnt(3)
	v_bfe_u32 v2, v90, 16, 1
	v_add3_u32 v2, v90, v2, s35
	s_waitcnt lgkmcnt(2)
	v_bfe_u32 v34, v92, 16, 1
	v_lshrrev_b32_e32 v2, 16, v2
	v_add3_u32 v34, v92, v34, s35
	v_and_or_b32 v80, v34, s36, v2
	s_waitcnt lgkmcnt(1)
	v_bfe_u32 v2, v94, 16, 1
	v_add3_u32 v2, v94, v2, s35
	s_waitcnt lgkmcnt(0)
	v_bfe_u32 v34, v96, 16, 1
	v_lshrrev_b32_e32 v2, 16, v2
	v_add3_u32 v34, v96, v34, s35
	v_and_or_b32 v81, v34, s36, v2
	v_or_b32_e32 v2, s6, v73
	v_lshl_add_u64 v[82:83], v[4:5], 0, s[0:1]
	v_lshlrev_b32_e32 v2, 9, v2
	v_lshl_add_u64 v[98:99], v[82:83], 0, v[2:3]
	v_bfe_u32 v2, v35, 16, 1
	v_add3_u32 v2, v35, v2, s35
	v_bfe_u32 v34, v85, 16, 1
	v_lshrrev_b32_e32 v2, 16, v2
	v_add3_u32 v34, v85, v34, s35
	global_store_dwordx4 v[98:99], v[78:81], off
	s_nop 1
	v_and_or_b32 v78, v34, s36, v2
	v_bfe_u32 v2, v87, 16, 1
	v_add3_u32 v2, v87, v2, s35
	v_bfe_u32 v34, v89, 16, 1
	v_lshrrev_b32_e32 v2, 16, v2
	v_add3_u32 v34, v89, v34, s35
	v_and_or_b32 v79, v34, s36, v2
	v_bfe_u32 v2, v91, 16, 1
	v_add3_u32 v2, v91, v2, s35
	v_bfe_u32 v34, v93, 16, 1
	v_lshrrev_b32_e32 v2, 16, v2
	v_add3_u32 v34, v93, v34, s35
	v_and_or_b32 v80, v34, s36, v2
	v_bfe_u32 v2, v95, 16, 1
	v_add3_u32 v2, v95, v2, s35
	v_bfe_u32 v34, v97, 16, 1
	v_lshrrev_b32_e32 v2, 16, v2
	v_add3_u32 v34, v97, v34, s35
	v_and_or_b32 v81, v34, s36, v2
	v_or_b32_e32 v2, s6, v75
	v_lshlrev_b32_e32 v2, 9, v2
	ds_read2_b32 v[34:35], v74 offset0:16 offset1:24
	v_lshl_add_u64 v[84:85], v[82:83], 0, v[2:3]
	global_store_dwordx4 v[84:85], v[78:81], off
	ds_read2_b32 v[84:85], v74 offset0:49 offset1:57
	ds_read2_b32 v[86:87], v74 offset0:82 offset1:90
	ds_read2_b32 v[88:89], v74 offset0:115 offset1:123
	s_waitcnt lgkmcnt(3)
	v_bfe_u32 v2, v34, 16, 1
	v_add3_u32 v2, v34, v2, s35
	s_waitcnt lgkmcnt(2)
	v_bfe_u32 v34, v84, 16, 1
	ds_read2_b32 v[90:91], v74 offset0:148 offset1:156
	v_lshrrev_b32_e32 v2, 16, v2
	v_add3_u32 v34, v84, v34, s35
	ds_read2_b32 v[92:93], v74 offset0:181 offset1:189
	v_and_or_b32 v78, v34, s36, v2
	s_waitcnt lgkmcnt(3)
	v_bfe_u32 v2, v86, 16, 1
	v_add3_u32 v2, v86, v2, s35
	s_waitcnt lgkmcnt(2)
	v_bfe_u32 v34, v88, 16, 1
	ds_read2_b32 v[94:95], v74 offset0:214 offset1:222
	v_lshrrev_b32_e32 v2, 16, v2
	v_add3_u32 v34, v88, v34, s35
	ds_read2_b32 v[96:97], v74 offset0:247 offset1:255
	v_and_or_b32 v79, v34, s36, v2
	s_waitcnt lgkmcnt(3)
	v_bfe_u32 v2, v90, 16, 1
	v_add3_u32 v2, v90, v2, s35
	s_waitcnt lgkmcnt(2)
	v_bfe_u32 v34, v92, 16, 1
	v_lshrrev_b32_e32 v2, 16, v2
	v_add3_u32 v34, v92, v34, s35
	v_and_or_b32 v80, v34, s36, v2
	s_waitcnt lgkmcnt(1)
	v_bfe_u32 v2, v94, 16, 1
	v_add3_u32 v2, v94, v2, s35
	s_waitcnt lgkmcnt(0)
	v_bfe_u32 v34, v96, 16, 1
	v_lshrrev_b32_e32 v2, 16, v2
	v_add3_u32 v34, v96, v34, s35
	v_and_or_b32 v81, v34, s36, v2
	v_or_b32_e32 v2, s6, v76
	v_lshlrev_b32_e32 v2, 9, v2
	v_lshl_add_u64 v[98:99], v[82:83], 0, v[2:3]
	v_bfe_u32 v2, v35, 16, 1
	v_add3_u32 v2, v35, v2, s35
	v_bfe_u32 v34, v85, 16, 1
	v_lshrrev_b32_e32 v2, 16, v2
	v_add3_u32 v34, v85, v34, s35
	global_store_dwordx4 v[98:99], v[78:81], off
	s_nop 1
	v_and_or_b32 v78, v34, s36, v2
	v_bfe_u32 v2, v87, 16, 1
	v_add3_u32 v2, v87, v2, s35
	v_bfe_u32 v34, v89, 16, 1
	v_lshrrev_b32_e32 v2, 16, v2
	v_add3_u32 v34, v89, v34, s35
	v_and_or_b32 v79, v34, s36, v2
	v_bfe_u32 v2, v91, 16, 1
	v_add3_u32 v2, v91, v2, s35
	v_bfe_u32 v34, v93, 16, 1
	v_lshrrev_b32_e32 v2, 16, v2
	v_add3_u32 v34, v93, v34, s35
	v_and_or_b32 v80, v34, s36, v2
	v_bfe_u32 v2, v95, 16, 1
	v_add3_u32 v2, v95, v2, s35
	v_bfe_u32 v34, v97, 16, 1
	v_lshrrev_b32_e32 v2, 16, v2
	v_add3_u32 v34, v97, v34, s35
	v_and_or_b32 v81, v34, s36, v2
	v_or_b32_e32 v2, s6, v77
	v_lshlrev_b32_e32 v2, 9, v2
	v_lshl_add_u64 v[34:35], v[82:83], 0, v[2:3]
	global_store_dwordx4 v[34:35], v[78:81], off
	s_waitcnt lgkmcnt(0)

.LBB0_22:
	s_andn2_b64 vcc, exec, s[4:5]
	s_cbranch_vccnz .LBB0_24
	s_add_i32 s0, s39, 48
	s_and_b32 s4, s0, 0xff
	s_mulk_i32 s4, 0xab
	s_bfe_u32 s4, s4, 0x4000c
	s_mul_i32 s5, s4, 24
	s_sub_i32 s0, s0, s5
	s_lshl_b32 s6, s4, 6
	s_and_b32 s5, s0, 0xff
	v_or_b32_e32 v2, s6, v1
	s_lshl_b32 s0, s5, 7
	v_mul_u32_u24_e32 v2, 0x300, v2
	v_lshl_add_u64 v[34:35], v[22:23], 0, s[0:1]
	v_lshlrev_b32_e32 v2, 2, v2
	v_lshl_add_u64 v[78:79], v[34:35], 0, v[2:3]
	v_or_b32_e32 v2, s6, v38
	v_mul_u32_u24_e32 v2, 0x300, v2
	v_lshlrev_b32_e32 v2, 2, v2
	v_lshl_add_u64 v[80:81], v[34:35], 0, v[2:3]
	v_or_b32_e32 v2, s6, v39
	v_mul_u32_u24_e32 v2, 0x300, v2
	v_lshlrev_b32_e32 v2, 2, v2
	v_lshl_add_u64 v[82:83], v[34:35], 0, v[2:3]
	v_or_b32_e32 v2, s6, v40
	v_mul_u32_u24_e32 v2, 0x300, v2
	v_lshlrev_b32_e32 v2, 2, v2
	v_lshl_add_u64 v[84:85], v[34:35], 0, v[2:3]
	v_or_b32_e32 v2, s6, v41
	v_mul_u32_u24_e32 v2, 0x300, v2
	v_lshlrev_b32_e32 v2, 2, v2
	v_lshl_add_u64 v[86:87], v[34:35], 0, v[2:3]
	v_or_b32_e32 v2, s6, v42
	v_mul_u32_u24_e32 v2, 0x300, v2
	v_lshlrev_b32_e32 v2, 2, v2
	v_lshl_add_u64 v[88:89], v[34:35], 0, v[2:3]
	v_or_b32_e32 v2, s6, v43
	v_mul_u32_u24_e32 v2, 0x300, v2
	v_lshlrev_b32_e32 v2, 2, v2
	v_lshl_add_u64 v[90:91], v[34:35], 0, v[2:3]
	v_or_b32_e32 v2, s6, v45
	v_mul_u32_u24_e32 v2, 0x300, v2
	v_lshlrev_b32_e32 v2, 2, v2
	v_lshl_add_u64 v[92:93], v[34:35], 0, v[2:3]
	v_or_b32_e32 v2, s6, v46
	v_mul_u32_u24_e32 v2, 0x300, v2
	v_lshlrev_b32_e32 v2, 2, v2
	global_load_dword v94, v[78:79], off nt
	global_load_dword v95, v[80:81], off nt
	global_load_dword v96, v[82:83], off nt
	global_load_dword v97, v[84:85], off nt
	global_load_dword v98, v[86:87], off nt
	global_load_dword v99, v[88:89], off nt
	global_load_dword v100, v[90:91], off nt
	global_load_dword v101, v[92:93], off nt
	v_lshl_add_u64 v[78:79], v[34:35], 0, v[2:3]
	v_or_b32_e32 v2, s6, v47
	v_mul_u32_u24_e32 v2, 0x300, v2
	v_lshlrev_b32_e32 v2, 2, v2
	v_lshl_add_u64 v[80:81], v[34:35], 0, v[2:3]
	v_or_b32_e32 v2, s6, v48
	v_mul_u32_u24_e32 v2, 0x300, v2
	v_lshlrev_b32_e32 v2, 2, v2
	v_lshl_add_u64 v[82:83], v[34:35], 0, v[2:3]
	v_or_b32_e32 v2, s6, v49
	v_mul_u32_u24_e32 v2, 0x300, v2
	v_lshlrev_b32_e32 v2, 2, v2
	v_lshl_add_u64 v[84:85], v[34:35], 0, v[2:3]
	v_or_b32_e32 v2, s6, v50
	v_mul_u32_u24_e32 v2, 0x300, v2
	v_lshlrev_b32_e32 v2, 2, v2
	v_lshl_add_u64 v[86:87], v[34:35], 0, v[2:3]
	v_or_b32_e32 v2, s6, v52
	v_mul_u32_u24_e32 v2, 0x300, v2
	v_lshlrev_b32_e32 v2, 2, v2
	v_lshl_add_u64 v[88:89], v[34:35], 0, v[2:3]
	v_or_b32_e32 v2, s6, v53
	v_mul_u32_u24_e32 v2, 0x300, v2
	v_lshlrev_b32_e32 v2, 2, v2
	v_lshl_add_u64 v[90:91], v[34:35], 0, v[2:3]
	v_or_b32_e32 v2, s6, v54
	v_mul_u32_u24_e32 v2, 0x300, v2
	v_lshlrev_b32_e32 v2, 2, v2
	v_lshl_add_u64 v[92:93], v[34:35], 0, v[2:3]
	v_or_b32_e32 v2, s6, v55
	v_mul_u32_u24_e32 v2, 0x300, v2
	v_lshlrev_b32_e32 v2, 2, v2
	global_load_dword v102, v[78:79], off nt
	global_load_dword v103, v[80:81], off nt
	global_load_dword v104, v[82:83], off nt
	global_load_dword v105, v[84:85], off nt
	global_load_dword v106, v[86:87], off nt
	global_load_dword v107, v[88:89], off nt
	global_load_dword v108, v[90:91], off nt
	global_load_dword v109, v[92:93], off nt
	v_lshl_add_u64 v[78:79], v[34:35], 0, v[2:3]
	v_or_b32_e32 v2, s6, v56
	v_mul_u32_u24_e32 v2, 0x300, v2
	v_lshlrev_b32_e32 v2, 2, v2
	v_lshl_add_u64 v[80:81], v[34:35], 0, v[2:3]
	v_or_b32_e32 v2, s6, v57
	v_mul_u32_u24_e32 v2, 0x300, v2
	v_lshlrev_b32_e32 v2, 2, v2
	v_lshl_add_u64 v[82:83], v[34:35], 0, v[2:3]
	v_or_b32_e32 v2, s6, v59
	v_mul_u32_u24_e32 v2, 0x300, v2
	v_lshlrev_b32_e32 v2, 2, v2
	v_lshl_add_u64 v[84:85], v[34:35], 0, v[2:3]
	v_or_b32_e32 v2, s6, v60
	v_mul_u32_u24_e32 v2, 0x300, v2
	v_lshlrev_b32_e32 v2, 2, v2
	v_lshl_add_u64 v[86:87], v[34:35], 0, v[2:3]
	v_or_b32_e32 v2, s6, v61
	v_mul_u32_u24_e32 v2, 0x300, v2
	v_lshlrev_b32_e32 v2, 2, v2
	v_lshl_add_u64 v[88:89], v[34:35], 0, v[2:3]
	v_or_b32_e32 v2, s6, v62
	v_mul_u32_u24_e32 v2, 0x300, v2
	v_lshlrev_b32_e32 v2, 2, v2
	v_lshl_add_u64 v[90:91], v[34:35], 0, v[2:3]
	v_or_b32_e32 v2, s6, v63
	v_mul_u32_u24_e32 v2, 0x300, v2
	v_lshlrev_b32_e32 v2, 2, v2
	v_lshl_add_u64 v[92:93], v[34:35], 0, v[2:3]
	v_or_b32_e32 v2, s6, v64
	v_mul_u32_u24_e32 v2, 0x300, v2
	v_lshlrev_b32_e32 v2, 2, v2
	global_load_dword v110, v[78:79], off nt
	global_load_dword v111, v[80:81], off nt
	global_load_dword v112, v[82:83], off nt
	global_load_dword v113, v[84:85], off nt
	global_load_dword v114, v[86:87], off nt
	global_load_dword v115, v[88:89], off nt
	global_load_dword v116, v[90:91], off nt
	s_nop 0
	global_load_dword v92, v[92:93], off nt
	v_lshl_add_u64 v[78:79], v[34:35], 0, v[2:3]
	v_or_b32_e32 v2, s6, v66
	v_mul_u32_u24_e32 v2, 0x300, v2
	v_lshlrev_b32_e32 v2, 2, v2
	v_lshl_add_u64 v[80:81], v[34:35], 0, v[2:3]
	v_or_b32_e32 v2, s6, v67
	v_mul_u32_u24_e32 v2, 0x300, v2
	v_lshlrev_b32_e32 v2, 2, v2
	v_lshl_add_u64 v[82:83], v[34:35], 0, v[2:3]
	v_or_b32_e32 v2, s6, v68
	v_mul_u32_u24_e32 v2, 0x300, v2
	v_lshlrev_b32_e32 v2, 2, v2
	v_lshl_add_u64 v[84:85], v[34:35], 0, v[2:3]
	v_or_b32_e32 v2, s6, v69
	v_mul_u32_u24_e32 v2, 0x300, v2
	v_lshlrev_b32_e32 v2, 2, v2
	v_lshl_add_u64 v[86:87], v[34:35], 0, v[2:3]
	v_or_b32_e32 v2, s6, v70
	v_mul_u32_u24_e32 v2, 0x300, v2
	v_lshlrev_b32_e32 v2, 2, v2
	v_lshl_add_u64 v[88:89], v[34:35], 0, v[2:3]
	v_or_b32_e32 v2, s6, v71
	v_mul_u32_u24_e32 v2, 0x300, v2
	v_lshlrev_b32_e32 v2, 2, v2
	v_lshl_add_u64 v[90:91], v[34:35], 0, v[2:3]
	v_or_b32_e32 v2, s6, v72
	v_mul_u32_u24_e32 v2, 0x300, v2
	v_lshlrev_b32_e32 v2, 2, v2
	v_lshl_add_u64 v[34:35], v[34:35], 0, v[2:3]
	global_load_dword v2, v[78:79], off nt
	s_nop 0
	global_load_dword v78, v[80:81], off nt
	global_load_dword v79, v[82:83], off nt
	s_nop 0
	global_load_dword v80, v[84:85], off nt
	global_load_dword v81, v[86:87], off nt
	global_load_dword v82, v[88:89], off nt
	global_load_dword v83, v[90:91], off nt
	s_nop 0
	global_load_dword v34, v[34:35], off nt
	v_add_u32_e32 v35, v36, v37
	s_waitcnt vmcnt(30)
	ds_write2_b32 v35, v94, v95 offset1:66
	s_waitcnt vmcnt(28)
	ds_write2_b32 v35, v96, v97 offset0:132 offset1:198
	v_add_u32_e32 v35, 0x400, v35
	s_waitcnt vmcnt(26)
	ds_write2_b32 v35, v98, v99 offset0:8 offset1:74
	v_add_u32_e32 v35, v36, v44
	s_waitcnt vmcnt(24)
	ds_write2_b32 v35, v100, v101 offset1:66
	s_waitcnt vmcnt(22)
	ds_write2_b32 v35, v102, v103 offset0:132 offset1:198
	v_add_u32_e32 v35, 0x400, v35
	s_waitcnt vmcnt(20)
	ds_write2_b32 v35, v104, v105 offset0:8 offset1:74
	v_add_u32_e32 v35, v36, v51
	s_waitcnt vmcnt(18)
	ds_write2_b32 v35, v106, v107 offset1:66
	s_waitcnt vmcnt(16)
	ds_write2_b32 v35, v108, v109 offset0:132 offset1:198
	v_add_u32_e32 v35, 0x400, v35
	s_lshl_b32 s5, s5, 5
	s_lshl_b32 s0, s4, 7
	s_waitcnt vmcnt(14)
	ds_write2_b32 v35, v110, v111 offset0:8 offset1:74
	v_add_u32_e32 v35, v36, v58
	s_waitcnt vmcnt(12)
	ds_write2_b32 v35, v112, v113 offset1:66
	s_waitcnt vmcnt(10)
	ds_write2_b32 v35, v114, v115 offset0:132 offset1:198
	v_add_u32_e32 v35, 0x400, v35
	s_waitcnt vmcnt(8)
	ds_write2_b32 v35, v116, v92 offset0:8 offset1:74
	v_add_u32_e32 v35, v36, v65
	s_waitcnt vmcnt(6)
	ds_write2_b32 v35, v2, v78 offset1:66
	s_waitcnt vmcnt(4)
	ds_write2_b32 v35, v79, v80 offset0:132 offset1:198
	v_add_u32_e32 v2, 0x400, v35
	s_waitcnt vmcnt(2)
	ds_write2_b32 v2, v81, v82 offset0:8 offset1:74
	s_waitcnt vmcnt(0)
	ds_write2_b32 v2, v83, v34 offset0:140 offset1:206
	s_waitcnt lgkmcnt(0)
	ds_read2_b32 v[34:35], v74 offset1:8
	ds_read2_b32 v[84:85], v74 offset0:33 offset1:41
	ds_read2_b32 v[86:87], v74 offset0:66 offset1:74
	ds_read2_b32 v[88:89], v74 offset0:99 offset1:107
	ds_read2_b32 v[90:91], v74 offset0:132 offset1:140
	s_waitcnt lgkmcnt(4)
	v_bfe_u32 v2, v34, 16, 1
	v_add3_u32 v2, v34, v2, s35
	s_waitcnt lgkmcnt(3)
	v_bfe_u32 v34, v84, 16, 1
	v_lshrrev_b32_e32 v2, 16, v2
	v_add3_u32 v34, v84, v34, s35
	ds_read2_b32 v[92:93], v74 offset0:165 offset1:173
	v_and_or_b32 v78, v34, s36, v2
	s_waitcnt lgkmcnt(3)
	v_bfe_u32 v2, v86, 16, 1
	v_add3_u32 v2, v86, v2, s35
	s_waitcnt lgkmcnt(2)
	v_bfe_u32 v34, v88, 16, 1
	ds_read2_b32 v[94:95], v74 offset0:198 offset1:206
	v_lshrrev_b32_e32 v2, 16, v2
	v_add3_u32 v34, v88, v34, s35
	ds_read2_b32 v[96:97], v74 offset0:231 offset1:239
	v_and_or_b32 v79, v34, s36, v2
	s_waitcnt lgkmcnt(3)
	v_bfe_u32 v2, v90, 16, 1
	v_add3_u32 v2, v90, v2, s35
	s_waitcnt lgkmcnt(2)
	v_bfe_u32 v34, v92, 16, 1
	v_lshrrev_b32_e32 v2, 16, v2
	v_add3_u32 v34, v92, v34, s35
	v_and_or_b32 v80, v34, s36, v2
	s_waitcnt lgkmcnt(1)
	v_bfe_u32 v2, v94, 16, 1
	v_add3_u32 v2, v94, v2, s35
	s_waitcnt lgkmcnt(0)
	v_bfe_u32 v34, v96, 16, 1
	v_lshrrev_b32_e32 v2, 16, v2
	v_add3_u32 v34, v96, v34, s35
	v_and_or_b32 v81, v34, s36, v2
	v_or_b32_e32 v2, s5, v73
	v_mul_u32_u24_e32 v2, 0x180, v2
	v_lshl_add_u64 v[82:83], v[6:7], 0, s[0:1]
	v_lshlrev_b32_e32 v2, 1, v2
	v_lshl_add_u64 v[98:99], v[82:83], 0, v[2:3]
	v_bfe_u32 v2, v35, 16, 1
	v_add3_u32 v2, v35, v2, s35
	v_bfe_u32 v34, v85, 16, 1
	v_lshrrev_b32_e32 v2, 16, v2
	v_add3_u32 v34, v85, v34, s35
	global_store_dwordx4 v[98:99], v[78:81], off
	s_nop 1
	v_and_or_b32 v78, v34, s36, v2
	v_bfe_u32 v2, v87, 16, 1
	v_add3_u32 v2, v87, v2, s35
	v_bfe_u32 v34, v89, 16, 1
	v_lshrrev_b32_e32 v2, 16, v2
	v_add3_u32 v34, v89, v34, s35
	v_and_or_b32 v79, v34, s36, v2
	v_bfe_u32 v2, v91, 16, 1
	v_add3_u32 v2, v91, v2, s35
	v_bfe_u32 v34, v93, 16, 1
	v_lshrrev_b32_e32 v2, 16, v2
	v_add3_u32 v34, v93, v34, s35
	v_and_or_b32 v80, v34, s36, v2
	v_bfe_u32 v2, v95, 16, 1
	v_add3_u32 v2, v95, v2, s35
	v_bfe_u32 v34, v97, 16, 1
	v_lshrrev_b32_e32 v2, 16, v2
	v_add3_u32 v34, v97, v34, s35
	v_and_or_b32 v81, v34, s36, v2
	v_or_b32_e32 v2, s5, v75
	v_mul_u32_u24_e32 v2, 0x180, v2
	v_lshlrev_b32_e32 v2, 1, v2
	ds_read2_b32 v[34:35], v74 offset0:16 offset1:24
	v_lshl_add_u64 v[84:85], v[82:83], 0, v[2:3]
	global_store_dwordx4 v[84:85], v[78:81], off
	ds_read2_b32 v[84:85], v74 offset0:49 offset1:57
	ds_read2_b32 v[86:87], v74 offset0:82 offset1:90
	ds_read2_b32 v[88:89], v74 offset0:115 offset1:123
	s_waitcnt lgkmcnt(3)
	v_bfe_u32 v2, v34, 16, 1
	v_add3_u32 v2, v34, v2, s35
	s_waitcnt lgkmcnt(2)
	v_bfe_u32 v34, v84, 16, 1
	ds_read2_b32 v[90:91], v74 offset0:148 offset1:156
	v_lshrrev_b32_e32 v2, 16, v2
	v_add3_u32 v34, v84, v34, s35
	ds_read2_b32 v[92:93], v74 offset0:181 offset1:189
	v_and_or_b32 v78, v34, s36, v2
	s_waitcnt lgkmcnt(3)
	v_bfe_u32 v2, v86, 16, 1
	v_add3_u32 v2, v86, v2, s35
	s_waitcnt lgkmcnt(2)
	v_bfe_u32 v34, v88, 16, 1
	ds_read2_b32 v[94:95], v74 offset0:214 offset1:222
	v_lshrrev_b32_e32 v2, 16, v2
	v_add3_u32 v34, v88, v34, s35
	ds_read2_b32 v[96:97], v74 offset0:247 offset1:255
	v_and_or_b32 v79, v34, s36, v2
	s_waitcnt lgkmcnt(3)
	v_bfe_u32 v2, v90, 16, 1
	v_add3_u32 v2, v90, v2, s35
	s_waitcnt lgkmcnt(2)
	v_bfe_u32 v34, v92, 16, 1
	v_lshrrev_b32_e32 v2, 16, v2
	v_add3_u32 v34, v92, v34, s35
	v_and_or_b32 v80, v34, s36, v2
	s_waitcnt lgkmcnt(1)
	v_bfe_u32 v2, v94, 16, 1
	v_add3_u32 v2, v94, v2, s35
	s_waitcnt lgkmcnt(0)
	v_bfe_u32 v34, v96, 16, 1
	v_lshrrev_b32_e32 v2, 16, v2
	v_add3_u32 v34, v96, v34, s35
	v_and_or_b32 v81, v34, s36, v2
	v_or_b32_e32 v2, s5, v76
	v_mul_u32_u24_e32 v2, 0x180, v2
	v_lshlrev_b32_e32 v2, 1, v2
	v_lshl_add_u64 v[98:99], v[82:83], 0, v[2:3]
	v_bfe_u32 v2, v35, 16, 1
	v_add3_u32 v2, v35, v2, s35
	v_bfe_u32 v34, v85, 16, 1
	v_lshrrev_b32_e32 v2, 16, v2
	v_add3_u32 v34, v85, v34, s35
	global_store_dwordx4 v[98:99], v[78:81], off
	s_nop 1
	v_and_or_b32 v78, v34, s36, v2
	v_bfe_u32 v2, v87, 16, 1
	v_add3_u32 v2, v87, v2, s35
	v_bfe_u32 v34, v89, 16, 1
	v_lshrrev_b32_e32 v2, 16, v2
	v_add3_u32 v34, v89, v34, s35
	v_and_or_b32 v79, v34, s36, v2
	v_bfe_u32 v2, v91, 16, 1
	v_add3_u32 v2, v91, v2, s35
	v_bfe_u32 v34, v93, 16, 1
	v_lshrrev_b32_e32 v2, 16, v2
	v_add3_u32 v34, v93, v34, s35
	v_and_or_b32 v80, v34, s36, v2
	v_bfe_u32 v2, v95, 16, 1
	v_add3_u32 v2, v95, v2, s35
	v_bfe_u32 v34, v97, 16, 1
	v_lshrrev_b32_e32 v2, 16, v2
	v_add3_u32 v34, v97, v34, s35
	v_and_or_b32 v81, v34, s36, v2
	v_or_b32_e32 v2, s5, v77
	v_mul_u32_u24_e32 v2, 0x180, v2
	v_lshlrev_b32_e32 v2, 1, v2
	v_lshl_add_u64 v[34:35], v[82:83], 0, v[2:3]
	global_store_dwordx4 v[34:35], v[78:81], off
	s_waitcnt lgkmcnt(0)

.LBB0_25:
	s_andn2_b64 vcc, exec, s[4:5]
	s_cbranch_vccnz .LBB0_27
	s_add_i32 s0, s28, 0xfffce600
	s_and_b32 s5, s33, 0x1c0
	s_and_b32 s4, s0, 0x3e0
	s_lshl_b32 s0, s4, 2
	v_or_b32_e32 v2, s5, v1
	v_lshl_add_u64 v[34:35], v[24:25], 0, s[0:1]
	v_lshlrev_b32_e32 v2, 12, v2
	v_lshl_add_u64 v[78:79], v[34:35], 0, v[2:3]
	v_or_b32_e32 v2, s5, v38
	v_lshlrev_b32_e32 v2, 12, v2
	v_lshl_add_u64 v[80:81], v[34:35], 0, v[2:3]
	v_or_b32_e32 v2, s5, v39
	v_lshlrev_b32_e32 v2, 12, v2
	v_lshl_add_u64 v[82:83], v[34:35], 0, v[2:3]
	v_or_b32_e32 v2, s5, v40
	v_lshlrev_b32_e32 v2, 12, v2
	v_lshl_add_u64 v[84:85], v[34:35], 0, v[2:3]
	v_or_b32_e32 v2, s5, v41
	v_lshlrev_b32_e32 v2, 12, v2
	v_lshl_add_u64 v[86:87], v[34:35], 0, v[2:3]
	v_or_b32_e32 v2, s5, v42
	v_lshlrev_b32_e32 v2, 12, v2
	v_lshl_add_u64 v[88:89], v[34:35], 0, v[2:3]
	v_or_b32_e32 v2, s5, v43
	v_lshlrev_b32_e32 v2, 12, v2
	v_lshl_add_u64 v[90:91], v[34:35], 0, v[2:3]
	v_or_b32_e32 v2, s5, v45
	v_lshlrev_b32_e32 v2, 12, v2
	v_lshl_add_u64 v[92:93], v[34:35], 0, v[2:3]
	v_or_b32_e32 v2, s5, v46
	v_lshlrev_b32_e32 v2, 12, v2
	global_load_dword v94, v[78:79], off nt
	global_load_dword v95, v[80:81], off nt
	global_load_dword v96, v[82:83], off nt
	global_load_dword v97, v[84:85], off nt
	global_load_dword v98, v[86:87], off nt
	global_load_dword v99, v[88:89], off nt
	global_load_dword v100, v[90:91], off nt
	global_load_dword v101, v[92:93], off nt
	v_lshl_add_u64 v[78:79], v[34:35], 0, v[2:3]
	v_or_b32_e32 v2, s5, v47
	v_lshlrev_b32_e32 v2, 12, v2
	v_lshl_add_u64 v[80:81], v[34:35], 0, v[2:3]
	v_or_b32_e32 v2, s5, v48
	v_lshlrev_b32_e32 v2, 12, v2
	v_lshl_add_u64 v[82:83], v[34:35], 0, v[2:3]
	v_or_b32_e32 v2, s5, v49
	v_lshlrev_b32_e32 v2, 12, v2
	v_lshl_add_u64 v[84:85], v[34:35], 0, v[2:3]
	v_or_b32_e32 v2, s5, v50
	v_lshlrev_b32_e32 v2, 12, v2
	v_lshl_add_u64 v[86:87], v[34:35], 0, v[2:3]
	v_or_b32_e32 v2, s5, v52
	v_lshlrev_b32_e32 v2, 12, v2
	v_lshl_add_u64 v[88:89], v[34:35], 0, v[2:3]
	v_or_b32_e32 v2, s5, v53
	v_lshlrev_b32_e32 v2, 12, v2
	v_lshl_add_u64 v[90:91], v[34:35], 0, v[2:3]
	v_or_b32_e32 v2, s5, v54
	v_lshlrev_b32_e32 v2, 12, v2
	v_lshl_add_u64 v[92:93], v[34:35], 0, v[2:3]
	v_or_b32_e32 v2, s5, v55
	v_lshlrev_b32_e32 v2, 12, v2
	global_load_dword v102, v[78:79], off nt
	global_load_dword v103, v[80:81], off nt
	global_load_dword v104, v[82:83], off nt
	global_load_dword v105, v[84:85], off nt
	global_load_dword v106, v[86:87], off nt
	global_load_dword v107, v[88:89], off nt
	global_load_dword v108, v[90:91], off nt
	global_load_dword v109, v[92:93], off nt
	v_lshl_add_u64 v[78:79], v[34:35], 0, v[2:3]
	v_or_b32_e32 v2, s5, v56
	v_lshlrev_b32_e32 v2, 12, v2
	v_lshl_add_u64 v[80:81], v[34:35], 0, v[2:3]
	v_or_b32_e32 v2, s5, v57
	v_lshlrev_b32_e32 v2, 12, v2
	v_lshl_add_u64 v[82:83], v[34:35], 0, v[2:3]
	v_or_b32_e32 v2, s5, v59
	v_lshlrev_b32_e32 v2, 12, v2
	v_lshl_add_u64 v[84:85], v[34:35], 0, v[2:3]
	v_or_b32_e32 v2, s5, v60
	v_lshlrev_b32_e32 v2, 12, v2
	v_lshl_add_u64 v[86:87], v[34:35], 0, v[2:3]
	v_or_b32_e32 v2, s5, v61
	v_lshlrev_b32_e32 v2, 12, v2
	v_lshl_add_u64 v[88:89], v[34:35], 0, v[2:3]
	v_or_b32_e32 v2, s5, v62
	v_lshlrev_b32_e32 v2, 12, v2
	v_lshl_add_u64 v[90:91], v[34:35], 0, v[2:3]
	v_or_b32_e32 v2, s5, v63
	v_lshlrev_b32_e32 v2, 12, v2
	v_lshl_add_u64 v[92:93], v[34:35], 0, v[2:3]
	v_or_b32_e32 v2, s5, v64
	v_lshlrev_b32_e32 v2, 12, v2
	global_load_dword v110, v[78:79], off nt
	global_load_dword v111, v[80:81], off nt
	global_load_dword v112, v[82:83], off nt
	global_load_dword v113, v[84:85], off nt
	global_load_dword v114, v[86:87], off nt
	global_load_dword v115, v[88:89], off nt
	global_load_dword v116, v[90:91], off nt
	s_nop 0
	global_load_dword v92, v[92:93], off nt
	v_lshl_add_u64 v[78:79], v[34:35], 0, v[2:3]
	v_or_b32_e32 v2, s5, v66
	v_lshlrev_b32_e32 v2, 12, v2
	v_lshl_add_u64 v[80:81], v[34:35], 0, v[2:3]
	v_or_b32_e32 v2, s5, v67
	v_lshlrev_b32_e32 v2, 12, v2
	v_lshl_add_u64 v[82:83], v[34:35], 0, v[2:3]
	v_or_b32_e32 v2, s5, v68
	v_lshlrev_b32_e32 v2, 12, v2
	v_lshl_add_u64 v[84:85], v[34:35], 0, v[2:3]
	v_or_b32_e32 v2, s5, v69
	v_lshlrev_b32_e32 v2, 12, v2
	v_lshl_add_u64 v[86:87], v[34:35], 0, v[2:3]
	v_or_b32_e32 v2, s5, v70
	v_lshlrev_b32_e32 v2, 12, v2
	v_lshl_add_u64 v[88:89], v[34:35], 0, v[2:3]
	v_or_b32_e32 v2, s5, v71
	v_lshlrev_b32_e32 v2, 12, v2
	v_lshl_add_u64 v[90:91], v[34:35], 0, v[2:3]
	v_or_b32_e32 v2, s5, v72
	v_lshlrev_b32_e32 v2, 12, v2
	v_lshl_add_u64 v[34:35], v[34:35], 0, v[2:3]
	global_load_dword v2, v[78:79], off nt
	s_nop 0
	global_load_dword v78, v[80:81], off nt
	global_load_dword v79, v[82:83], off nt
	s_nop 0
	global_load_dword v80, v[84:85], off nt
	global_load_dword v81, v[86:87], off nt
	global_load_dword v82, v[88:89], off nt
	global_load_dword v83, v[90:91], off nt
	s_nop 0
	global_load_dword v34, v[34:35], off nt
	v_add_u32_e32 v35, v36, v37
	s_waitcnt vmcnt(30)
	ds_write2_b32 v35, v94, v95 offset1:66
	s_waitcnt vmcnt(28)
	ds_write2_b32 v35, v96, v97 offset0:132 offset1:198
	v_add_u32_e32 v35, 0x400, v35
	s_waitcnt vmcnt(26)
	ds_write2_b32 v35, v98, v99 offset0:8 offset1:74
	v_add_u32_e32 v35, v36, v44
	s_waitcnt vmcnt(24)
	ds_write2_b32 v35, v100, v101 offset1:66
	s_waitcnt vmcnt(22)
	ds_write2_b32 v35, v102, v103 offset0:132 offset1:198
	v_add_u32_e32 v35, 0x400, v35
	s_waitcnt vmcnt(20)
	ds_write2_b32 v35, v104, v105 offset0:8 offset1:74
	v_add_u32_e32 v35, v36, v51
	s_waitcnt vmcnt(18)
	ds_write2_b32 v35, v106, v107 offset1:66
	s_waitcnt vmcnt(16)
	ds_write2_b32 v35, v108, v109 offset0:132 offset1:198
	v_add_u32_e32 v35, 0x400, v35
	s_lshl_b32 s0, s5, 1
	s_waitcnt vmcnt(14)
	ds_write2_b32 v35, v110, v111 offset0:8 offset1:74
	v_add_u32_e32 v35, v36, v58
	s_waitcnt vmcnt(12)
	ds_write2_b32 v35, v112, v113 offset1:66
	s_waitcnt vmcnt(10)
	ds_write2_b32 v35, v114, v115 offset0:132 offset1:198
	v_add_u32_e32 v35, 0x400, v35
	s_waitcnt vmcnt(8)
	ds_write2_b32 v35, v116, v92 offset0:8 offset1:74
	v_add_u32_e32 v35, v36, v65
	s_waitcnt vmcnt(6)
	ds_write2_b32 v35, v2, v78 offset1:66
	s_waitcnt vmcnt(4)
	ds_write2_b32 v35, v79, v80 offset0:132 offset1:198
	v_add_u32_e32 v2, 0x400, v35
	s_waitcnt vmcnt(2)
	ds_write2_b32 v2, v81, v82 offset0:8 offset1:74
	s_waitcnt vmcnt(0)
	ds_write2_b32 v2, v83, v34 offset0:140 offset1:206
	s_waitcnt lgkmcnt(0)
	ds_read2_b32 v[34:35], v74 offset1:8
	ds_read2_b32 v[84:85], v74 offset0:33 offset1:41
	ds_read2_b32 v[86:87], v74 offset0:66 offset1:74
	ds_read2_b32 v[88:89], v74 offset0:99 offset1:107
	ds_read2_b32 v[90:91], v74 offset0:132 offset1:140
	s_waitcnt lgkmcnt(4)
	v_bfe_u32 v2, v34, 16, 1
	v_add3_u32 v2, v34, v2, s35
	s_waitcnt lgkmcnt(3)
	v_bfe_u32 v34, v84, 16, 1
	v_lshrrev_b32_e32 v2, 16, v2
	v_add3_u32 v34, v84, v34, s35
	ds_read2_b32 v[92:93], v74 offset0:165 offset1:173
	v_and_or_b32 v78, v34, s36, v2
	s_waitcnt lgkmcnt(3)
	v_bfe_u32 v2, v86, 16, 1
	v_add3_u32 v2, v86, v2, s35
	s_waitcnt lgkmcnt(2)
	v_bfe_u32 v34, v88, 16, 1
	ds_read2_b32 v[94:95], v74 offset0:198 offset1:206
	v_lshrrev_b32_e32 v2, 16, v2
	v_add3_u32 v34, v88, v34, s35
	ds_read2_b32 v[96:97], v74 offset0:231 offset1:239
	v_and_or_b32 v79, v34, s36, v2
	s_waitcnt lgkmcnt(3)
	v_bfe_u32 v2, v90, 16, 1
	v_add3_u32 v2, v90, v2, s35
	s_waitcnt lgkmcnt(2)
	v_bfe_u32 v34, v92, 16, 1
	v_lshrrev_b32_e32 v2, 16, v2
	v_add3_u32 v34, v92, v34, s35
	v_and_or_b32 v80, v34, s36, v2
	s_waitcnt lgkmcnt(1)
	v_bfe_u32 v2, v94, 16, 1
	v_add3_u32 v2, v94, v2, s35
	s_waitcnt lgkmcnt(0)
	v_bfe_u32 v34, v96, 16, 1
	v_lshrrev_b32_e32 v2, 16, v2
	v_add3_u32 v34, v96, v34, s35
	v_and_or_b32 v81, v34, s36, v2
	v_or_b32_e32 v2, s4, v73
	v_lshl_add_u64 v[82:83], v[8:9], 0, s[0:1]
	v_lshlrev_b32_e32 v2, 10, v2
	v_lshl_add_u64 v[98:99], v[82:83], 0, v[2:3]
	v_bfe_u32 v2, v35, 16, 1
	v_add3_u32 v2, v35, v2, s35
	v_bfe_u32 v34, v85, 16, 1
	v_lshrrev_b32_e32 v2, 16, v2
	v_add3_u32 v34, v85, v34, s35
	global_store_dwordx4 v[98:99], v[78:81], off
	s_nop 1
	v_and_or_b32 v78, v34, s36, v2
	v_bfe_u32 v2, v87, 16, 1
	v_add3_u32 v2, v87, v2, s35
	v_bfe_u32 v34, v89, 16, 1
	v_lshrrev_b32_e32 v2, 16, v2
	v_add3_u32 v34, v89, v34, s35
	v_and_or_b32 v79, v34, s36, v2
	v_bfe_u32 v2, v91, 16, 1
	v_add3_u32 v2, v91, v2, s35
	v_bfe_u32 v34, v93, 16, 1
	v_lshrrev_b32_e32 v2, 16, v2
	v_add3_u32 v34, v93, v34, s35
	v_and_or_b32 v80, v34, s36, v2
	v_bfe_u32 v2, v95, 16, 1
	v_add3_u32 v2, v95, v2, s35
	v_bfe_u32 v34, v97, 16, 1
	v_lshrrev_b32_e32 v2, 16, v2
	v_add3_u32 v34, v97, v34, s35
	v_and_or_b32 v81, v34, s36, v2
	v_or_b32_e32 v2, s4, v75
	v_lshlrev_b32_e32 v2, 10, v2
	ds_read2_b32 v[34:35], v74 offset0:16 offset1:24
	v_lshl_add_u64 v[84:85], v[82:83], 0, v[2:3]
	global_store_dwordx4 v[84:85], v[78:81], off
	ds_read2_b32 v[84:85], v74 offset0:49 offset1:57
	ds_read2_b32 v[86:87], v74 offset0:82 offset1:90
	ds_read2_b32 v[88:89], v74 offset0:115 offset1:123
	s_waitcnt lgkmcnt(3)
	v_bfe_u32 v2, v34, 16, 1
	v_add3_u32 v2, v34, v2, s35
	s_waitcnt lgkmcnt(2)
	v_bfe_u32 v34, v84, 16, 1
	ds_read2_b32 v[90:91], v74 offset0:148 offset1:156
	v_lshrrev_b32_e32 v2, 16, v2
	v_add3_u32 v34, v84, v34, s35
	ds_read2_b32 v[92:93], v74 offset0:181 offset1:189
	v_and_or_b32 v78, v34, s36, v2
	s_waitcnt lgkmcnt(3)
	v_bfe_u32 v2, v86, 16, 1
	v_add3_u32 v2, v86, v2, s35
	s_waitcnt lgkmcnt(2)
	v_bfe_u32 v34, v88, 16, 1
	ds_read2_b32 v[94:95], v74 offset0:214 offset1:222
	v_lshrrev_b32_e32 v2, 16, v2
	v_add3_u32 v34, v88, v34, s35
	ds_read2_b32 v[96:97], v74 offset0:247 offset1:255
	v_and_or_b32 v79, v34, s36, v2
	s_waitcnt lgkmcnt(3)
	v_bfe_u32 v2, v90, 16, 1
	v_add3_u32 v2, v90, v2, s35
	s_waitcnt lgkmcnt(2)
	v_bfe_u32 v34, v92, 16, 1
	v_lshrrev_b32_e32 v2, 16, v2
	v_add3_u32 v34, v92, v34, s35
	v_and_or_b32 v80, v34, s36, v2
	s_waitcnt lgkmcnt(1)
	v_bfe_u32 v2, v94, 16, 1
	v_add3_u32 v2, v94, v2, s35
	s_waitcnt lgkmcnt(0)
	v_bfe_u32 v34, v96, 16, 1
	v_lshrrev_b32_e32 v2, 16, v2
	v_add3_u32 v34, v96, v34, s35
	v_and_or_b32 v81, v34, s36, v2
	v_or_b32_e32 v2, s4, v76
	v_lshlrev_b32_e32 v2, 10, v2
	v_lshl_add_u64 v[98:99], v[82:83], 0, v[2:3]
	v_bfe_u32 v2, v35, 16, 1
	v_add3_u32 v2, v35, v2, s35
	v_bfe_u32 v34, v85, 16, 1
	v_lshrrev_b32_e32 v2, 16, v2
	v_add3_u32 v34, v85, v34, s35
	global_store_dwordx4 v[98:99], v[78:81], off
	s_nop 1
	v_and_or_b32 v78, v34, s36, v2
	v_bfe_u32 v2, v87, 16, 1
	v_add3_u32 v2, v87, v2, s35
	v_bfe_u32 v34, v89, 16, 1
	v_lshrrev_b32_e32 v2, 16, v2
	v_add3_u32 v34, v89, v34, s35
	v_and_or_b32 v79, v34, s36, v2
	v_bfe_u32 v2, v91, 16, 1
	v_add3_u32 v2, v91, v2, s35
	v_bfe_u32 v34, v93, 16, 1
	v_lshrrev_b32_e32 v2, 16, v2
	v_add3_u32 v34, v93, v34, s35
	v_and_or_b32 v80, v34, s36, v2
	v_bfe_u32 v2, v95, 16, 1
	v_add3_u32 v2, v95, v2, s35
	v_bfe_u32 v34, v97, 16, 1
	v_lshrrev_b32_e32 v2, 16, v2
	v_add3_u32 v34, v97, v34, s35
	v_and_or_b32 v81, v34, s36, v2
	v_or_b32_e32 v2, s4, v77
	v_lshlrev_b32_e32 v2, 10, v2
	v_lshl_add_u64 v[34:35], v[82:83], 0, v[2:3]
	global_store_dwordx4 v[34:35], v[78:81], off
	s_waitcnt lgkmcnt(0)

.LBB0_28:
	s_andn2_b64 vcc, exec, s[4:5]
	s_cbranch_vccnz .LBB0_30
	s_add_i32 s0, s33, 0x400
	s_and_b32 s5, s0, 0x1ffc0
	s_add_i32 s0, s28, 0xfffd2600
	s_and_b32 s4, s0, 0x3e0
	s_lshl_b32 s0, s4, 2
	v_or_b32_e32 v2, s5, v1
	v_lshl_add_u64 v[34:35], v[26:27], 0, s[0:1]
	v_lshlrev_b32_e32 v2, 12, v2
	v_lshl_add_u64 v[78:79], v[34:35], 0, v[2:3]
	v_or_b32_e32 v2, s5, v38
	v_lshlrev_b32_e32 v2, 12, v2
	v_lshl_add_u64 v[80:81], v[34:35], 0, v[2:3]
	v_or_b32_e32 v2, s5, v39
	v_lshlrev_b32_e32 v2, 12, v2
	v_lshl_add_u64 v[82:83], v[34:35], 0, v[2:3]
	v_or_b32_e32 v2, s5, v40
	v_lshlrev_b32_e32 v2, 12, v2
	v_lshl_add_u64 v[84:85], v[34:35], 0, v[2:3]
	v_or_b32_e32 v2, s5, v41
	v_lshlrev_b32_e32 v2, 12, v2
	v_lshl_add_u64 v[86:87], v[34:35], 0, v[2:3]
	v_or_b32_e32 v2, s5, v42
	v_lshlrev_b32_e32 v2, 12, v2
	v_lshl_add_u64 v[88:89], v[34:35], 0, v[2:3]
	v_or_b32_e32 v2, s5, v43
	v_lshlrev_b32_e32 v2, 12, v2
	v_lshl_add_u64 v[90:91], v[34:35], 0, v[2:3]
	v_or_b32_e32 v2, s5, v45
	v_lshlrev_b32_e32 v2, 12, v2
	v_lshl_add_u64 v[92:93], v[34:35], 0, v[2:3]
	v_or_b32_e32 v2, s5, v46
	v_lshlrev_b32_e32 v2, 12, v2
	global_load_dword v94, v[78:79], off nt
	global_load_dword v95, v[80:81], off nt
	global_load_dword v96, v[82:83], off nt
	global_load_dword v97, v[84:85], off nt
	global_load_dword v98, v[86:87], off nt
	global_load_dword v99, v[88:89], off nt
	global_load_dword v100, v[90:91], off nt
	global_load_dword v101, v[92:93], off nt
	v_lshl_add_u64 v[78:79], v[34:35], 0, v[2:3]
	v_or_b32_e32 v2, s5, v47
	v_lshlrev_b32_e32 v2, 12, v2
	v_lshl_add_u64 v[80:81], v[34:35], 0, v[2:3]
	v_or_b32_e32 v2, s5, v48
	v_lshlrev_b32_e32 v2, 12, v2
	v_lshl_add_u64 v[82:83], v[34:35], 0, v[2:3]
	v_or_b32_e32 v2, s5, v49
	v_lshlrev_b32_e32 v2, 12, v2
	v_lshl_add_u64 v[84:85], v[34:35], 0, v[2:3]
	v_or_b32_e32 v2, s5, v50
	v_lshlrev_b32_e32 v2, 12, v2
	v_lshl_add_u64 v[86:87], v[34:35], 0, v[2:3]
	v_or_b32_e32 v2, s5, v52
	v_lshlrev_b32_e32 v2, 12, v2
	v_lshl_add_u64 v[88:89], v[34:35], 0, v[2:3]
	v_or_b32_e32 v2, s5, v53
	v_lshlrev_b32_e32 v2, 12, v2
	v_lshl_add_u64 v[90:91], v[34:35], 0, v[2:3]
	v_or_b32_e32 v2, s5, v54
	v_lshlrev_b32_e32 v2, 12, v2
	v_lshl_add_u64 v[92:93], v[34:35], 0, v[2:3]
	v_or_b32_e32 v2, s5, v55
	v_lshlrev_b32_e32 v2, 12, v2
	global_load_dword v102, v[78:79], off nt
	global_load_dword v103, v[80:81], off nt
	global_load_dword v104, v[82:83], off nt
	global_load_dword v105, v[84:85], off nt
	global_load_dword v106, v[86:87], off nt
	global_load_dword v107, v[88:89], off nt
	global_load_dword v108, v[90:91], off nt
	global_load_dword v109, v[92:93], off nt
	v_lshl_add_u64 v[78:79], v[34:35], 0, v[2:3]
	v_or_b32_e32 v2, s5, v56
	v_lshlrev_b32_e32 v2, 12, v2
	v_lshl_add_u64 v[80:81], v[34:35], 0, v[2:3]
	v_or_b32_e32 v2, s5, v57
	v_lshlrev_b32_e32 v2, 12, v2
	v_lshl_add_u64 v[82:83], v[34:35], 0, v[2:3]
	v_or_b32_e32 v2, s5, v59
	v_lshlrev_b32_e32 v2, 12, v2
	v_lshl_add_u64 v[84:85], v[34:35], 0, v[2:3]
	v_or_b32_e32 v2, s5, v60
	v_lshlrev_b32_e32 v2, 12, v2
	v_lshl_add_u64 v[86:87], v[34:35], 0, v[2:3]
	v_or_b32_e32 v2, s5, v61
	v_lshlrev_b32_e32 v2, 12, v2
	v_lshl_add_u64 v[88:89], v[34:35], 0, v[2:3]
	v_or_b32_e32 v2, s5, v62
	v_lshlrev_b32_e32 v2, 12, v2
	v_lshl_add_u64 v[90:91], v[34:35], 0, v[2:3]
	v_or_b32_e32 v2, s5, v63
	v_lshlrev_b32_e32 v2, 12, v2
	v_lshl_add_u64 v[92:93], v[34:35], 0, v[2:3]
	v_or_b32_e32 v2, s5, v64
	v_lshlrev_b32_e32 v2, 12, v2
	global_load_dword v110, v[78:79], off nt
	global_load_dword v111, v[80:81], off nt
	global_load_dword v112, v[82:83], off nt
	global_load_dword v113, v[84:85], off nt
	global_load_dword v114, v[86:87], off nt
	global_load_dword v115, v[88:89], off nt
	global_load_dword v116, v[90:91], off nt
	s_nop 0
	global_load_dword v92, v[92:93], off nt
	v_lshl_add_u64 v[78:79], v[34:35], 0, v[2:3]
	v_or_b32_e32 v2, s5, v66
	v_lshlrev_b32_e32 v2, 12, v2
	v_lshl_add_u64 v[80:81], v[34:35], 0, v[2:3]
	v_or_b32_e32 v2, s5, v67
	v_lshlrev_b32_e32 v2, 12, v2
	v_lshl_add_u64 v[82:83], v[34:35], 0, v[2:3]
	v_or_b32_e32 v2, s5, v68
	v_lshlrev_b32_e32 v2, 12, v2
	v_lshl_add_u64 v[84:85], v[34:35], 0, v[2:3]
	v_or_b32_e32 v2, s5, v69
	v_lshlrev_b32_e32 v2, 12, v2
	v_lshl_add_u64 v[86:87], v[34:35], 0, v[2:3]
	v_or_b32_e32 v2, s5, v70
	v_lshlrev_b32_e32 v2, 12, v2
	v_lshl_add_u64 v[88:89], v[34:35], 0, v[2:3]
	v_or_b32_e32 v2, s5, v71
	v_lshlrev_b32_e32 v2, 12, v2
	v_lshl_add_u64 v[90:91], v[34:35], 0, v[2:3]
	v_or_b32_e32 v2, s5, v72
	v_lshlrev_b32_e32 v2, 12, v2
	v_lshl_add_u64 v[34:35], v[34:35], 0, v[2:3]
	global_load_dword v2, v[78:79], off nt
	s_nop 0
	global_load_dword v78, v[80:81], off nt
	global_load_dword v79, v[82:83], off nt
	s_nop 0
	global_load_dword v80, v[84:85], off nt
	global_load_dword v81, v[86:87], off nt
	global_load_dword v82, v[88:89], off nt
	global_load_dword v83, v[90:91], off nt
	s_nop 0
	global_load_dword v34, v[34:35], off nt
	v_add_u32_e32 v35, v36, v37
	s_waitcnt vmcnt(30)
	ds_write2_b32 v35, v94, v95 offset1:66
	s_waitcnt vmcnt(28)
	ds_write2_b32 v35, v96, v97 offset0:132 offset1:198
	v_add_u32_e32 v35, 0x400, v35
	s_waitcnt vmcnt(26)
	ds_write2_b32 v35, v98, v99 offset0:8 offset1:74
	v_add_u32_e32 v35, v36, v44
	s_waitcnt vmcnt(24)
	ds_write2_b32 v35, v100, v101 offset1:66
	s_waitcnt vmcnt(22)
	ds_write2_b32 v35, v102, v103 offset0:132 offset1:198
	v_add_u32_e32 v35, 0x400, v35
	s_waitcnt vmcnt(20)
	ds_write2_b32 v35, v104, v105 offset0:8 offset1:74
	v_add_u32_e32 v35, v36, v51
	s_waitcnt vmcnt(18)
	ds_write2_b32 v35, v106, v107 offset1:66
	s_waitcnt vmcnt(16)
	ds_write2_b32 v35, v108, v109 offset0:132 offset1:198
	v_add_u32_e32 v35, 0x400, v35
	s_lshl_b32 s0, s5, 1
	s_waitcnt vmcnt(14)
	ds_write2_b32 v35, v110, v111 offset0:8 offset1:74
	v_add_u32_e32 v35, v36, v58
	s_waitcnt vmcnt(12)
	ds_write2_b32 v35, v112, v113 offset1:66
	s_waitcnt vmcnt(10)
	ds_write2_b32 v35, v114, v115 offset0:132 offset1:198
	v_add_u32_e32 v35, 0x400, v35
	s_waitcnt vmcnt(8)
	ds_write2_b32 v35, v116, v92 offset0:8 offset1:74
	v_add_u32_e32 v35, v36, v65
	s_waitcnt vmcnt(6)
	ds_write2_b32 v35, v2, v78 offset1:66
	s_waitcnt vmcnt(4)
	ds_write2_b32 v35, v79, v80 offset0:132 offset1:198
	v_add_u32_e32 v2, 0x400, v35
	s_waitcnt vmcnt(2)
	ds_write2_b32 v2, v81, v82 offset0:8 offset1:74
	s_waitcnt vmcnt(0)
	ds_write2_b32 v2, v83, v34 offset0:140 offset1:206
	s_waitcnt lgkmcnt(0)
	ds_read2_b32 v[34:35], v74 offset1:8
	ds_read2_b32 v[84:85], v74 offset0:33 offset1:41
	ds_read2_b32 v[86:87], v74 offset0:66 offset1:74
	ds_read2_b32 v[88:89], v74 offset0:99 offset1:107
	ds_read2_b32 v[90:91], v74 offset0:132 offset1:140
	s_waitcnt lgkmcnt(4)
	v_bfe_u32 v2, v34, 16, 1
	v_add3_u32 v2, v34, v2, s35
	s_waitcnt lgkmcnt(3)
	v_bfe_u32 v34, v84, 16, 1
	v_lshrrev_b32_e32 v2, 16, v2
	v_add3_u32 v34, v84, v34, s35
	ds_read2_b32 v[92:93], v74 offset0:165 offset1:173
	v_and_or_b32 v78, v34, s36, v2
	s_waitcnt lgkmcnt(3)
	v_bfe_u32 v2, v86, 16, 1
	v_add3_u32 v2, v86, v2, s35
	s_waitcnt lgkmcnt(2)
	v_bfe_u32 v34, v88, 16, 1
	ds_read2_b32 v[94:95], v74 offset0:198 offset1:206
	v_lshrrev_b32_e32 v2, 16, v2
	v_add3_u32 v34, v88, v34, s35
	ds_read2_b32 v[96:97], v74 offset0:231 offset1:239
	v_and_or_b32 v79, v34, s36, v2
	s_waitcnt lgkmcnt(3)
	v_bfe_u32 v2, v90, 16, 1
	v_add3_u32 v2, v90, v2, s35
	s_waitcnt lgkmcnt(2)
	v_bfe_u32 v34, v92, 16, 1
	v_lshrrev_b32_e32 v2, 16, v2
	v_add3_u32 v34, v92, v34, s35
	v_and_or_b32 v80, v34, s36, v2
	s_waitcnt lgkmcnt(1)
	v_bfe_u32 v2, v94, 16, 1
	v_add3_u32 v2, v94, v2, s35
	s_waitcnt lgkmcnt(0)
	v_bfe_u32 v34, v96, 16, 1
	v_lshrrev_b32_e32 v2, 16, v2
	v_add3_u32 v34, v96, v34, s35
	v_and_or_b32 v81, v34, s36, v2
	v_or_b32_e32 v2, s4, v73
	v_lshl_add_u64 v[82:83], v[10:11], 0, s[0:1]
	v_lshlrev_b32_e32 v2, 11, v2
	v_lshl_add_u64 v[98:99], v[82:83], 0, v[2:3]
	v_bfe_u32 v2, v35, 16, 1
	v_add3_u32 v2, v35, v2, s35
	v_bfe_u32 v34, v85, 16, 1
	v_lshrrev_b32_e32 v2, 16, v2
	v_add3_u32 v34, v85, v34, s35
	global_store_dwordx4 v[98:99], v[78:81], off
	s_nop 1
	v_and_or_b32 v78, v34, s36, v2
	v_bfe_u32 v2, v87, 16, 1
	v_add3_u32 v2, v87, v2, s35
	v_bfe_u32 v34, v89, 16, 1
	v_lshrrev_b32_e32 v2, 16, v2
	v_add3_u32 v34, v89, v34, s35
	v_and_or_b32 v79, v34, s36, v2
	v_bfe_u32 v2, v91, 16, 1
	v_add3_u32 v2, v91, v2, s35
	v_bfe_u32 v34, v93, 16, 1
	v_lshrrev_b32_e32 v2, 16, v2
	v_add3_u32 v34, v93, v34, s35
	v_and_or_b32 v80, v34, s36, v2
	v_bfe_u32 v2, v95, 16, 1
	v_add3_u32 v2, v95, v2, s35
	v_bfe_u32 v34, v97, 16, 1
	v_lshrrev_b32_e32 v2, 16, v2
	v_add3_u32 v34, v97, v34, s35
	v_and_or_b32 v81, v34, s36, v2
	v_or_b32_e32 v2, s4, v75
	v_lshlrev_b32_e32 v2, 11, v2
	ds_read2_b32 v[34:35], v74 offset0:16 offset1:24
	v_lshl_add_u64 v[84:85], v[82:83], 0, v[2:3]
	global_store_dwordx4 v[84:85], v[78:81], off
	ds_read2_b32 v[84:85], v74 offset0:49 offset1:57
	ds_read2_b32 v[86:87], v74 offset0:82 offset1:90
	ds_read2_b32 v[88:89], v74 offset0:115 offset1:123
	s_waitcnt lgkmcnt(3)
	v_bfe_u32 v2, v34, 16, 1
	v_add3_u32 v2, v34, v2, s35
	s_waitcnt lgkmcnt(2)
	v_bfe_u32 v34, v84, 16, 1
	ds_read2_b32 v[90:91], v74 offset0:148 offset1:156
	v_lshrrev_b32_e32 v2, 16, v2
	v_add3_u32 v34, v84, v34, s35
	ds_read2_b32 v[92:93], v74 offset0:181 offset1:189
	v_and_or_b32 v78, v34, s36, v2
	s_waitcnt lgkmcnt(3)
	v_bfe_u32 v2, v86, 16, 1
	v_add3_u32 v2, v86, v2, s35
	s_waitcnt lgkmcnt(2)
	v_bfe_u32 v34, v88, 16, 1
	ds_read2_b32 v[94:95], v74 offset0:214 offset1:222
	v_lshrrev_b32_e32 v2, 16, v2
	v_add3_u32 v34, v88, v34, s35
	ds_read2_b32 v[96:97], v74 offset0:247 offset1:255
	v_and_or_b32 v79, v34, s36, v2
	s_waitcnt lgkmcnt(3)
	v_bfe_u32 v2, v90, 16, 1
	v_add3_u32 v2, v90, v2, s35
	s_waitcnt lgkmcnt(2)
	v_bfe_u32 v34, v92, 16, 1
	v_lshrrev_b32_e32 v2, 16, v2
	v_add3_u32 v34, v92, v34, s35
	v_and_or_b32 v80, v34, s36, v2
	s_waitcnt lgkmcnt(1)
	v_bfe_u32 v2, v94, 16, 1
	v_add3_u32 v2, v94, v2, s35
	s_waitcnt lgkmcnt(0)
	v_bfe_u32 v34, v96, 16, 1
	v_lshrrev_b32_e32 v2, 16, v2
	v_add3_u32 v34, v96, v34, s35
	v_and_or_b32 v81, v34, s36, v2
	v_or_b32_e32 v2, s4, v76
	v_lshlrev_b32_e32 v2, 11, v2
	v_lshl_add_u64 v[98:99], v[82:83], 0, v[2:3]
	v_bfe_u32 v2, v35, 16, 1
	v_add3_u32 v2, v35, v2, s35
	v_bfe_u32 v34, v85, 16, 1
	v_lshrrev_b32_e32 v2, 16, v2
	v_add3_u32 v34, v85, v34, s35
	global_store_dwordx4 v[98:99], v[78:81], off
	s_nop 1
	v_and_or_b32 v78, v34, s36, v2
	v_bfe_u32 v2, v87, 16, 1
	v_add3_u32 v2, v87, v2, s35
	v_bfe_u32 v34, v89, 16, 1
	v_lshrrev_b32_e32 v2, 16, v2
	v_add3_u32 v34, v89, v34, s35
	v_and_or_b32 v79, v34, s36, v2
	v_bfe_u32 v2, v91, 16, 1
	v_add3_u32 v2, v91, v2, s35
	v_bfe_u32 v34, v93, 16, 1
	v_lshrrev_b32_e32 v2, 16, v2
	v_add3_u32 v34, v93, v34, s35
	v_and_or_b32 v80, v34, s36, v2
	v_bfe_u32 v2, v95, 16, 1
	v_add3_u32 v2, v95, v2, s35
	v_bfe_u32 v34, v97, 16, 1
	v_lshrrev_b32_e32 v2, 16, v2
	v_add3_u32 v34, v97, v34, s35
	v_and_or_b32 v81, v34, s36, v2
	v_or_b32_e32 v2, s4, v77
	v_lshlrev_b32_e32 v2, 11, v2
	v_lshl_add_u64 v[34:35], v[82:83], 0, v[2:3]
	global_store_dwordx4 v[34:35], v[78:81], off
	s_waitcnt lgkmcnt(0)

.LBB0_31:
	s_andn2_b64 vcc, exec, s[4:5]
	s_cbranch_vccnz .LBB0_33
	s_add_i32 s0, s33, 0xf00
	s_and_b32 s5, s0, 0x1ffc0
	s_add_i32 s0, s28, 0xfffdd600
	s_and_b32 s4, s0, 0x3e0
	s_lshl_b32 s0, s4, 2
	v_or_b32_e32 v2, s5, v1
	v_lshl_add_u64 v[34:35], v[28:29], 0, s[0:1]
	v_lshlrev_b32_e32 v2, 12, v2
	v_lshl_add_u64 v[78:79], v[34:35], 0, v[2:3]
	v_or_b32_e32 v2, s5, v38
	v_lshlrev_b32_e32 v2, 12, v2
	v_lshl_add_u64 v[80:81], v[34:35], 0, v[2:3]
	v_or_b32_e32 v2, s5, v39
	v_lshlrev_b32_e32 v2, 12, v2
	v_lshl_add_u64 v[82:83], v[34:35], 0, v[2:3]
	v_or_b32_e32 v2, s5, v40
	v_lshlrev_b32_e32 v2, 12, v2
	v_lshl_add_u64 v[84:85], v[34:35], 0, v[2:3]
	v_or_b32_e32 v2, s5, v41
	v_lshlrev_b32_e32 v2, 12, v2
	v_lshl_add_u64 v[86:87], v[34:35], 0, v[2:3]
	v_or_b32_e32 v2, s5, v42
	v_lshlrev_b32_e32 v2, 12, v2
	v_lshl_add_u64 v[88:89], v[34:35], 0, v[2:3]
	v_or_b32_e32 v2, s5, v43
	v_lshlrev_b32_e32 v2, 12, v2
	v_lshl_add_u64 v[90:91], v[34:35], 0, v[2:3]
	v_or_b32_e32 v2, s5, v45
	v_lshlrev_b32_e32 v2, 12, v2
	v_lshl_add_u64 v[92:93], v[34:35], 0, v[2:3]
	v_or_b32_e32 v2, s5, v46
	v_lshlrev_b32_e32 v2, 12, v2
	global_load_dword v94, v[78:79], off nt
	global_load_dword v95, v[80:81], off nt
	global_load_dword v96, v[82:83], off nt
	global_load_dword v97, v[84:85], off nt
	global_load_dword v98, v[86:87], off nt
	global_load_dword v99, v[88:89], off nt
	global_load_dword v100, v[90:91], off nt
	global_load_dword v101, v[92:93], off nt
	v_lshl_add_u64 v[78:79], v[34:35], 0, v[2:3]
	v_or_b32_e32 v2, s5, v47
	v_lshlrev_b32_e32 v2, 12, v2
	v_lshl_add_u64 v[80:81], v[34:35], 0, v[2:3]
	v_or_b32_e32 v2, s5, v48
	v_lshlrev_b32_e32 v2, 12, v2
	v_lshl_add_u64 v[82:83], v[34:35], 0, v[2:3]
	v_or_b32_e32 v2, s5, v49
	v_lshlrev_b32_e32 v2, 12, v2
	v_lshl_add_u64 v[84:85], v[34:35], 0, v[2:3]
	v_or_b32_e32 v2, s5, v50
	v_lshlrev_b32_e32 v2, 12, v2
	v_lshl_add_u64 v[86:87], v[34:35], 0, v[2:3]
	v_or_b32_e32 v2, s5, v52
	v_lshlrev_b32_e32 v2, 12, v2
	v_lshl_add_u64 v[88:89], v[34:35], 0, v[2:3]
	v_or_b32_e32 v2, s5, v53
	v_lshlrev_b32_e32 v2, 12, v2
	v_lshl_add_u64 v[90:91], v[34:35], 0, v[2:3]
	v_or_b32_e32 v2, s5, v54
	v_lshlrev_b32_e32 v2, 12, v2
	v_lshl_add_u64 v[92:93], v[34:35], 0, v[2:3]
	v_or_b32_e32 v2, s5, v55
	v_lshlrev_b32_e32 v2, 12, v2
	global_load_dword v102, v[78:79], off nt
	global_load_dword v103, v[80:81], off nt
	global_load_dword v104, v[82:83], off nt
	global_load_dword v105, v[84:85], off nt
	global_load_dword v106, v[86:87], off nt
	global_load_dword v107, v[88:89], off nt
	global_load_dword v108, v[90:91], off nt
	global_load_dword v109, v[92:93], off nt
	v_lshl_add_u64 v[78:79], v[34:35], 0, v[2:3]
	v_or_b32_e32 v2, s5, v56
	v_lshlrev_b32_e32 v2, 12, v2
	v_lshl_add_u64 v[80:81], v[34:35], 0, v[2:3]
	v_or_b32_e32 v2, s5, v57
	v_lshlrev_b32_e32 v2, 12, v2
	v_lshl_add_u64 v[82:83], v[34:35], 0, v[2:3]
	v_or_b32_e32 v2, s5, v59
	v_lshlrev_b32_e32 v2, 12, v2
	v_lshl_add_u64 v[84:85], v[34:35], 0, v[2:3]
	v_or_b32_e32 v2, s5, v60
	v_lshlrev_b32_e32 v2, 12, v2
	v_lshl_add_u64 v[86:87], v[34:35], 0, v[2:3]
	v_or_b32_e32 v2, s5, v61
	v_lshlrev_b32_e32 v2, 12, v2
	v_lshl_add_u64 v[88:89], v[34:35], 0, v[2:3]
	v_or_b32_e32 v2, s5, v62
	v_lshlrev_b32_e32 v2, 12, v2
	v_lshl_add_u64 v[90:91], v[34:35], 0, v[2:3]
	v_or_b32_e32 v2, s5, v63
	v_lshlrev_b32_e32 v2, 12, v2
	v_lshl_add_u64 v[92:93], v[34:35], 0, v[2:3]
	v_or_b32_e32 v2, s5, v64
	v_lshlrev_b32_e32 v2, 12, v2
	global_load_dword v110, v[78:79], off nt
	global_load_dword v111, v[80:81], off nt
	global_load_dword v112, v[82:83], off nt
	global_load_dword v113, v[84:85], off nt
	global_load_dword v114, v[86:87], off nt
	global_load_dword v115, v[88:89], off nt
	global_load_dword v116, v[90:91], off nt
	s_nop 0
	global_load_dword v92, v[92:93], off nt
	v_lshl_add_u64 v[78:79], v[34:35], 0, v[2:3]
	v_or_b32_e32 v2, s5, v66
	v_lshlrev_b32_e32 v2, 12, v2
	v_lshl_add_u64 v[80:81], v[34:35], 0, v[2:3]
	v_or_b32_e32 v2, s5, v67
	v_lshlrev_b32_e32 v2, 12, v2
	v_lshl_add_u64 v[82:83], v[34:35], 0, v[2:3]
	v_or_b32_e32 v2, s5, v68
	v_lshlrev_b32_e32 v2, 12, v2
	v_lshl_add_u64 v[84:85], v[34:35], 0, v[2:3]
	v_or_b32_e32 v2, s5, v69
	v_lshlrev_b32_e32 v2, 12, v2
	v_lshl_add_u64 v[86:87], v[34:35], 0, v[2:3]
	v_or_b32_e32 v2, s5, v70
	v_lshlrev_b32_e32 v2, 12, v2
	v_lshl_add_u64 v[88:89], v[34:35], 0, v[2:3]
	v_or_b32_e32 v2, s5, v71
	v_lshlrev_b32_e32 v2, 12, v2
	v_lshl_add_u64 v[90:91], v[34:35], 0, v[2:3]
	v_or_b32_e32 v2, s5, v72
	v_lshlrev_b32_e32 v2, 12, v2
	v_lshl_add_u64 v[34:35], v[34:35], 0, v[2:3]
	global_load_dword v2, v[78:79], off nt
	s_nop 0
	global_load_dword v78, v[80:81], off nt
	global_load_dword v79, v[82:83], off nt
	s_nop 0
	global_load_dword v80, v[84:85], off nt
	global_load_dword v81, v[86:87], off nt
	global_load_dword v82, v[88:89], off nt
	global_load_dword v83, v[90:91], off nt
	s_nop 0
	global_load_dword v34, v[34:35], off nt
	v_add_u32_e32 v35, v36, v37
	s_waitcnt vmcnt(30)
	ds_write2_b32 v35, v94, v95 offset1:66
	s_waitcnt vmcnt(28)
	ds_write2_b32 v35, v96, v97 offset0:132 offset1:198
	v_add_u32_e32 v35, 0x400, v35
	s_waitcnt vmcnt(26)
	ds_write2_b32 v35, v98, v99 offset0:8 offset1:74
	v_add_u32_e32 v35, v36, v44
	s_waitcnt vmcnt(24)
	ds_write2_b32 v35, v100, v101 offset1:66
	s_waitcnt vmcnt(22)
	ds_write2_b32 v35, v102, v103 offset0:132 offset1:198
	v_add_u32_e32 v35, 0x400, v35
	s_waitcnt vmcnt(20)
	ds_write2_b32 v35, v104, v105 offset0:8 offset1:74
	v_add_u32_e32 v35, v36, v51
	s_waitcnt vmcnt(18)
	ds_write2_b32 v35, v106, v107 offset1:66
	s_waitcnt vmcnt(16)
	ds_write2_b32 v35, v108, v109 offset0:132 offset1:198
	v_add_u32_e32 v35, 0x400, v35
	s_lshl_b32 s0, s5, 1
	s_waitcnt vmcnt(14)
	ds_write2_b32 v35, v110, v111 offset0:8 offset1:74
	v_add_u32_e32 v35, v36, v58
	s_waitcnt vmcnt(12)
	ds_write2_b32 v35, v112, v113 offset1:66
	s_waitcnt vmcnt(10)
	ds_write2_b32 v35, v114, v115 offset0:132 offset1:198
	v_add_u32_e32 v35, 0x400, v35
	s_waitcnt vmcnt(8)
	ds_write2_b32 v35, v116, v92 offset0:8 offset1:74
	v_add_u32_e32 v35, v36, v65
	s_waitcnt vmcnt(6)
	ds_write2_b32 v35, v2, v78 offset1:66
	s_waitcnt vmcnt(4)
	ds_write2_b32 v35, v79, v80 offset0:132 offset1:198
	v_add_u32_e32 v2, 0x400, v35
	s_waitcnt vmcnt(2)
	ds_write2_b32 v2, v81, v82 offset0:8 offset1:74
	s_waitcnt vmcnt(0)
	ds_write2_b32 v2, v83, v34 offset0:140 offset1:206
	s_waitcnt lgkmcnt(0)
	ds_read2_b32 v[34:35], v74 offset1:8
	ds_read2_b32 v[84:85], v74 offset0:33 offset1:41
	ds_read2_b32 v[86:87], v74 offset0:66 offset1:74
	ds_read2_b32 v[88:89], v74 offset0:99 offset1:107
	ds_read2_b32 v[90:91], v74 offset0:132 offset1:140
	s_waitcnt lgkmcnt(4)
	v_bfe_u32 v2, v34, 16, 1
	v_add3_u32 v2, v34, v2, s35
	s_waitcnt lgkmcnt(3)
	v_bfe_u32 v34, v84, 16, 1
	v_lshrrev_b32_e32 v2, 16, v2
	v_add3_u32 v34, v84, v34, s35
	ds_read2_b32 v[92:93], v74 offset0:165 offset1:173
	v_and_or_b32 v78, v34, s36, v2
	s_waitcnt lgkmcnt(3)
	v_bfe_u32 v2, v86, 16, 1
	v_add3_u32 v2, v86, v2, s35
	s_waitcnt lgkmcnt(2)
	v_bfe_u32 v34, v88, 16, 1
	ds_read2_b32 v[94:95], v74 offset0:198 offset1:206
	v_lshrrev_b32_e32 v2, 16, v2
	v_add3_u32 v34, v88, v34, s35
	ds_read2_b32 v[96:97], v74 offset0:231 offset1:239
	v_and_or_b32 v79, v34, s36, v2
	s_waitcnt lgkmcnt(3)
	v_bfe_u32 v2, v90, 16, 1
	v_add3_u32 v2, v90, v2, s35
	s_waitcnt lgkmcnt(2)
	v_bfe_u32 v34, v92, 16, 1
	v_lshrrev_b32_e32 v2, 16, v2
	v_add3_u32 v34, v92, v34, s35
	v_and_or_b32 v80, v34, s36, v2
	s_waitcnt lgkmcnt(1)
	v_bfe_u32 v2, v94, 16, 1
	v_add3_u32 v2, v94, v2, s35
	s_waitcnt lgkmcnt(0)
	v_bfe_u32 v34, v96, 16, 1
	v_lshrrev_b32_e32 v2, 16, v2
	v_add3_u32 v34, v96, v34, s35
	v_and_or_b32 v81, v34, s36, v2
	v_or_b32_e32 v2, s4, v73
	v_mul_u32_u24_e32 v2, 0xb00, v2
	v_lshl_add_u64 v[82:83], v[12:13], 0, s[0:1]
	v_lshlrev_b32_e32 v2, 1, v2
	v_lshl_add_u64 v[98:99], v[82:83], 0, v[2:3]
	v_bfe_u32 v2, v35, 16, 1
	v_add3_u32 v2, v35, v2, s35
	v_bfe_u32 v34, v85, 16, 1
	v_lshrrev_b32_e32 v2, 16, v2
	v_add3_u32 v34, v85, v34, s35
	global_store_dwordx4 v[98:99], v[78:81], off
	s_nop 1
	v_and_or_b32 v78, v34, s36, v2
	v_bfe_u32 v2, v87, 16, 1
	v_add3_u32 v2, v87, v2, s35
	v_bfe_u32 v34, v89, 16, 1
	v_lshrrev_b32_e32 v2, 16, v2
	v_add3_u32 v34, v89, v34, s35
	v_and_or_b32 v79, v34, s36, v2
	v_bfe_u32 v2, v91, 16, 1
	v_add3_u32 v2, v91, v2, s35
	v_bfe_u32 v34, v93, 16, 1
	v_lshrrev_b32_e32 v2, 16, v2
	v_add3_u32 v34, v93, v34, s35
	v_and_or_b32 v80, v34, s36, v2
	v_bfe_u32 v2, v95, 16, 1
	v_add3_u32 v2, v95, v2, s35
	v_bfe_u32 v34, v97, 16, 1
	v_lshrrev_b32_e32 v2, 16, v2
	v_add3_u32 v34, v97, v34, s35
	v_and_or_b32 v81, v34, s36, v2
	v_or_b32_e32 v2, s4, v75
	v_mul_u32_u24_e32 v2, 0xb00, v2
	v_lshlrev_b32_e32 v2, 1, v2
	ds_read2_b32 v[34:35], v74 offset0:16 offset1:24
	v_lshl_add_u64 v[84:85], v[82:83], 0, v[2:3]
	global_store_dwordx4 v[84:85], v[78:81], off
	ds_read2_b32 v[84:85], v74 offset0:49 offset1:57
	ds_read2_b32 v[86:87], v74 offset0:82 offset1:90
	ds_read2_b32 v[88:89], v74 offset0:115 offset1:123
	s_waitcnt lgkmcnt(3)
	v_bfe_u32 v2, v34, 16, 1
	v_add3_u32 v2, v34, v2, s35
	s_waitcnt lgkmcnt(2)
	v_bfe_u32 v34, v84, 16, 1
	ds_read2_b32 v[90:91], v74 offset0:148 offset1:156
	v_lshrrev_b32_e32 v2, 16, v2
	v_add3_u32 v34, v84, v34, s35
	ds_read2_b32 v[92:93], v74 offset0:181 offset1:189
	v_and_or_b32 v78, v34, s36, v2
	s_waitcnt lgkmcnt(3)
	v_bfe_u32 v2, v86, 16, 1
	v_add3_u32 v2, v86, v2, s35
	s_waitcnt lgkmcnt(2)
	v_bfe_u32 v34, v88, 16, 1
	ds_read2_b32 v[94:95], v74 offset0:214 offset1:222
	v_lshrrev_b32_e32 v2, 16, v2
	v_add3_u32 v34, v88, v34, s35
	ds_read2_b32 v[96:97], v74 offset0:247 offset1:255
	v_and_or_b32 v79, v34, s36, v2
	s_waitcnt lgkmcnt(3)
	v_bfe_u32 v2, v90, 16, 1
	v_add3_u32 v2, v90, v2, s35
	s_waitcnt lgkmcnt(2)
	v_bfe_u32 v34, v92, 16, 1
	v_lshrrev_b32_e32 v2, 16, v2
	v_add3_u32 v34, v92, v34, s35
	v_and_or_b32 v80, v34, s36, v2
	s_waitcnt lgkmcnt(1)
	v_bfe_u32 v2, v94, 16, 1
	v_add3_u32 v2, v94, v2, s35
	s_waitcnt lgkmcnt(0)
	v_bfe_u32 v34, v96, 16, 1
	v_lshrrev_b32_e32 v2, 16, v2
	v_add3_u32 v34, v96, v34, s35
	v_and_or_b32 v81, v34, s36, v2
	v_or_b32_e32 v2, s4, v76
	v_mul_u32_u24_e32 v2, 0xb00, v2
	v_lshlrev_b32_e32 v2, 1, v2
	v_lshl_add_u64 v[98:99], v[82:83], 0, v[2:3]
	v_bfe_u32 v2, v35, 16, 1
	v_add3_u32 v2, v35, v2, s35
	v_bfe_u32 v34, v85, 16, 1
	v_lshrrev_b32_e32 v2, 16, v2
	v_add3_u32 v34, v85, v34, s35
	global_store_dwordx4 v[98:99], v[78:81], off
	s_nop 1
	v_and_or_b32 v78, v34, s36, v2
	v_bfe_u32 v2, v87, 16, 1
	v_add3_u32 v2, v87, v2, s35
	v_bfe_u32 v34, v89, 16, 1
	v_lshrrev_b32_e32 v2, 16, v2
	v_add3_u32 v34, v89, v34, s35
	v_and_or_b32 v79, v34, s36, v2
	v_bfe_u32 v2, v91, 16, 1
	v_add3_u32 v2, v91, v2, s35
	v_bfe_u32 v34, v93, 16, 1
	v_lshrrev_b32_e32 v2, 16, v2
	v_add3_u32 v34, v93, v34, s35
	v_and_or_b32 v80, v34, s36, v2
	v_bfe_u32 v2, v95, 16, 1
	v_add3_u32 v2, v95, v2, s35
	v_bfe_u32 v34, v97, 16, 1
	v_lshrrev_b32_e32 v2, 16, v2
	v_add3_u32 v34, v97, v34, s35
	v_and_or_b32 v81, v34, s36, v2
	v_or_b32_e32 v2, s4, v77
	v_mul_u32_u24_e32 v2, 0xb00, v2
	v_lshlrev_b32_e32 v2, 1, v2
	v_lshl_add_u64 v[34:35], v[82:83], 0, v[2:3]
	global_store_dwordx4 v[34:35], v[78:81], off
	s_waitcnt lgkmcnt(0)

.LBB0_34:
	s_andn2_b64 vcc, exec, s[4:5]
	s_cbranch_vccnz .LBB0_36
	s_add_i32 s0, s39, 0xf500
	s_and_b32 s4, s0, 0xffff
	s_mulk_i32 s4, 0x1447
	s_lshr_b32 s4, s4, 19
	s_mul_i32 s5, s4, 0x65
	s_sub_i32 s6, s0, s5
	s_lshl_b32 s7, s4, 6
	s_lshl_b32 s0, s6, 5
	s_and_b32 s5, s0, 0xffe0
	v_or_b32_e32 v2, s7, v1
	s_lshl_b32 s0, s5, 2
	v_mul_u32_u24_e32 v2, 0xca0, v2
	v_lshl_add_u64 v[34:35], v[30:31], 0, s[0:1]
	v_lshlrev_b32_e32 v2, 2, v2
	v_lshl_add_u64 v[78:79], v[34:35], 0, v[2:3]
	v_or_b32_e32 v2, s7, v38
	v_mul_u32_u24_e32 v2, 0xca0, v2
	v_lshlrev_b32_e32 v2, 2, v2
	v_lshl_add_u64 v[80:81], v[34:35], 0, v[2:3]
	v_or_b32_e32 v2, s7, v39
	v_mul_u32_u24_e32 v2, 0xca0, v2
	v_lshlrev_b32_e32 v2, 2, v2
	v_lshl_add_u64 v[82:83], v[34:35], 0, v[2:3]
	v_or_b32_e32 v2, s7, v40
	v_mul_u32_u24_e32 v2, 0xca0, v2
	v_lshlrev_b32_e32 v2, 2, v2
	v_lshl_add_u64 v[84:85], v[34:35], 0, v[2:3]
	v_or_b32_e32 v2, s7, v41
	v_mul_u32_u24_e32 v2, 0xca0, v2
	v_lshlrev_b32_e32 v2, 2, v2
	v_lshl_add_u64 v[86:87], v[34:35], 0, v[2:3]
	v_or_b32_e32 v2, s7, v42
	v_mul_u32_u24_e32 v2, 0xca0, v2
	v_lshlrev_b32_e32 v2, 2, v2
	v_lshl_add_u64 v[88:89], v[34:35], 0, v[2:3]
	v_or_b32_e32 v2, s7, v43
	v_mul_u32_u24_e32 v2, 0xca0, v2
	v_lshlrev_b32_e32 v2, 2, v2
	v_lshl_add_u64 v[90:91], v[34:35], 0, v[2:3]
	v_or_b32_e32 v2, s7, v45
	v_mul_u32_u24_e32 v2, 0xca0, v2
	v_lshlrev_b32_e32 v2, 2, v2
	v_lshl_add_u64 v[92:93], v[34:35], 0, v[2:3]
	v_or_b32_e32 v2, s7, v46
	v_mul_u32_u24_e32 v2, 0xca0, v2
	v_lshlrev_b32_e32 v2, 2, v2
	global_load_dword v94, v[78:79], off nt
	global_load_dword v95, v[80:81], off nt
	global_load_dword v96, v[82:83], off nt
	global_load_dword v97, v[84:85], off nt
	global_load_dword v98, v[86:87], off nt
	global_load_dword v99, v[88:89], off nt
	global_load_dword v100, v[90:91], off nt
	global_load_dword v101, v[92:93], off nt
	v_lshl_add_u64 v[78:79], v[34:35], 0, v[2:3]
	v_or_b32_e32 v2, s7, v47
	v_mul_u32_u24_e32 v2, 0xca0, v2
	v_lshlrev_b32_e32 v2, 2, v2
	v_lshl_add_u64 v[80:81], v[34:35], 0, v[2:3]
	v_or_b32_e32 v2, s7, v48
	v_mul_u32_u24_e32 v2, 0xca0, v2
	v_lshlrev_b32_e32 v2, 2, v2
	v_lshl_add_u64 v[82:83], v[34:35], 0, v[2:3]
	v_or_b32_e32 v2, s7, v49
	v_mul_u32_u24_e32 v2, 0xca0, v2
	v_lshlrev_b32_e32 v2, 2, v2
	v_lshl_add_u64 v[84:85], v[34:35], 0, v[2:3]
	v_or_b32_e32 v2, s7, v50
	v_mul_u32_u24_e32 v2, 0xca0, v2
	v_lshlrev_b32_e32 v2, 2, v2
	v_lshl_add_u64 v[86:87], v[34:35], 0, v[2:3]
	v_or_b32_e32 v2, s7, v52
	v_mul_u32_u24_e32 v2, 0xca0, v2
	v_lshlrev_b32_e32 v2, 2, v2
	v_lshl_add_u64 v[88:89], v[34:35], 0, v[2:3]
	v_or_b32_e32 v2, s7, v53
	v_mul_u32_u24_e32 v2, 0xca0, v2
	v_lshlrev_b32_e32 v2, 2, v2
	v_lshl_add_u64 v[90:91], v[34:35], 0, v[2:3]
	v_or_b32_e32 v2, s7, v54
	v_mul_u32_u24_e32 v2, 0xca0, v2
	v_lshlrev_b32_e32 v2, 2, v2
	v_lshl_add_u64 v[92:93], v[34:35], 0, v[2:3]
	v_or_b32_e32 v2, s7, v55
	v_mul_u32_u24_e32 v2, 0xca0, v2
	v_lshlrev_b32_e32 v2, 2, v2
	global_load_dword v102, v[78:79], off nt
	global_load_dword v103, v[80:81], off nt
	global_load_dword v104, v[82:83], off nt
	global_load_dword v105, v[84:85], off nt
	global_load_dword v106, v[86:87], off nt
	global_load_dword v107, v[88:89], off nt
	global_load_dword v108, v[90:91], off nt
	global_load_dword v109, v[92:93], off nt
	v_lshl_add_u64 v[78:79], v[34:35], 0, v[2:3]
	v_or_b32_e32 v2, s7, v56
	v_mul_u32_u24_e32 v2, 0xca0, v2
	v_lshlrev_b32_e32 v2, 2, v2
	v_lshl_add_u64 v[80:81], v[34:35], 0, v[2:3]
	v_or_b32_e32 v2, s7, v57
	v_mul_u32_u24_e32 v2, 0xca0, v2
	v_lshlrev_b32_e32 v2, 2, v2
	v_lshl_add_u64 v[82:83], v[34:35], 0, v[2:3]
	v_or_b32_e32 v2, s7, v59
	v_mul_u32_u24_e32 v2, 0xca0, v2
	v_lshlrev_b32_e32 v2, 2, v2
	v_lshl_add_u64 v[84:85], v[34:35], 0, v[2:3]
	v_or_b32_e32 v2, s7, v60
	v_mul_u32_u24_e32 v2, 0xca0, v2
	v_lshlrev_b32_e32 v2, 2, v2
	v_lshl_add_u64 v[86:87], v[34:35], 0, v[2:3]
	v_or_b32_e32 v2, s7, v61
	v_mul_u32_u24_e32 v2, 0xca0, v2
	v_lshlrev_b32_e32 v2, 2, v2
	v_lshl_add_u64 v[88:89], v[34:35], 0, v[2:3]
	v_or_b32_e32 v2, s7, v62
	v_mul_u32_u24_e32 v2, 0xca0, v2
	v_lshlrev_b32_e32 v2, 2, v2
	v_lshl_add_u64 v[90:91], v[34:35], 0, v[2:3]
	v_or_b32_e32 v2, s7, v63
	v_mul_u32_u24_e32 v2, 0xca0, v2
	v_lshlrev_b32_e32 v2, 2, v2
	v_lshl_add_u64 v[92:93], v[34:35], 0, v[2:3]
	v_or_b32_e32 v2, s7, v64
	v_mul_u32_u24_e32 v2, 0xca0, v2
	v_lshlrev_b32_e32 v2, 2, v2
	global_load_dword v110, v[78:79], off nt
	global_load_dword v111, v[80:81], off nt
	global_load_dword v112, v[82:83], off nt
	global_load_dword v113, v[84:85], off nt
	global_load_dword v114, v[86:87], off nt
	global_load_dword v115, v[88:89], off nt
	global_load_dword v116, v[90:91], off nt
	s_nop 0
	global_load_dword v92, v[92:93], off nt
	v_lshl_add_u64 v[78:79], v[34:35], 0, v[2:3]
	v_or_b32_e32 v2, s7, v66
	v_mul_u32_u24_e32 v2, 0xca0, v2
	v_lshlrev_b32_e32 v2, 2, v2
	v_lshl_add_u64 v[80:81], v[34:35], 0, v[2:3]
	v_or_b32_e32 v2, s7, v67
	v_mul_u32_u24_e32 v2, 0xca0, v2
	v_lshlrev_b32_e32 v2, 2, v2
	v_lshl_add_u64 v[82:83], v[34:35], 0, v[2:3]
	v_or_b32_e32 v2, s7, v68
	v_mul_u32_u24_e32 v2, 0xca0, v2
	v_lshlrev_b32_e32 v2, 2, v2
	v_lshl_add_u64 v[84:85], v[34:35], 0, v[2:3]
	v_or_b32_e32 v2, s7, v69
	v_mul_u32_u24_e32 v2, 0xca0, v2
	v_lshlrev_b32_e32 v2, 2, v2
	v_lshl_add_u64 v[86:87], v[34:35], 0, v[2:3]
	v_or_b32_e32 v2, s7, v70
	v_mul_u32_u24_e32 v2, 0xca0, v2
	v_lshlrev_b32_e32 v2, 2, v2
	v_lshl_add_u64 v[88:89], v[34:35], 0, v[2:3]
	v_or_b32_e32 v2, s7, v71
	v_mul_u32_u24_e32 v2, 0xca0, v2
	v_lshlrev_b32_e32 v2, 2, v2
	v_lshl_add_u64 v[90:91], v[34:35], 0, v[2:3]
	v_or_b32_e32 v2, s7, v72
	v_mul_u32_u24_e32 v2, 0xca0, v2
	v_lshlrev_b32_e32 v2, 2, v2
	v_lshl_add_u64 v[34:35], v[34:35], 0, v[2:3]
	global_load_dword v2, v[78:79], off nt
	s_nop 0
	global_load_dword v78, v[80:81], off nt
	global_load_dword v79, v[82:83], off nt
	s_nop 0
	global_load_dword v80, v[84:85], off nt
	global_load_dword v81, v[86:87], off nt
	global_load_dword v82, v[88:89], off nt
	global_load_dword v83, v[90:91], off nt
	s_nop 0
	global_load_dword v34, v[34:35], off nt
	v_add_u32_e32 v35, v36, v37
	s_waitcnt vmcnt(30)
	ds_write2_b32 v35, v94, v95 offset1:66
	s_waitcnt vmcnt(28)
	ds_write2_b32 v35, v96, v97 offset0:132 offset1:198
	v_add_u32_e32 v35, 0x400, v35
	s_waitcnt vmcnt(26)
	ds_write2_b32 v35, v98, v99 offset0:8 offset1:74
	v_add_u32_e32 v35, v36, v44
	s_waitcnt vmcnt(24)
	ds_write2_b32 v35, v100, v101 offset1:66
	s_waitcnt vmcnt(22)
	ds_write2_b32 v35, v102, v103 offset0:132 offset1:198
	v_add_u32_e32 v35, 0x400, v35
	s_waitcnt vmcnt(20)
	ds_write2_b32 v35, v104, v105 offset0:8 offset1:74
	v_add_u32_e32 v35, v36, v51
	s_waitcnt vmcnt(18)
	ds_write2_b32 v35, v106, v107 offset1:66
	s_waitcnt vmcnt(16)
	ds_write2_b32 v35, v108, v109 offset0:132 offset1:198
	v_add_u32_e32 v35, 0x400, v35
	s_and_b32 s0, s6, 0xffff
	s_cmp_lt_u32 s0, 37
	s_cselect_b32 s6, s37, 0xfffffd60
	s_cmp_gt_u32 s0, 15
	s_cselect_b32 s0, s6, 0
	s_add_i32 s5, s0, s5
	v_or_b32_e32 v98, s5, v73
	s_lshl_b32 s0, s4, 7
	v_ashrrev_i32_e32 v99, 31, v98
	v_lshlrev_b64 v[98:99], 11, v[98:99]
	s_waitcnt vmcnt(14)
	ds_write2_b32 v35, v110, v111 offset0:8 offset1:74
	v_add_u32_e32 v35, v36, v58
	s_waitcnt vmcnt(12)
	ds_write2_b32 v35, v112, v113 offset1:66
	s_waitcnt vmcnt(10)
	ds_write2_b32 v35, v114, v115 offset0:132 offset1:198
	v_add_u32_e32 v35, 0x400, v35
	s_waitcnt vmcnt(8)
	ds_write2_b32 v35, v116, v92 offset0:8 offset1:74
	v_add_u32_e32 v35, v36, v65
	s_waitcnt vmcnt(6)
	ds_write2_b32 v35, v2, v78 offset1:66
	s_waitcnt vmcnt(4)
	ds_write2_b32 v35, v79, v80 offset0:132 offset1:198
	v_add_u32_e32 v2, 0x400, v35
	s_waitcnt vmcnt(2)
	ds_write2_b32 v2, v81, v82 offset0:8 offset1:74
	s_waitcnt vmcnt(0)
	ds_write2_b32 v2, v83, v34 offset0:140 offset1:206
	s_waitcnt lgkmcnt(0)
	ds_read2_b32 v[34:35], v74 offset1:8
	ds_read2_b32 v[84:85], v74 offset0:33 offset1:41
	ds_read2_b32 v[86:87], v74 offset0:66 offset1:74
	ds_read2_b32 v[88:89], v74 offset0:99 offset1:107
	ds_read2_b32 v[90:91], v74 offset0:132 offset1:140
	s_waitcnt lgkmcnt(4)
	v_bfe_u32 v2, v34, 16, 1
	v_add3_u32 v2, v34, v2, s35
	s_waitcnt lgkmcnt(3)
	v_bfe_u32 v34, v84, 16, 1
	v_lshrrev_b32_e32 v2, 16, v2
	v_add3_u32 v34, v84, v34, s35
	ds_read2_b32 v[92:93], v74 offset0:165 offset1:173
	v_and_or_b32 v78, v34, s36, v2
	s_waitcnt lgkmcnt(3)
	v_bfe_u32 v2, v86, 16, 1
	v_add3_u32 v2, v86, v2, s35
	s_waitcnt lgkmcnt(2)
	v_bfe_u32 v34, v88, 16, 1
	ds_read2_b32 v[94:95], v74 offset0:198 offset1:206
	v_lshrrev_b32_e32 v2, 16, v2
	v_add3_u32 v34, v88, v34, s35
	ds_read2_b32 v[96:97], v74 offset0:231 offset1:239
	v_and_or_b32 v79, v34, s36, v2
	s_waitcnt lgkmcnt(3)
	v_bfe_u32 v2, v90, 16, 1
	v_add3_u32 v2, v90, v2, s35
	s_waitcnt lgkmcnt(2)
	v_bfe_u32 v34, v92, 16, 1
	v_lshrrev_b32_e32 v2, 16, v2
	v_add3_u32 v34, v92, v34, s35
	v_and_or_b32 v80, v34, s36, v2
	s_waitcnt lgkmcnt(1)
	v_bfe_u32 v2, v94, 16, 1
	v_add3_u32 v2, v94, v2, s35
	s_waitcnt lgkmcnt(0)
	v_bfe_u32 v34, v96, 16, 1
	v_lshrrev_b32_e32 v2, 16, v2
	v_add3_u32 v34, v96, v34, s35
	v_and_or_b32 v81, v34, s36, v2
	v_bfe_u32 v2, v35, 16, 1
	v_lshl_add_u64 v[82:83], v[14:15], 0, s[0:1]
	v_add3_u32 v2, v35, v2, s35
	v_bfe_u32 v34, v85, 16, 1
	v_lshl_add_u64 v[98:99], v[82:83], 0, v[98:99]
	v_lshrrev_b32_e32 v2, 16, v2
	v_add3_u32 v34, v85, v34, s35
	global_store_dwordx4 v[98:99], v[78:81], off
	ds_read2_b32 v[84:85], v74 offset0:16 offset1:24
	v_or_b32_e32 v98, s5, v76
	v_and_or_b32 v78, v34, s36, v2
	v_bfe_u32 v2, v87, 16, 1
	v_add3_u32 v2, v87, v2, s35
	v_bfe_u32 v34, v89, 16, 1
	v_lshrrev_b32_e32 v2, 16, v2
	v_add3_u32 v34, v89, v34, s35
	v_and_or_b32 v79, v34, s36, v2
	v_bfe_u32 v2, v91, 16, 1
	v_add3_u32 v2, v91, v2, s35
	v_bfe_u32 v34, v93, 16, 1
	v_lshrrev_b32_e32 v2, 16, v2
	v_add3_u32 v34, v93, v34, s35
	v_and_or_b32 v80, v34, s36, v2
	v_bfe_u32 v2, v95, 16, 1
	v_add3_u32 v2, v95, v2, s35
	v_bfe_u32 v34, v97, 16, 1
	v_lshrrev_b32_e32 v2, 16, v2
	v_add3_u32 v34, v97, v34, s35
	v_and_or_b32 v81, v34, s36, v2
	v_or_b32_e32 v34, s5, v75
	v_ashrrev_i32_e32 v35, 31, v34
	v_lshlrev_b64 v[34:35], 11, v[34:35]
	v_lshl_add_u64 v[34:35], v[82:83], 0, v[34:35]
	global_store_dwordx4 v[34:35], v[78:81], off
	ds_read2_b32 v[34:35], v74 offset0:49 offset1:57
	ds_read2_b32 v[86:87], v74 offset0:82 offset1:90
	ds_read2_b32 v[88:89], v74 offset0:115 offset1:123
	s_waitcnt lgkmcnt(3)
	v_bfe_u32 v2, v84, 16, 1
	v_add3_u32 v2, v84, v2, s35
	s_waitcnt lgkmcnt(2)
	v_bfe_u32 v78, v34, 16, 1
	ds_read2_b32 v[90:91], v74 offset0:148 offset1:156
	v_lshrrev_b32_e32 v2, 16, v2
	v_add3_u32 v34, v34, v78, s35
	ds_read2_b32 v[92:93], v74 offset0:181 offset1:189
	v_and_or_b32 v78, v34, s36, v2
	s_waitcnt lgkmcnt(3)
	v_bfe_u32 v2, v86, 16, 1
	v_add3_u32 v2, v86, v2, s35
	s_waitcnt lgkmcnt(2)
	v_bfe_u32 v34, v88, 16, 1
	ds_read2_b32 v[94:95], v74 offset0:214 offset1:222
	v_lshrrev_b32_e32 v2, 16, v2
	v_add3_u32 v34, v88, v34, s35
	ds_read2_b32 v[96:97], v74 offset0:247 offset1:255
	v_and_or_b32 v79, v34, s36, v2
	s_waitcnt lgkmcnt(3)
	v_bfe_u32 v2, v90, 16, 1
	v_add3_u32 v2, v90, v2, s35
	s_waitcnt lgkmcnt(2)
	v_bfe_u32 v34, v92, 16, 1
	v_lshrrev_b32_e32 v2, 16, v2
	v_add3_u32 v34, v92, v34, s35
	v_and_or_b32 v80, v34, s36, v2
	s_waitcnt lgkmcnt(1)
	v_bfe_u32 v2, v94, 16, 1
	v_add3_u32 v2, v94, v2, s35
	s_waitcnt lgkmcnt(0)
	v_bfe_u32 v34, v96, 16, 1
	v_lshrrev_b32_e32 v2, 16, v2
	v_add3_u32 v34, v96, v34, s35
	v_and_or_b32 v81, v34, s36, v2
	v_ashrrev_i32_e32 v99, 31, v98
	v_bfe_u32 v2, v85, 16, 1
	v_lshlrev_b64 v[98:99], 11, v[98:99]
	v_add3_u32 v2, v85, v2, s35
	v_bfe_u32 v34, v35, 16, 1
	v_lshl_add_u64 v[98:99], v[82:83], 0, v[98:99]
	v_lshrrev_b32_e32 v2, 16, v2
	v_add3_u32 v34, v35, v34, s35
	global_store_dwordx4 v[98:99], v[78:81], off
	s_nop 1
	v_and_or_b32 v78, v34, s36, v2
	v_bfe_u32 v2, v87, 16, 1
	v_add3_u32 v2, v87, v2, s35
	v_bfe_u32 v34, v89, 16, 1
	v_lshrrev_b32_e32 v2, 16, v2
	v_add3_u32 v34, v89, v34, s35
	v_and_or_b32 v79, v34, s36, v2
	v_bfe_u32 v2, v91, 16, 1
	v_add3_u32 v2, v91, v2, s35
	v_bfe_u32 v34, v93, 16, 1
	v_lshrrev_b32_e32 v2, 16, v2
	v_add3_u32 v34, v93, v34, s35
	v_and_or_b32 v80, v34, s36, v2
	v_bfe_u32 v2, v95, 16, 1
	v_add3_u32 v2, v95, v2, s35
	v_bfe_u32 v34, v97, 16, 1
	v_lshrrev_b32_e32 v2, 16, v2
	v_add3_u32 v34, v97, v34, s35
	v_and_or_b32 v81, v34, s36, v2
	v_or_b32_e32 v34, s5, v77
	v_ashrrev_i32_e32 v35, 31, v34
	v_lshlrev_b64 v[34:35], 11, v[34:35]
	v_lshl_add_u64 v[34:35], v[82:83], 0, v[34:35]
	global_store_dwordx4 v[34:35], v[78:81], off
	s_waitcnt lgkmcnt(0)

.LBB0_37:
	s_andn2_b64 vcc, exec, s[4:5]
	s_cbranch_vccnz .LBB0_10
	s_mul_hi_i32 s0, s39, 0x2e8ba2e9
	s_lshr_b32 s4, s0, 31
	s_ashr_i32 s0, s0, 5
	s_add_i32 s0, s0, s4
	s_mul_i32 s5, s0, 0xffffea00
	s_add_i32 s6, s28, s5
	s_lshl_b32 s4, s0, 6
	s_ashr_i32 s7, s6, 31
	v_lshl_add_u64 v[34:35], s[6:7], 2, v[32:33]
	v_or_b32_e32 v2, s4, v1
	v_mad_i64_i32 v[78:79], s[10:11], v2, s38, v[34:35]
	v_or_b32_e32 v2, s4, v38
	v_mad_i64_i32 v[80:81], s[10:11], v2, s38, v[34:35]
	v_or_b32_e32 v2, s4, v39
	v_mad_i64_i32 v[82:83], s[10:11], v2, s38, v[34:35]
	v_or_b32_e32 v2, s4, v40
	v_mad_i64_i32 v[84:85], s[10:11], v2, s38, v[34:35]
	v_or_b32_e32 v2, s4, v41
	v_or_b32_e32 v88, s4, v42
	v_or_b32_e32 v90, s4, v43
	v_or_b32_e32 v92, s4, v45
	v_or_b32_e32 v94, s4, v46
	v_or_b32_e32 v96, s4, v47
	v_or_b32_e32 v98, s4, v48
	v_or_b32_e32 v100, s4, v49
	v_mad_i64_i32 v[86:87], s[10:11], v2, s38, v[34:35]
	v_mad_i64_i32 v[88:89], s[10:11], v88, s38, v[34:35]
	v_mad_i64_i32 v[90:91], s[10:11], v90, s38, v[34:35]
	v_mad_i64_i32 v[92:93], s[10:11], v92, s38, v[34:35]
	global_load_dword v2, v[78:79], off nt
	global_load_dword v111, v[80:81], off nt
	global_load_dword v112, v[82:83], off nt
	global_load_dword v113, v[84:85], off nt
	global_load_dword v114, v[86:87], off nt
	global_load_dword v115, v[88:89], off nt
	global_load_dword v116, v[90:91], off nt
	global_load_dword v117, v[92:93], off nt
	v_or_b32_e32 v102, s4, v50
	v_or_b32_e32 v104, s4, v52
	v_or_b32_e32 v105, s4, v53
	v_or_b32_e32 v106, s4, v54
	v_mad_i64_i32 v[94:95], s[10:11], v94, s38, v[34:35]
	v_mad_i64_i32 v[96:97], s[10:11], v96, s38, v[34:35]
	v_mad_i64_i32 v[98:99], s[10:11], v98, s38, v[34:35]
	v_mad_i64_i32 v[100:101], s[10:11], v100, s38, v[34:35]
	v_mad_i64_i32 v[102:103], s[10:11], v102, s38, v[34:35]
	v_mad_i64_i32 v[78:79], s[10:11], v104, s38, v[34:35]
	v_mad_i64_i32 v[80:81], s[10:11], v105, s38, v[34:35]
	v_mad_i64_i32 v[82:83], s[10:11], v106, s38, v[34:35]
	global_load_dword v94, v[94:95], off nt
	s_nop 0
	global_load_dword v95, v[96:97], off nt
	s_nop 0
	global_load_dword v96, v[98:99], off nt
	global_load_dword v97, v[100:101], off nt
	s_nop 0
	global_load_dword v98, v[102:103], off nt
	global_load_dword v99, v[78:79], off nt
	global_load_dword v100, v[80:81], off nt
	global_load_dword v101, v[82:83], off nt
	v_or_b32_e32 v107, s4, v55
	v_or_b32_e32 v108, s4, v56
	v_or_b32_e32 v109, s4, v57
	v_or_b32_e32 v110, s4, v59
	v_or_b32_e32 v80, s4, v60
	v_or_b32_e32 v82, s4, v61
	v_or_b32_e32 v90, s4, v62
	v_or_b32_e32 v92, s4, v63
	v_mad_i64_i32 v[84:85], s[10:11], v107, s38, v[34:35]
	v_mad_i64_i32 v[86:87], s[10:11], v108, s38, v[34:35]
	v_mad_i64_i32 v[88:89], s[10:11], v109, s38, v[34:35]
	v_mad_i64_i32 v[78:79], s[10:11], v110, s38, v[34:35]
	v_mad_i64_i32 v[80:81], s[10:11], v80, s38, v[34:35]
	v_mad_i64_i32 v[82:83], s[10:11], v82, s38, v[34:35]
	v_mad_i64_i32 v[90:91], s[10:11], v90, s38, v[34:35]
	v_mad_i64_i32 v[92:93], s[10:11], v92, s38, v[34:35]
	global_load_dword v102, v[84:85], off nt
	global_load_dword v103, v[86:87], off nt
	global_load_dword v104, v[88:89], off nt
	global_load_dword v105, v[78:79], off nt
	global_load_dword v106, v[80:81], off nt
	global_load_dword v107, v[82:83], off nt
	global_load_dword v108, v[90:91], off nt
	s_nop 0
	global_load_dword v92, v[92:93], off nt
	v_or_b32_e32 v78, s4, v64
	v_or_b32_e32 v80, s4, v66
	v_or_b32_e32 v82, s4, v67
	v_or_b32_e32 v84, s4, v68
	v_or_b32_e32 v86, s4, v69
	v_or_b32_e32 v88, s4, v70
	v_or_b32_e32 v90, s4, v71
	v_or_b32_e32 v93, s4, v72
	v_mad_i64_i32 v[78:79], s[10:11], v78, s38, v[34:35]
	v_mad_i64_i32 v[80:81], s[10:11], v80, s38, v[34:35]
	v_mad_i64_i32 v[82:83], s[10:11], v82, s38, v[34:35]
	v_mad_i64_i32 v[84:85], s[10:11], v84, s38, v[34:35]
	v_mad_i64_i32 v[86:87], s[10:11], v86, s38, v[34:35]
	v_mad_i64_i32 v[88:89], s[10:11], v88, s38, v[34:35]
	v_mad_i64_i32 v[90:91], s[10:11], v90, s38, v[34:35]
	v_mad_i64_i32 v[34:35], s[10:11], v93, s38, v[34:35]
	global_load_dword v78, v[78:79], off nt
	s_nop 0
	global_load_dword v79, v[80:81], off nt
	s_nop 0
	global_load_dword v80, v[82:83], off nt
	global_load_dword v81, v[84:85], off nt
	s_nop 0
	global_load_dword v82, v[86:87], off nt
	global_load_dword v83, v[88:89], off nt
	global_load_dword v84, v[90:91], off nt
	s_nop 0
	global_load_dword v34, v[34:35], off nt
	v_add_u32_e32 v35, v36, v37
	s_waitcnt vmcnt(30)
	ds_write2_b32 v35, v2, v111 offset1:66
	s_waitcnt vmcnt(28)
	ds_write2_b32 v35, v112, v113 offset0:132 offset1:198
	v_add_u32_e32 v2, 0x400, v35
	s_waitcnt vmcnt(26)
	ds_write2_b32 v2, v114, v115 offset0:8 offset1:74
	v_add_u32_e32 v2, v36, v44
	s_waitcnt vmcnt(24)
	ds_write2_b32 v2, v116, v117 offset1:66
	s_waitcnt vmcnt(22)
	ds_write2_b32 v2, v94, v95 offset0:132 offset1:198
	v_add_u32_e32 v2, 0x400, v2
	s_waitcnt vmcnt(20)
	ds_write2_b32 v2, v96, v97 offset0:8 offset1:74
	v_add_u32_e32 v2, v36, v51
	s_waitcnt vmcnt(18)
	ds_write2_b32 v2, v98, v99 offset1:66
	s_waitcnt vmcnt(16)
	ds_write2_b32 v2, v100, v101 offset0:132 offset1:198
	v_add_u32_e32 v2, 0x400, v2
	s_mulk_i32 s0, 0xff50
	s_add_i32 s0, s39, s0
	s_add_i32 s5, s6, 0xfffff500
	s_cmpk_lt_i32 s0, 0x58
	s_cselect_b32 s0, s6, s5
	s_cselect_b32 s5, 0, 0x80
	s_lshl_b32 s6, s0, 1
	s_and_b32 s0, s0, 0x60
	s_and_b32 s6, s6, 0xffffff00
	s_or_b32 s0, s0, s5
	s_or_b32 s0, s0, s6
	v_or_b32_e32 v98, s0, v73
	s_ashr_i32 s5, s4, 31
	v_ashrrev_i32_e32 v99, 31, v98
	v_lshlrev_b64 v[98:99], 11, v[98:99]
	s_waitcnt vmcnt(14)
	ds_write2_b32 v2, v102, v103 offset0:8 offset1:74
	v_add_u32_e32 v2, v36, v58
	s_waitcnt vmcnt(12)
	ds_write2_b32 v2, v104, v105 offset1:66
	s_waitcnt vmcnt(10)
	ds_write2_b32 v2, v106, v107 offset0:132 offset1:198
	v_add_u32_e32 v2, 0x400, v2
	s_waitcnt vmcnt(8)
	ds_write2_b32 v2, v108, v92 offset0:8 offset1:74
	v_add_u32_e32 v2, v36, v65
	s_waitcnt vmcnt(6)
	ds_write2_b32 v2, v78, v79 offset1:66
	s_waitcnt vmcnt(4)
	ds_write2_b32 v2, v80, v81 offset0:132 offset1:198
	v_add_u32_e32 v2, 0x400, v2
	s_waitcnt vmcnt(2)
	ds_write2_b32 v2, v82, v83 offset0:8 offset1:74
	s_waitcnt vmcnt(0)
	ds_write2_b32 v2, v84, v34 offset0:140 offset1:206
	s_waitcnt lgkmcnt(0)
	ds_read2_b32 v[34:35], v74 offset1:8
	ds_read2_b32 v[84:85], v74 offset0:33 offset1:41
	ds_read2_b32 v[86:87], v74 offset0:66 offset1:74
	ds_read2_b32 v[88:89], v74 offset0:99 offset1:107
	ds_read2_b32 v[90:91], v74 offset0:132 offset1:140
	s_waitcnt lgkmcnt(4)
	v_bfe_u32 v2, v34, 16, 1
	v_add3_u32 v2, v34, v2, s35
	s_waitcnt lgkmcnt(3)
	v_bfe_u32 v34, v84, 16, 1
	v_lshrrev_b32_e32 v2, 16, v2
	v_add3_u32 v34, v84, v34, s35
	ds_read2_b32 v[92:93], v74 offset0:165 offset1:173
	v_and_or_b32 v78, v34, s36, v2
	s_waitcnt lgkmcnt(3)
	v_bfe_u32 v2, v86, 16, 1
	v_add3_u32 v2, v86, v2, s35
	s_waitcnt lgkmcnt(2)
	v_bfe_u32 v34, v88, 16, 1
	ds_read2_b32 v[94:95], v74 offset0:198 offset1:206
	v_lshrrev_b32_e32 v2, 16, v2
	v_add3_u32 v34, v88, v34, s35
	ds_read2_b32 v[96:97], v74 offset0:231 offset1:239
	v_and_or_b32 v79, v34, s36, v2
	s_waitcnt lgkmcnt(3)
	v_bfe_u32 v2, v90, 16, 1
	v_add3_u32 v2, v90, v2, s35
	s_waitcnt lgkmcnt(2)
	v_bfe_u32 v34, v92, 16, 1
	v_lshrrev_b32_e32 v2, 16, v2
	v_add3_u32 v34, v92, v34, s35
	v_and_or_b32 v80, v34, s36, v2
	s_waitcnt lgkmcnt(1)
	v_bfe_u32 v2, v94, 16, 1
	v_add3_u32 v2, v94, v2, s35
	s_waitcnt lgkmcnt(0)
	v_bfe_u32 v34, v96, 16, 1
	v_lshrrev_b32_e32 v2, 16, v2
	v_add3_u32 v34, v96, v34, s35
	v_and_or_b32 v81, v34, s36, v2
	v_bfe_u32 v2, v35, 16, 1
	v_lshl_add_u64 v[82:83], s[4:5], 1, v[16:17]
	v_add3_u32 v2, v35, v2, s35
	v_bfe_u32 v34, v85, 16, 1
	v_lshl_add_u64 v[98:99], v[82:83], 0, v[98:99]
	v_lshrrev_b32_e32 v2, 16, v2
	v_add3_u32 v34, v85, v34, s35
	global_store_dwordx4 v[98:99], v[78:81], off
	ds_read2_b32 v[84:85], v74 offset0:16 offset1:24
	v_or_b32_e32 v98, s0, v76
	v_and_or_b32 v78, v34, s36, v2
	v_bfe_u32 v2, v87, 16, 1
	v_add3_u32 v2, v87, v2, s35
	v_bfe_u32 v34, v89, 16, 1
	v_lshrrev_b32_e32 v2, 16, v2
	v_add3_u32 v34, v89, v34, s35
	v_and_or_b32 v79, v34, s36, v2
	v_bfe_u32 v2, v91, 16, 1
	v_add3_u32 v2, v91, v2, s35
	v_bfe_u32 v34, v93, 16, 1
	v_lshrrev_b32_e32 v2, 16, v2
	v_add3_u32 v34, v93, v34, s35
	v_and_or_b32 v80, v34, s36, v2
	v_bfe_u32 v2, v95, 16, 1
	v_add3_u32 v2, v95, v2, s35
	v_bfe_u32 v34, v97, 16, 1
	v_lshrrev_b32_e32 v2, 16, v2
	v_add3_u32 v34, v97, v34, s35
	v_and_or_b32 v81, v34, s36, v2
	v_or_b32_e32 v34, s0, v75
	v_ashrrev_i32_e32 v35, 31, v34
	v_lshlrev_b64 v[34:35], 11, v[34:35]
	v_lshl_add_u64 v[34:35], v[82:83], 0, v[34:35]
	global_store_dwordx4 v[34:35], v[78:81], off
	ds_read2_b32 v[34:35], v74 offset0:49 offset1:57
	ds_read2_b32 v[86:87], v74 offset0:82 offset1:90
	ds_read2_b32 v[88:89], v74 offset0:115 offset1:123
	s_waitcnt lgkmcnt(3)
	v_bfe_u32 v2, v84, 16, 1
	v_add3_u32 v2, v84, v2, s35
	s_waitcnt lgkmcnt(2)
	v_bfe_u32 v78, v34, 16, 1
	ds_read2_b32 v[90:91], v74 offset0:148 offset1:156
	v_lshrrev_b32_e32 v2, 16, v2
	v_add3_u32 v34, v34, v78, s35
	ds_read2_b32 v[92:93], v74 offset0:181 offset1:189
	v_and_or_b32 v78, v34, s36, v2
	s_waitcnt lgkmcnt(3)
	v_bfe_u32 v2, v86, 16, 1
	v_add3_u32 v2, v86, v2, s35
	s_waitcnt lgkmcnt(2)
	v_bfe_u32 v34, v88, 16, 1
	ds_read2_b32 v[94:95], v74 offset0:214 offset1:222
	v_lshrrev_b32_e32 v2, 16, v2
	v_add3_u32 v34, v88, v34, s35
	ds_read2_b32 v[96:97], v74 offset0:247 offset1:255
	v_and_or_b32 v79, v34, s36, v2
	s_waitcnt lgkmcnt(3)
	v_bfe_u32 v2, v90, 16, 1
	v_add3_u32 v2, v90, v2, s35
	s_waitcnt lgkmcnt(2)
	v_bfe_u32 v34, v92, 16, 1
	v_lshrrev_b32_e32 v2, 16, v2
	v_add3_u32 v34, v92, v34, s35
	v_and_or_b32 v80, v34, s36, v2
	s_waitcnt lgkmcnt(1)
	v_bfe_u32 v2, v94, 16, 1
	v_add3_u32 v2, v94, v2, s35
	s_waitcnt lgkmcnt(0)
	v_bfe_u32 v34, v96, 16, 1
	v_lshrrev_b32_e32 v2, 16, v2
	v_add3_u32 v34, v96, v34, s35
	v_and_or_b32 v81, v34, s36, v2
	v_ashrrev_i32_e32 v99, 31, v98
	v_bfe_u32 v2, v85, 16, 1
	v_lshlrev_b64 v[98:99], 11, v[98:99]
	v_add3_u32 v2, v85, v2, s35
	v_bfe_u32 v34, v35, 16, 1
	v_lshl_add_u64 v[98:99], v[82:83], 0, v[98:99]
	v_lshrrev_b32_e32 v2, 16, v2
	v_add3_u32 v34, v35, v34, s35
	global_store_dwordx4 v[98:99], v[78:81], off
	s_nop 1
	v_and_or_b32 v78, v34, s36, v2
	v_bfe_u32 v2, v87, 16, 1
	v_add3_u32 v2, v87, v2, s35
	v_bfe_u32 v34, v89, 16, 1
	v_lshrrev_b32_e32 v2, 16, v2
	v_add3_u32 v34, v89, v34, s35
	v_and_or_b32 v79, v34, s36, v2
	v_bfe_u32 v2, v91, 16, 1
	v_add3_u32 v2, v91, v2, s35
	v_bfe_u32 v34, v93, 16, 1
	v_lshrrev_b32_e32 v2, 16, v2
	v_add3_u32 v34, v93, v34, s35
	v_and_or_b32 v80, v34, s36, v2
	v_bfe_u32 v2, v95, 16, 1
	v_add3_u32 v2, v95, v2, s35
	v_bfe_u32 v34, v97, 16, 1
	v_lshrrev_b32_e32 v2, 16, v2
	v_add3_u32 v34, v97, v34, s35
	v_and_or_b32 v81, v34, s36, v2
	v_or_b32_e32 v34, s0, v77
	v_ashrrev_i32_e32 v35, 31, v34
	v_lshlrev_b64 v[34:35], 11, v[34:35]
	v_lshl_add_u64 v[34:35], v[82:83], 0, v[34:35]
	global_store_dwordx4 v[34:35], v[78:81], off
	s_waitcnt lgkmcnt(0)
	s_branch .LBB0_10

.LBB0_72:
	s_or_b64 exec, exec, s[4:5]
	global_load_dwordx4 v[56:59], v[36:37], off nt
	global_load_dwordx4 v[60:63], v[38:39], off nt
	v_pk_mul_f32 v[44:45], v[44:45], v[32:33] op_sel_hi:[1,0]
	v_pk_mul_f32 v[30:31], v[30:31], v[32:33] op_sel_hi:[1,0]
	v_pk_mul_f32 v[28:29], v[28:29], v[46:47] op_sel_hi:[1,0]
	v_pk_mul_f32 v[26:27], v[26:27], v[46:47] op_sel_hi:[1,0]
	s_lshl_b64 s[4:5], s[30:31], 11
	v_lshl_add_u64 v[64:65], v[40:41], 0, s[4:5]
	v_pk_mul_f32 v[20:21], v[20:21], v[46:47] op_sel_hi:[1,0]
	v_pk_mul_f32 v[18:19], v[18:19], v[46:47] op_sel_hi:[1,0]
	v_pk_mul_f32 v[12:13], v[12:13], v[46:47] op_sel_hi:[1,0]
	v_pk_mul_f32 v[10:11], v[10:11], v[46:47] op_sel_hi:[1,0]
	v_pk_mul_f32 v[4:5], v[4:5], v[46:47] op_sel_hi:[1,0]
	v_pk_mul_f32 v[2:3], v[2:3], v[46:47] op_sel_hi:[1,0]
	s_add_i32 s36, s36, s10
	s_add_u32 s16, s16, s10
	s_addc_u32 s17, s17, s11
	s_add_i32 s28, s28, s3
	s_cmp_gt_i32 s36, 0x800f
	s_waitcnt vmcnt(0)
	v_pk_fma_f32 v[44:45], v[44:45], v[58:59], v[62:63]
	v_pk_fma_f32 v[30:31], v[30:31], v[56:57], v[60:61]
	v_pk_fma_f32 v[28:29], v[28:29], v[58:59], v[62:63]
	v_pk_fma_f32 v[26:27], v[26:27], v[56:57], v[60:61]
	v_bfe_u32 v33, v30, 16, 1
	v_bfe_u32 v56, v44, 16, 1
	v_bfe_u32 v55, v31, 16, 1
	v_bfe_u32 v57, v45, 16, 1
	v_bfe_u32 v58, v26, 16, 1
	v_bfe_u32 v59, v27, 16, 1
	v_bfe_u32 v60, v28, 16, 1
	v_add3_u32 v30, v30, v33, s33
	v_add3_u32 v33, v44, v56, s33
	v_bfe_u32 v61, v29, 16, 1
	v_add3_u32 v31, v31, v55, s33
	v_add3_u32 v44, v45, v57, s33
	v_add3_u32 v26, v26, v58, s33
	v_add3_u32 v45, v27, v59, s33
	v_add3_u32 v27, v28, v60, s33
	v_lshrrev_b32_e32 v28, 16, v30
	v_lshrrev_b32_e32 v30, 16, v33
	v_add3_u32 v29, v29, v61, s33
	v_lshrrev_b32_e32 v33, 16, v26
	v_lshrrev_b32_e32 v55, 16, v27
	v_and_or_b32 v26, v31, s35, v28
	v_and_or_b32 v27, v44, s35, v30
	v_and_or_b32 v28, v45, s35, v33
	v_and_or_b32 v29, v29, s35, v55
	global_store_dwordx2 v[42:43], v[26:27], off
	global_store_dwordx2 v[64:65], v[28:29], off
	global_load_dwordx4 v[26:29], v[36:37], off offset:1024 nt
	s_nop 0
	global_load_dwordx4 v[56:59], v[38:39], off offset:1024 nt
	v_pk_mul_f32 v[24:25], v[24:25], v[32:33] op_sel_hi:[1,0]
	v_pk_mul_f32 v[22:23], v[22:23], v[32:33] op_sel_hi:[1,0]
	s_waitcnt vmcnt(0)
	v_pk_fma_f32 v[24:25], v[24:25], v[28:29], v[58:59]
	v_pk_fma_f32 v[22:23], v[22:23], v[26:27], v[56:57]
	v_pk_fma_f32 v[20:21], v[20:21], v[28:29], v[58:59]
	v_pk_fma_f32 v[18:19], v[18:19], v[26:27], v[56:57]
	v_bfe_u32 v26, v22, 16, 1
	v_bfe_u32 v28, v24, 16, 1
	v_bfe_u32 v27, v23, 16, 1
	v_bfe_u32 v29, v25, 16, 1
	v_bfe_u32 v30, v18, 16, 1
	v_bfe_u32 v31, v19, 16, 1
	v_bfe_u32 v33, v20, 16, 1
	v_add3_u32 v22, v22, v26, s33
	v_add3_u32 v24, v24, v28, s33
	v_bfe_u32 v44, v21, 16, 1
	v_add3_u32 v23, v23, v27, s33
	v_add3_u32 v25, v25, v29, s33
	v_add3_u32 v18, v18, v30, s33
	v_add3_u32 v26, v19, v31, s33
	v_add3_u32 v19, v20, v33, s33
	v_lshrrev_b32_e32 v20, 16, v22
	v_lshrrev_b32_e32 v22, 16, v24
	v_add3_u32 v21, v21, v44, s33
	v_lshrrev_b32_e32 v24, 16, v18
	v_lshrrev_b32_e32 v27, 16, v19
	v_and_or_b32 v18, v23, s35, v20
	v_and_or_b32 v19, v25, s35, v22
	v_and_or_b32 v20, v26, s35, v24
	v_and_or_b32 v21, v21, s35, v27
	global_store_dwordx2 v[42:43], v[18:19], off offset:512
	global_store_dwordx2 v[64:65], v[20:21], off offset:512
	global_load_dwordx4 v[18:21], v[36:37], off offset:2048 nt
	s_nop 0
	global_load_dwordx4 v[22:25], v[38:39], off offset:2048 nt
	v_pk_mul_f32 v[16:17], v[16:17], v[32:33] op_sel_hi:[1,0]
	v_pk_mul_f32 v[14:15], v[14:15], v[32:33] op_sel_hi:[1,0]
	v_pk_mul_f32 v[8:9], v[8:9], v[32:33] op_sel_hi:[1,0]
	v_pk_mul_f32 v[6:7], v[6:7], v[32:33] op_sel_hi:[1,0]
	s_waitcnt vmcnt(0)
	v_pk_fma_f32 v[16:17], v[16:17], v[20:21], v[24:25]
	v_pk_fma_f32 v[14:15], v[14:15], v[18:19], v[22:23]
	v_pk_fma_f32 v[12:13], v[12:13], v[20:21], v[24:25]
	v_pk_fma_f32 v[10:11], v[10:11], v[18:19], v[22:23]
	v_bfe_u32 v18, v14, 16, 1
	v_bfe_u32 v20, v16, 16, 1
	v_bfe_u32 v19, v15, 16, 1
	v_bfe_u32 v21, v17, 16, 1
	v_bfe_u32 v22, v10, 16, 1
	v_bfe_u32 v23, v11, 16, 1
	v_bfe_u32 v24, v12, 16, 1
	v_add3_u32 v14, v14, v18, s33
	v_add3_u32 v16, v16, v20, s33
	v_bfe_u32 v25, v13, 16, 1
	v_add3_u32 v15, v15, v19, s33
	v_add3_u32 v17, v17, v21, s33
	v_add3_u32 v10, v10, v22, s33
	v_add3_u32 v18, v11, v23, s33
	v_add3_u32 v11, v12, v24, s33
	v_lshrrev_b32_e32 v12, 16, v14
	v_lshrrev_b32_e32 v14, 16, v16
	v_add3_u32 v13, v13, v25, s33
	v_lshrrev_b32_e32 v16, 16, v10
	v_lshrrev_b32_e32 v19, 16, v11
	v_and_or_b32 v10, v15, s35, v12
	v_and_or_b32 v11, v17, s35, v14
	v_and_or_b32 v12, v18, s35, v16
	v_and_or_b32 v13, v13, s35, v19
	global_store_dwordx2 v[42:43], v[10:11], off offset:1024
	global_store_dwordx2 v[64:65], v[12:13], off offset:1024
	global_load_dwordx4 v[10:13], v[36:37], off offset:3072 nt
	s_nop 0
	global_load_dwordx4 v[14:17], v[38:39], off offset:3072 nt
	s_waitcnt vmcnt(0)
	v_pk_fma_f32 v[8:9], v[8:9], v[12:13], v[16:17]
	v_pk_fma_f32 v[6:7], v[6:7], v[10:11], v[14:15]
	v_pk_fma_f32 v[4:5], v[4:5], v[12:13], v[16:17]
	v_pk_fma_f32 v[2:3], v[2:3], v[10:11], v[14:15]
	v_bfe_u32 v10, v6, 16, 1
	v_bfe_u32 v12, v8, 16, 1
	v_bfe_u32 v11, v7, 16, 1
	v_bfe_u32 v13, v9, 16, 1
	v_bfe_u32 v14, v2, 16, 1
	v_bfe_u32 v15, v3, 16, 1
	v_bfe_u32 v16, v4, 16, 1
	v_add3_u32 v6, v6, v10, s33
	v_add3_u32 v8, v8, v12, s33
	v_bfe_u32 v17, v5, 16, 1
	v_add3_u32 v7, v7, v11, s33
	v_add3_u32 v9, v9, v13, s33
	v_add3_u32 v2, v2, v14, s33
	v_add3_u32 v10, v3, v15, s33
	v_add3_u32 v3, v4, v16, s33
	v_lshrrev_b32_e32 v4, 16, v6
	v_lshrrev_b32_e32 v6, 16, v8
	v_add3_u32 v5, v5, v17, s33
	v_lshrrev_b32_e32 v8, 16, v2
	v_lshrrev_b32_e32 v11, 16, v3
	v_and_or_b32 v2, v7, s35, v4
	v_and_or_b32 v3, v9, s35, v6
	v_and_or_b32 v4, v10, s35, v8
	v_and_or_b32 v5, v5, s35, v11
	global_store_dwordx2 v[42:43], v[2:3], off offset:1536
	global_store_dwordx2 v[64:65], v[4:5], off offset:1536
	v_lshl_add_u64 v[42:43], v[42:43], 0, s[22:23]
	s_cbranch_scc1 .LBB0_79

.LBB0_77:
	v_lshl_add_u64 v[2:3], s[4:5], 0, v[34:35]
	s_add_i32 s4, s36, 0xffff8000
	v_readlane_b32 s6, v240, 26
	v_readlane_b32 s7, v240, 27
	s_add_u32 s6, s6, s16
	s_addc_u32 s5, s7, s17
	global_load_dwordx4 v[26:29], v[2:3], off nt
	global_load_dwordx4 v[18:21], v[2:3], off offset:1024 nt
	global_load_dwordx4 v[10:13], v[2:3], off offset:2048 nt
	s_nop 0
	global_load_dwordx4 v[2:5], v[2:3], off offset:3072 nt
	s_cmp_lt_i32 s36, 0x8000
	v_readlane_b32 s40, v240, 4
	s_cselect_b32 s5, s5, 0
	s_cselect_b32 s4, s6, s4
	v_readlane_b32 s41, v240, 5
	v_readlane_b32 s42, v240, 6
	v_readlane_b32 s43, v240, 7
	s_cselect_b32 s6, s41, s43
	s_cselect_b32 s7, s40, s42
	s_lshl_b64 s[4:5], s[4:5], 12
	s_add_u32 s4, s7, s4
	s_addc_u32 s5, s6, s5
	v_lshl_add_u64 v[6:7], s[4:5], 0, v[34:35]
	global_load_dwordx4 v[30:33], v[6:7], off nt
	global_load_dwordx4 v[22:25], v[6:7], off offset:1024 nt
	global_load_dwordx4 v[14:17], v[6:7], off offset:2048 nt
	s_nop 0
	global_load_dwordx4 v[6:9], v[6:7], off offset:3072 nt
	v_readlane_b32 s44, v240, 8
	v_readlane_b32 s45, v240, 9
	v_readlane_b32 s46, v240, 10
	v_readlane_b32 s47, v240, 11
	v_readlane_b32 s48, v240, 12
	v_readlane_b32 s49, v240, 13
	v_readlane_b32 s50, v240, 14
	v_readlane_b32 s51, v240, 15
	v_readlane_b32 s52, v240, 16
	v_readlane_b32 s53, v240, 17
	v_readlane_b32 s54, v240, 18
	v_readlane_b32 s55, v240, 19
	s_waitcnt vmcnt(7)
	v_mov_b32_e32 v44, v27
	v_mov_b32_e32 v45, v28
	v_mov_b32_e32 v56, v26
	v_mov_b32_e32 v57, v29
	s_waitcnt vmcnt(6)
	v_mov_b32_e32 v58, v19
	v_mov_b32_e32 v59, v20
	v_mov_b32_e32 v60, v18
	v_mov_b32_e32 v61, v21
	v_pk_add_f32 v[44:45], v[44:45], v[56:57]
	v_pk_add_f32 v[56:57], v[58:59], v[60:61]
	v_add_f32_e32 v46, v44, v45
	v_pk_add_f32 v[44:45], v[56:57], v[56:57] op_sel:[0,1] op_sel_hi:[1,0]
	s_waitcnt vmcnt(5)
	v_add_f32_e32 v62, v10, v11
	v_add_f32_e32 v64, v12, v13
	s_waitcnt vmcnt(4)
	v_mov_b32_e32 v67, v2
	v_mov_b32_e32 v63, v4
	v_mov_b32_e32 v65, v5
	v_add_f32_e32 v66, 0, v46
	v_mov_b32_e32 v45, v3
	v_pk_add_f32 v[58:59], v[62:63], v[64:65]
	v_pk_add_f32 v[44:45], v[66:67], v[44:45]
	s_waitcnt vmcnt(3)
	v_mov_b32_e32 v56, v30
	v_pk_add_f32 v[44:45], v[44:45], v[58:59]
	v_mov_b32_e32 v57, v33
	v_add_f32_e32 v46, v44, v45
	v_mov_b32_e32 v44, v31
	v_mov_b32_e32 v45, v32
	s_waitcnt vmcnt(2)
	v_mov_b32_e32 v58, v23
	v_mov_b32_e32 v59, v24
	v_mov_b32_e32 v60, v22
	v_mov_b32_e32 v61, v25
	v_pk_add_f32 v[44:45], v[44:45], v[56:57]
	v_pk_add_f32 v[56:57], v[58:59], v[60:61]
	v_add_f32_e32 v60, v44, v45
	v_pk_add_f32 v[44:45], v[56:57], v[56:57] op_sel:[0,1] op_sel_hi:[1,0]
	s_waitcnt vmcnt(1)
	v_add_f32_e32 v62, v14, v15
	v_add_f32_e32 v64, v16, v17
	s_waitcnt vmcnt(0)
	v_mov_b32_e32 v67, v6
	v_mov_b32_e32 v63, v8
	v_mov_b32_e32 v65, v9
	v_add_f32_e32 v66, 0, v60
	v_mov_b32_e32 v45, v7
	v_pk_add_f32 v[58:59], v[62:63], v[64:65]
	v_pk_add_f32 v[44:45], v[66:67], v[44:45]
	ds_bpermute_b32 v55, v1, v46
	v_pk_add_f32 v[44:45], v[44:45], v[58:59]
	s_waitcnt lgkmcnt(0)
	v_add_f32_e32 v46, v46, v55
	v_add_f32_e32 v44, v44, v45
	ds_bpermute_b32 v45, v1, v44
	ds_bpermute_b32 v55, v47, v46
	s_waitcnt lgkmcnt(1)
	v_add_f32_e32 v44, v44, v45
	ds_bpermute_b32 v45, v47, v44
	s_waitcnt lgkmcnt(1)
	v_add_f32_e32 v46, v46, v55
	ds_bpermute_b32 v55, v48, v46
	s_waitcnt lgkmcnt(1)
	v_add_f32_e32 v44, v44, v45
	ds_bpermute_b32 v45, v48, v44
	s_waitcnt lgkmcnt(1)
	v_add_f32_e32 v46, v46, v55
	ds_bpermute_b32 v55, v49, v46
	s_waitcnt lgkmcnt(1)
	v_add_f32_e32 v44, v44, v45
	ds_bpermute_b32 v45, v49, v44
	s_waitcnt lgkmcnt(1)
	v_add_f32_e32 v46, v46, v55
	ds_bpermute_b32 v55, v50, v46
	s_waitcnt lgkmcnt(1)
	v_add_f32_e32 v44, v44, v45
	ds_bpermute_b32 v45, v50, v44
	s_waitcnt lgkmcnt(1)
	v_add_f32_e32 v46, v46, v55
	ds_bpermute_b32 v55, v51, v46
	s_waitcnt lgkmcnt(1)
	v_add_f32_e32 v44, v44, v45
	ds_bpermute_b32 v56, v51, v44
	s_waitcnt lgkmcnt(1)
	v_add_f32_e32 v55, v46, v55
	v_fmamk_f32 v29, v55, 0xba800000, v29
	v_fmamk_f32 v27, v55, 0xba800000, v27
	v_fmamk_f32 v28, v55, 0xba800000, v28
	v_fmac_f32_e32 v26, 0xba800000, v55
	v_mul_f32_e32 v45, v27, v27
	v_mul_f32_e32 v46, v29, v29
	s_waitcnt lgkmcnt(0)
	v_add_f32_e32 v56, v44, v56
	v_fmac_f32_e32 v45, v26, v26
	v_fmac_f32_e32 v46, v28, v28
	v_fmamk_f32 v44, v56, 0xba800000, v32
	v_fmamk_f32 v31, v56, 0xba800000, v31
	v_fmamk_f32 v24, v56, 0xba800000, v24
	v_fmamk_f32 v23, v56, 0xba800000, v23
	v_add_f32_e32 v46, v45, v46
	v_fmamk_f32 v45, v56, 0xba800000, v33
	v_fmac_f32_e32 v30, 0xba800000, v56
	v_fmamk_f32 v25, v56, 0xba800000, v25
	v_fmac_f32_e32 v22, 0xba800000, v56
	v_fmamk_f32 v16, v56, 0xba800000, v16
	v_fmamk_f32 v15, v56, 0xba800000, v15
	v_mul_f32_e32 v32, v31, v31
	v_mul_f32_e32 v33, v44, v44
	v_mul_f32_e32 v58, v23, v23
	v_mul_f32_e32 v59, v24, v24
	v_fmamk_f32 v17, v56, 0xba800000, v17
	v_fmac_f32_e32 v14, 0xba800000, v56
	v_mul_f32_e32 v60, v15, v15
	v_mul_f32_e32 v61, v16, v16
	v_fmac_f32_e32 v32, v30, v30
	v_fmac_f32_e32 v33, v45, v45
	v_fmac_f32_e32 v58, v22, v22
	v_fmac_f32_e32 v59, v25, v25
	v_fmac_f32_e32 v60, v14, v14
	v_fmac_f32_e32 v61, v17, v17
	v_add_f32_e32 v32, v32, v33
	v_add_f32_e32 v33, v58, v59
	v_fmamk_f32 v8, v56, 0xba800000, v8
	v_fmamk_f32 v7, v56, 0xba800000, v7
	v_add_f32_e32 v58, v60, v61
	v_add_f32_e32 v32, v32, v33
	v_fmamk_f32 v9, v56, 0xba800000, v9
	v_add_f32_e32 v32, v58, v32
	v_fmac_f32_e32 v6, 0xba800000, v56
	v_mul_f32_e32 v33, v7, v7
	v_mul_f32_e32 v58, v8, v8
	v_fmac_f32_e32 v33, v6, v6
	v_fmac_f32_e32 v58, v9, v9
	v_add_f32_e32 v33, v33, v58
	v_add_f32_e32 v32, v33, v32
	ds_bpermute_b32 v33, v1, v32
	v_fmamk_f32 v21, v55, 0xba800000, v21
	v_fmamk_f32 v19, v55, 0xba800000, v19
	v_fmamk_f32 v20, v55, 0xba800000, v20
	v_fmac_f32_e32 v18, 0xba800000, v55
	s_waitcnt lgkmcnt(0)
	v_add_f32_e32 v32, v32, v33
	ds_bpermute_b32 v33, v47, v32
	v_mul_f32_e32 v57, v19, v19
	v_mul_f32_e32 v58, v21, v21
	v_fmac_f32_e32 v57, v18, v18
	v_fmac_f32_e32 v58, v20, v20
	v_add_f32_e32 v57, v57, v58
	v_fmamk_f32 v13, v55, 0xba800000, v13
	v_fmamk_f32 v11, v55, 0xba800000, v11
	s_waitcnt lgkmcnt(0)
	v_add_f32_e32 v32, v32, v33
	v_add_f32_e32 v46, v46, v57
	v_fmamk_f32 v12, v55, 0xba800000, v12
	v_fmac_f32_e32 v10, 0xba800000, v55
	ds_bpermute_b32 v33, v48, v32
	v_mul_f32_e32 v57, v11, v11
	v_mul_f32_e32 v58, v13, v13
	v_fmac_f32_e32 v57, v10, v10
	v_fmac_f32_e32 v58, v12, v12
	v_add_f32_e32 v57, v57, v58
	v_fmamk_f32 v5, v55, 0xba800000, v5
	v_fmamk_f32 v3, v55, 0xba800000, v3
	v_add_f32_e32 v46, v57, v46
	v_fmamk_f32 v4, v55, 0xba800000, v4
	v_fmac_f32_e32 v2, 0xba800000, v55
	v_mul_f32_e32 v57, v3, v3
	v_mul_f32_e32 v58, v5, v5
	v_fmac_f32_e32 v57, v2, v2
	v_fmac_f32_e32 v58, v4, v4
	s_waitcnt lgkmcnt(0)
	v_add_f32_e32 v32, v32, v33
	v_add_f32_e32 v57, v57, v58
	ds_bpermute_b32 v33, v49, v32
	v_add_f32_e32 v46, v57, v46
	ds_bpermute_b32 v57, v1, v46
	s_waitcnt lgkmcnt(1)
	v_add_f32_e32 v32, v32, v33
	ds_bpermute_b32 v33, v50, v32
	s_waitcnt lgkmcnt(1)
	v_add_f32_e32 v46, v46, v57
	ds_bpermute_b32 v57, v47, v46
	s_waitcnt lgkmcnt(1)
	v_add_f32_e32 v32, v32, v33
	ds_bpermute_b32 v33, v51, v32
	s_waitcnt lgkmcnt(1)
	v_add_f32_e32 v46, v46, v57
	ds_bpermute_b32 v57, v48, v46
	s_waitcnt lgkmcnt(1)
	v_add_f32_e32 v32, v32, v33
	v_fmamk_f32 v32, v32, 0x3a800000, v52
	s_waitcnt lgkmcnt(0)
	v_add_f32_e32 v46, v46, v57
	v_mul_f32_e32 v33, 0x4f800000, v32
	v_cmp_gt_f32_e32 vcc, s34, v32
	ds_bpermute_b32 v57, v49, v46
	s_waitcnt lgkmcnt(0)
	v_add_f32_e32 v46, v46, v57
	v_cndmask_b32_e32 v32, v32, v33, vcc
	v_sqrt_f32_e32 v33, v32
	ds_bpermute_b32 v57, v50, v46
	v_add_u32_e32 v58, -1, v33
	v_fma_f32 v59, -v58, v33, v32
	v_cmp_ge_f32_e64 s[4:5], 0, v59
	v_add_u32_e32 v59, 1, v33
	s_waitcnt lgkmcnt(0)
	v_add_f32_e32 v46, v46, v57
	v_cndmask_b32_e64 v58, v33, v58, s[4:5]
	v_fma_f32 v33, -v59, v33, v32
	v_cmp_lt_f32_e64 s[4:5], 0, v33
	ds_bpermute_b32 v57, v51, v46
	s_waitcnt lgkmcnt(0)
	v_add_f32_e32 v46, v46, v57
	v_cndmask_b32_e64 v33, v58, v59, s[4:5]
	v_mul_f32_e32 v58, 0x37800000, v33
	v_cndmask_b32_e32 v33, v33, v58, vcc
	v_cmp_class_f32_e32 vcc, v32, v53
	v_fmamk_f32 v46, v46, 0x3a800000, v52
	v_mul_f32_e32 v57, 0x4f800000, v46
	v_cndmask_b32_e32 v32, v33, v32, vcc
	v_div_scale_f32 v33, s[4:5], v32, v32, 1.0
	v_rcp_f32_e32 v58, v33
	v_cmp_gt_f32_e64 s[4:5], s34, v46
	v_fma_f32 v59, -v33, v58, 1.0
	s_nop 0
	v_cndmask_b32_e64 v46, v46, v57, s[4:5]
	v_fmac_f32_e32 v58, v59, v58
	v_div_scale_f32 v59, vcc, 1.0, v32, 1.0
	v_sqrt_f32_e32 v57, v46
	v_mul_f32_e32 v60, v59, v58
	v_fma_f32 v61, -v33, v60, v59
	v_fmac_f32_e32 v60, v61, v58
	v_fma_f32 v33, -v33, v60, v59
	v_add_u32_e32 v59, -1, v57
	v_fma_f32 v61, -v59, v57, v46
	v_cmp_ge_f32_e64 s[6:7], 0, v61
	v_add_u32_e32 v61, 1, v57
	v_div_fmas_f32 v33, v33, v58, v60
	v_cndmask_b32_e64 v59, v57, v59, s[6:7]
	v_fma_f32 v57, -v61, v57, v46
	v_cmp_lt_f32_e64 s[6:7], 0, v57
	v_div_fixup_f32 v32, v33, v32, 1.0
	s_nop 0
	v_cndmask_b32_e64 v57, v59, v61, s[6:7]
	v_mul_f32_e32 v59, 0x37800000, v57
	v_cndmask_b32_e64 v57, v57, v59, s[4:5]
	v_cmp_class_f32_e64 s[4:5], v46, v53
	s_nop 1
	v_cndmask_b32_e64 v46, v57, v46, s[4:5]
	v_div_scale_f32 v57, s[4:5], v46, v46, 1.0
	v_rcp_f32_e32 v59, v57
	s_nop 0
	v_fma_f32 v33, -v57, v59, 1.0
	v_fmac_f32_e32 v59, v33, v59
	v_div_scale_f32 v33, vcc, 1.0, v46, 1.0
	v_mul_f32_e32 v58, v33, v59
	v_fma_f32 v60, -v57, v58, v33
	v_fmac_f32_e32 v58, v60, v59
	v_fma_f32 v33, -v57, v58, v33
	v_div_fmas_f32 v33, v33, v59, v58
	v_div_fixup_f32 v46, v33, v46, 1.0
	s_and_saveexec_b64 s[4:5], s[18:19]
	s_cbranch_execz .LBB0_72
	s_ashr_i32 s29, s28, 31
	s_lshl_b64 s[6:7], s[28:29], 2
	s_add_u32 s6, s94, s6
	s_addc_u32 s7, s95, s7
	s_lshl_b32 s38, s30, 1
	s_ashr_i32 s39, s38, 31
	s_lshl_b64 s[38:39], s[38:39], 2
	s_add_u32 s38, s94, s38
	v_mul_f32_e32 v56, 0x3a800000, v56
	v_mul_f32_e32 v58, 0x3a800000, v55
	s_addc_u32 s39, s95, s39
	v_mov_b32_e32 v57, v32
	v_mov_b32_e32 v59, v46
	global_store_dwordx2 v54, v[56:57], s[6:7]
	global_store_dwordx2 v54, v[58:59], s[38:39]
	s_branch .LBB0_72

.LBB0_989:
	s_lshl_b32 s20, s11, 5
	s_lshl_b32 s29, s28, 8
	s_or_b32 s20, s29, s20
	v_or_b32_e32 v128, s20, v182
	s_lshl_b32 s20, s10, 8
	s_add_i32 s29, s20, s75
	v_or_b32_e32 v130, s29, v161
	v_ashrrev_i32_e32 v131, 31, v130
	v_lshlrev_b64 v[132:133], 11, v[130:131]
	v_ashrrev_i32_e32 v129, 31, v128
	v_lshl_add_u64 v[132:133], s[18:19], 0, v[132:133]
	v_lshlrev_b64 v[178:179], 1, v[128:129]
	v_lshl_add_u64 v[136:137], v[132:133], 0, v[178:179]
	s_barrier
	v_lshlrev_b32_e32 v241, 11, v130
	v_add_u32_e32 v241, v241, v178
	global_load_dwordx4 v[208:211], v241, s[18:19] nt
	global_load_dwordx4 v[212:215], v241, s[18:19] offset:256 nt
	v_add_u32_e32 v242, 0x8000, v241
	global_load_dwordx4 v[216:219], v242, s[18:19] nt
	global_load_dwordx4 v[220:223], v242, s[18:19] offset:256 nt
	v_add_u32_e32 v242, 0x10000, v241
	global_load_dwordx4 v[224:227], v242, s[18:19] nt
	global_load_dwordx4 v[228:231], v242, s[18:19] offset:256 nt
	v_add_u32_e32 v242, 0x18000, v241
	global_load_dwordx4 v[232:235], v242, s[18:19] nt
	global_load_dwordx4 v[236:239], v242, s[18:19] offset:256 nt
	s_nop 0
	v_or_b32_e32 v140, 16, v130
	v_ashrrev_i32_e32 v141, 31, v140
	v_lshlrev_b64 v[140:141], 11, v[140:141]
	v_lshl_add_u64 v[140:141], s[18:19], 0, v[140:141]
	v_lshl_add_u64 v[140:141], v[140:141], 0, v[178:179]
	v_xor_b32_e32 v131, 16, v192
	s_lshl_b32 s11, s11, 3
	s_add_i32 s11, s11, 0
	s_waitcnt vmcnt(6)
	v_mov_b32_e32 v132, v208
	v_mov_b32_e32 v133, v209
	v_mov_b32_e32 v134, v210
	v_mov_b32_e32 v135, v211
	v_mov_b32_e32 v136, v212
	v_mov_b32_e32 v137, v213
	v_mov_b32_e32 v138, v214
	v_mov_b32_e32 v139, v215
	v_add_u32_e32 v242, 0x40000, v241
	global_load_dwordx4 v[208:211], v242, s[18:19] nt
	global_load_dwordx4 v[212:215], v242, s[18:19] offset:256 nt
	v_lshlrev_b32_e32 v142, 16, v132
	v_and_b32_e32 v143, 0xffff0000, v132
	v_lshlrev_b32_e32 v132, 16, v133
	v_and_b32_e32 v133, 0xffff0000, v133
	v_lshlrev_b32_e32 v144, 16, v134
	v_and_b32_e32 v145, 0xffff0000, v134
	v_lshlrev_b32_e32 v134, 16, v135
	v_and_b32_e32 v135, 0xffff0000, v135
	v_lshlrev_b32_e32 v146, 16, v136
	v_and_b32_e32 v147, 0xffff0000, v136
	v_lshlrev_b32_e32 v136, 16, v137
	v_and_b32_e32 v137, 0xffff0000, v137
	v_lshlrev_b32_e32 v148, 16, v138
	v_and_b32_e32 v149, 0xffff0000, v138
	v_lshlrev_b32_e32 v138, 16, v139
	v_and_b32_e32 v139, 0xffff0000, v139
	v_pk_fma_f32 v[102:103], v[132:133], s[26:27], v[102:103] op_sel_hi:[1,0,1]
	v_pk_fma_f32 v[100:101], v[142:143], s[26:27], v[100:101] op_sel_hi:[1,0,1]
	v_pk_fma_f32 v[98:99], v[134:135], s[26:27], v[98:99] op_sel_hi:[1,0,1]
	v_pk_fma_f32 v[96:97], v[144:145], s[26:27], v[96:97] op_sel_hi:[1,0,1]
	v_pk_fma_f32 v[90:91], v[136:137], s[26:27], v[90:91] op_sel_hi:[1,0,1]
	v_pk_fma_f32 v[88:89], v[146:147], s[26:27], v[88:89] op_sel_hi:[1,0,1]
	v_pk_fma_f32 v[82:83], v[138:139], s[26:27], v[82:83] op_sel_hi:[1,0,1]
	v_pk_fma_f32 v[80:81], v[148:149], s[26:27], v[80:81] op_sel_hi:[1,0,1]
	s_nop 0
	v_or_b32_e32 v140, 32, v130
	v_ashrrev_i32_e32 v141, 31, v140
	v_lshlrev_b64 v[140:141], 11, v[140:141]
	v_lshl_add_u64 v[140:141], s[18:19], 0, v[140:141]
	v_lshl_add_u64 v[140:141], v[140:141], 0, v[178:179]
	s_waitcnt vmcnt(7)
	v_mov_b32_e32 v132, v216
	v_mov_b32_e32 v133, v217
	v_mov_b32_e32 v134, v218
	v_mov_b32_e32 v135, v219
	v_lshlrev_b32_e32 v142, 16, v132
	v_and_b32_e32 v143, 0xffff0000, v132
	v_lshlrev_b32_e32 v132, 16, v133
	v_and_b32_e32 v133, 0xffff0000, v133
	v_lshlrev_b32_e32 v144, 16, v134
	v_and_b32_e32 v145, 0xffff0000, v134
	v_lshlrev_b32_e32 v134, 16, v135
	v_and_b32_e32 v135, 0xffff0000, v135
	s_waitcnt vmcnt(6)
	v_mov_b32_e32 v136, v220
	v_mov_b32_e32 v137, v221
	v_mov_b32_e32 v138, v222
	v_mov_b32_e32 v139, v223
	v_add_u32_e32 v242, 0x48000, v241
	global_load_dwordx4 v[216:219], v242, s[18:19] nt
	global_load_dwordx4 v[220:223], v242, s[18:19] offset:256 nt
	v_lshlrev_b32_e32 v146, 16, v136
	v_and_b32_e32 v147, 0xffff0000, v136
	v_lshlrev_b32_e32 v136, 16, v137
	v_and_b32_e32 v137, 0xffff0000, v137
	v_lshlrev_b32_e32 v148, 16, v138
	v_and_b32_e32 v149, 0xffff0000, v138
	v_lshlrev_b32_e32 v138, 16, v139
	v_and_b32_e32 v139, 0xffff0000, v139
	v_pk_fma_f32 v[110:111], v[132:133], s[26:27], v[110:111] op_sel_hi:[1,0,1]
	v_pk_fma_f32 v[108:109], v[142:143], s[26:27], v[108:109] op_sel_hi:[1,0,1]
	v_pk_fma_f32 v[106:107], v[134:135], s[26:27], v[106:107] op_sel_hi:[1,0,1]
	v_pk_fma_f32 v[104:105], v[144:145], s[26:27], v[104:105] op_sel_hi:[1,0,1]
	v_pk_fma_f32 v[78:79], v[136:137], s[26:27], v[78:79] op_sel_hi:[1,0,1]
	v_pk_fma_f32 v[76:77], v[146:147], s[26:27], v[76:77] op_sel_hi:[1,0,1]
	v_pk_fma_f32 v[70:71], v[138:139], s[26:27], v[70:71] op_sel_hi:[1,0,1]
	v_pk_fma_f32 v[68:69], v[148:149], s[26:27], v[68:69] op_sel_hi:[1,0,1]
	s_nop 0
	v_or_b32_e32 v140, 48, v130
	v_ashrrev_i32_e32 v141, 31, v140
	v_lshlrev_b64 v[140:141], 11, v[140:141]
	v_lshl_add_u64 v[140:141], s[18:19], 0, v[140:141]
	v_lshl_add_u64 v[140:141], v[140:141], 0, v[178:179]
	s_waitcnt vmcnt(7)
	v_mov_b32_e32 v132, v224
	v_mov_b32_e32 v133, v225
	v_mov_b32_e32 v134, v226
	v_mov_b32_e32 v135, v227
	v_lshlrev_b32_e32 v142, 16, v132
	v_and_b32_e32 v143, 0xffff0000, v132
	v_lshlrev_b32_e32 v132, 16, v133
	v_and_b32_e32 v133, 0xffff0000, v133
	v_lshlrev_b32_e32 v144, 16, v134
	v_and_b32_e32 v145, 0xffff0000, v134
	v_lshlrev_b32_e32 v134, 16, v135
	v_and_b32_e32 v135, 0xffff0000, v135
	s_waitcnt vmcnt(6)
	v_mov_b32_e32 v136, v228
	v_mov_b32_e32 v137, v229
	v_mov_b32_e32 v138, v230
	v_mov_b32_e32 v139, v231
	v_add_u32_e32 v242, 0x50000, v241
	global_load_dwordx4 v[224:227], v242, s[18:19] nt
	global_load_dwordx4 v[228:231], v242, s[18:19] offset:256 nt
	v_lshlrev_b32_e32 v146, 16, v136
	v_and_b32_e32 v147, 0xffff0000, v136
	v_lshlrev_b32_e32 v136, 16, v137
	v_and_b32_e32 v137, 0xffff0000, v137
	v_lshlrev_b32_e32 v148, 16, v138
	v_and_b32_e32 v149, 0xffff0000, v138
	v_lshlrev_b32_e32 v138, 16, v139
	v_and_b32_e32 v139, 0xffff0000, v139
	v_pk_fma_f32 v[122:123], v[132:133], s[26:27], v[122:123] op_sel_hi:[1,0,1]
	v_pk_fma_f32 v[120:121], v[142:143], s[26:27], v[120:121] op_sel_hi:[1,0,1]
	v_pk_fma_f32 v[114:115], v[134:135], s[26:27], v[114:115] op_sel_hi:[1,0,1]
	v_pk_fma_f32 v[112:113], v[144:145], s[26:27], v[112:113] op_sel_hi:[1,0,1]
	v_pk_fma_f32 v[94:95], v[136:137], s[26:27], v[94:95] op_sel_hi:[1,0,1]
	v_pk_fma_f32 v[92:93], v[146:147], s[26:27], v[92:93] op_sel_hi:[1,0,1]
	v_pk_fma_f32 v[86:87], v[138:139], s[26:27], v[86:87] op_sel_hi:[1,0,1]
	v_pk_fma_f32 v[84:85], v[148:149], s[26:27], v[84:85] op_sel_hi:[1,0,1]
	s_nop 0
	v_add_u32_e32 v140, 0x80, v130
	v_ashrrev_i32_e32 v141, 31, v140
	v_lshlrev_b64 v[140:141], 11, v[140:141]
	v_lshl_add_u64 v[140:141], s[18:19], 0, v[140:141]
	v_lshl_add_u64 v[140:141], v[140:141], 0, v[178:179]
	s_waitcnt vmcnt(7)
	v_mov_b32_e32 v132, v232
	v_mov_b32_e32 v133, v233
	v_mov_b32_e32 v134, v234
	v_mov_b32_e32 v135, v235
	v_lshlrev_b32_e32 v142, 16, v132
	v_and_b32_e32 v143, 0xffff0000, v132
	v_lshlrev_b32_e32 v132, 16, v133
	v_and_b32_e32 v133, 0xffff0000, v133
	v_lshlrev_b32_e32 v144, 16, v134
	v_and_b32_e32 v145, 0xffff0000, v134
	v_lshlrev_b32_e32 v134, 16, v135
	v_and_b32_e32 v135, 0xffff0000, v135
	s_waitcnt vmcnt(6)
	v_mov_b32_e32 v136, v236
	v_mov_b32_e32 v137, v237
	v_mov_b32_e32 v138, v238
	v_mov_b32_e32 v139, v239
	v_add_u32_e32 v242, 0x58000, v241
	global_load_dwordx4 v[232:235], v242, s[18:19] nt
	global_load_dwordx4 v[236:239], v242, s[18:19] offset:256 nt
	v_lshlrev_b32_e32 v146, 16, v136
	v_and_b32_e32 v147, 0xffff0000, v136
	v_lshlrev_b32_e32 v136, 16, v137
	v_and_b32_e32 v137, 0xffff0000, v137
	v_lshlrev_b32_e32 v148, 16, v138
	v_and_b32_e32 v149, 0xffff0000, v138
	v_lshlrev_b32_e32 v138, 16, v139
	v_and_b32_e32 v139, 0xffff0000, v139
	v_pk_fma_f32 v[126:127], v[132:133], s[26:27], v[126:127] op_sel_hi:[1,0,1]
	v_pk_fma_f32 v[124:125], v[142:143], s[26:27], v[124:125] op_sel_hi:[1,0,1]
	v_pk_fma_f32 v[118:119], v[134:135], s[26:27], v[118:119] op_sel_hi:[1,0,1]
	v_pk_fma_f32 v[116:117], v[144:145], s[26:27], v[116:117] op_sel_hi:[1,0,1]
	v_pk_fma_f32 v[74:75], v[136:137], s[26:27], v[74:75] op_sel_hi:[1,0,1]
	v_pk_fma_f32 v[72:73], v[146:147], s[26:27], v[72:73] op_sel_hi:[1,0,1]
	v_pk_fma_f32 v[66:67], v[138:139], s[26:27], v[66:67] op_sel_hi:[1,0,1]
	v_pk_fma_f32 v[64:65], v[148:149], s[26:27], v[64:65] op_sel_hi:[1,0,1]
	s_nop 0
	v_add_u32_e32 v140, 0x90, v130
	v_ashrrev_i32_e32 v141, 31, v140
	v_lshlrev_b64 v[140:141], 11, v[140:141]
	v_lshl_add_u64 v[140:141], s[18:19], 0, v[140:141]
	v_lshl_add_u64 v[140:141], v[140:141], 0, v[178:179]
	s_waitcnt vmcnt(7)
	v_mov_b32_e32 v132, v208
	v_mov_b32_e32 v133, v209
	v_mov_b32_e32 v134, v210
	v_mov_b32_e32 v135, v211
	v_lshlrev_b32_e32 v142, 16, v132
	v_and_b32_e32 v143, 0xffff0000, v132
	v_lshlrev_b32_e32 v132, 16, v133
	v_and_b32_e32 v133, 0xffff0000, v133
	v_lshlrev_b32_e32 v144, 16, v134
	v_and_b32_e32 v145, 0xffff0000, v134
	v_lshlrev_b32_e32 v134, 16, v135
	v_and_b32_e32 v135, 0xffff0000, v135
	s_waitcnt vmcnt(6)
	v_mov_b32_e32 v136, v212
	v_mov_b32_e32 v137, v213
	v_mov_b32_e32 v138, v214
	v_mov_b32_e32 v139, v215
	v_lshlrev_b32_e32 v146, 16, v136
	v_and_b32_e32 v147, 0xffff0000, v136
	v_lshlrev_b32_e32 v136, 16, v137
	v_and_b32_e32 v137, 0xffff0000, v137
	v_lshlrev_b32_e32 v148, 16, v138
	v_and_b32_e32 v149, 0xffff0000, v138
	v_lshlrev_b32_e32 v138, 16, v139
	v_and_b32_e32 v139, 0xffff0000, v139
	v_pk_fma_f32 v[62:63], v[132:133], s[26:27], v[62:63] op_sel_hi:[1,0,1]
	v_pk_fma_f32 v[60:61], v[142:143], s[26:27], v[60:61] op_sel_hi:[1,0,1]
	v_pk_fma_f32 v[58:59], v[134:135], s[26:27], v[58:59] op_sel_hi:[1,0,1]
	v_pk_fma_f32 v[56:57], v[144:145], s[26:27], v[56:57] op_sel_hi:[1,0,1]
	v_pk_fma_f32 v[54:55], v[136:137], s[26:27], v[54:55] op_sel_hi:[1,0,1]
	v_pk_fma_f32 v[52:53], v[146:147], s[26:27], v[52:53] op_sel_hi:[1,0,1]
	v_pk_fma_f32 v[50:51], v[138:139], s[26:27], v[50:51] op_sel_hi:[1,0,1]
	v_pk_fma_f32 v[48:49], v[148:149], s[26:27], v[48:49] op_sel_hi:[1,0,1]
	s_nop 0
	v_add_u32_e32 v140, 0xa0, v130
	v_ashrrev_i32_e32 v141, 31, v140
	v_lshlrev_b64 v[140:141], 11, v[140:141]
	v_lshl_add_u64 v[140:141], s[18:19], 0, v[140:141]
	v_lshl_add_u64 v[140:141], v[140:141], 0, v[178:179]
	s_waitcnt vmcnt(5)
	v_mov_b32_e32 v132, v216
	v_mov_b32_e32 v133, v217
	v_mov_b32_e32 v134, v218
	v_mov_b32_e32 v135, v219
	v_lshlrev_b32_e32 v142, 16, v132
	v_and_b32_e32 v143, 0xffff0000, v132
	v_lshlrev_b32_e32 v132, 16, v133
	v_and_b32_e32 v133, 0xffff0000, v133
	v_lshlrev_b32_e32 v144, 16, v134
	v_and_b32_e32 v145, 0xffff0000, v134
	v_lshlrev_b32_e32 v134, 16, v135
	v_and_b32_e32 v135, 0xffff0000, v135
	s_waitcnt vmcnt(4)
	v_mov_b32_e32 v136, v220
	v_mov_b32_e32 v137, v221
	v_mov_b32_e32 v138, v222
	v_mov_b32_e32 v139, v223
	v_lshlrev_b32_e32 v146, 16, v136
	v_and_b32_e32 v147, 0xffff0000, v136
	v_lshlrev_b32_e32 v136, 16, v137
	v_and_b32_e32 v137, 0xffff0000, v137
	v_lshlrev_b32_e32 v148, 16, v138
	v_and_b32_e32 v149, 0xffff0000, v138
	v_lshlrev_b32_e32 v138, 16, v139
	v_and_b32_e32 v139, 0xffff0000, v139
	v_pk_fma_f32 v[46:47], v[132:133], s[26:27], v[46:47] op_sel_hi:[1,0,1]
	v_pk_fma_f32 v[44:45], v[142:143], s[26:27], v[44:45] op_sel_hi:[1,0,1]
	v_pk_fma_f32 v[42:43], v[134:135], s[26:27], v[42:43] op_sel_hi:[1,0,1]
	v_pk_fma_f32 v[40:41], v[144:145], s[26:27], v[40:41] op_sel_hi:[1,0,1]
	v_pk_fma_f32 v[38:39], v[136:137], s[26:27], v[38:39] op_sel_hi:[1,0,1]
	v_pk_fma_f32 v[36:37], v[146:147], s[26:27], v[36:37] op_sel_hi:[1,0,1]
	v_pk_fma_f32 v[34:35], v[138:139], s[26:27], v[34:35] op_sel_hi:[1,0,1]
	v_pk_fma_f32 v[32:33], v[148:149], s[26:27], v[32:33] op_sel_hi:[1,0,1]
	v_mov_b32_e32 v144, v101
	v_and_b32_e32 v140, 64, v192
	v_add_u32_e32 v154, 64, v140
	v_add_u32_e32 v140, 0xb0, v130
	v_ashrrev_i32_e32 v141, 31, v140
	v_lshlrev_b64 v[140:141], 11, v[140:141]
	v_lshl_add_u64 v[140:141], s[18:19], 0, v[140:141]
	v_lshl_add_u64 v[140:141], v[140:141], 0, v[178:179]
	v_cmp_lt_i32_e32 vcc, v131, v154
	v_mov_b32_e32 v145, v102
	v_mov_b32_e32 v146, v100
	v_mov_b32_e32 v147, v103
	v_cndmask_b32_e32 v131, v192, v131, vcc
	v_pk_add_f32 v[144:145], v[144:145], v[146:147]
	v_lshlrev_b32_e32 v130, 2, v131
	v_add_f32_e32 v131, v144, v145
	s_waitcnt vmcnt(3)
	v_mov_b32_e32 v132, v224
	v_mov_b32_e32 v133, v225
	v_mov_b32_e32 v134, v226
	v_mov_b32_e32 v135, v227
	v_lshlrev_b32_e32 v142, 16, v132
	v_and_b32_e32 v143, 0xffff0000, v132
	v_lshlrev_b32_e32 v132, 16, v133
	v_and_b32_e32 v133, 0xffff0000, v133
	v_lshlrev_b32_e32 v148, 16, v134
	v_and_b32_e32 v149, 0xffff0000, v134
	v_lshlrev_b32_e32 v134, 16, v135
	v_and_b32_e32 v135, 0xffff0000, v135
	s_waitcnt vmcnt(2)
	v_mov_b32_e32 v136, v228
	v_mov_b32_e32 v137, v229
	v_mov_b32_e32 v138, v230
	v_mov_b32_e32 v139, v231
	v_lshlrev_b32_e32 v150, 16, v136
	v_and_b32_e32 v151, 0xffff0000, v136
	v_lshlrev_b32_e32 v136, 16, v137
	v_and_b32_e32 v137, 0xffff0000, v137
	v_lshlrev_b32_e32 v152, 16, v138
	v_and_b32_e32 v153, 0xffff0000, v138
	v_lshlrev_b32_e32 v138, 16, v139
	v_and_b32_e32 v139, 0xffff0000, v139
	v_pk_fma_f32 v[30:31], v[132:133], s[26:27], v[30:31] op_sel_hi:[1,0,1]
	v_pk_fma_f32 v[28:29], v[142:143], s[26:27], v[28:29] op_sel_hi:[1,0,1]
	v_pk_fma_f32 v[26:27], v[134:135], s[26:27], v[26:27] op_sel_hi:[1,0,1]
	v_pk_fma_f32 v[24:25], v[148:149], s[26:27], v[24:25] op_sel_hi:[1,0,1]
	v_pk_fma_f32 v[22:23], v[136:137], s[26:27], v[22:23] op_sel_hi:[1,0,1]
	v_pk_fma_f32 v[20:21], v[150:151], s[26:27], v[20:21] op_sel_hi:[1,0,1]
	v_pk_fma_f32 v[18:19], v[138:139], s[26:27], v[18:19] op_sel_hi:[1,0,1]
	v_pk_fma_f32 v[16:17], v[152:153], s[26:27], v[16:17] op_sel_hi:[1,0,1]
	v_mov_b32_e32 v132, v97
	v_mov_b32_e32 v133, v98
	v_mov_b32_e32 v134, v96
	v_mov_b32_e32 v135, v99
	v_pk_add_f32 v[132:133], v[132:133], v[134:135]
	v_add_f32_e32 v149, v88, v89
	v_pk_add_f32 v[132:133], v[132:133], v[132:133] op_sel_hi:[0,1]
	v_add_f32_e32 v151, v90, v91
	v_mov_b32_e32 v148, v80
	v_mov_b32_e32 v150, v81
	v_mov_b32_e32 v152, v83
	v_add_f32_e32 v153, 0, v131
	v_mov_b32_e32 v132, v82
	v_pk_add_f32 v[134:135], v[148:149], v[150:151]
	v_pk_add_f32 v[132:133], v[132:133], v[152:153]
	v_xor_b32_e32 v131, 32, v192
	v_pk_add_f32 v[132:133], v[134:135], v[132:133]
	v_cmp_lt_i32_e32 vcc, v131, v154
	v_add_f32_e32 v132, v132, v133
	ds_bpermute_b32 v133, v130, v132
	v_cndmask_b32_e32 v131, v192, v131, vcc
	v_lshlrev_b32_e32 v131, 2, v131
	s_waitcnt lgkmcnt(0)
	v_add_f32_e32 v132, v132, v133
	ds_bpermute_b32 v133, v131, v132
	s_waitcnt lgkmcnt(0)
	v_add_f32_e32 v132, v132, v133
	v_fmamk_f32 v134, v132, 0xbc800000, v103
	v_fmamk_f32 v144, v132, 0xbc800000, v101
	v_fmamk_f32 v146, v132, 0xbc800000, v99
	v_fmamk_f32 v148, v132, 0xbc800000, v97
	v_fmamk_f32 v133, v132, 0xbc800000, v102
	v_fmamk_f32 v135, v132, 0xbc800000, v100
	v_fmamk_f32 v145, v132, 0xbc800000, v98
	v_fmamk_f32 v147, v132, 0xbc800000, v96
	v_fmamk_f32 v150, v132, 0xbc800000, v91
	v_fmamk_f32 v152, v132, 0xbc800000, v89
	v_mul_f32_e32 v144, v144, v144
	v_mul_f32_e32 v134, v134, v134
	v_mul_f32_e32 v148, v148, v148
	v_mul_f32_e32 v146, v146, v146
	v_fmamk_f32 v149, v132, 0xbc800000, v90
	v_fmamk_f32 v151, v132, 0xbc800000, v88
	v_fmamk_f32 v154, v132, 0xbc800000, v83
	v_fmamk_f32 v156, v132, 0xbc800000, v81
	v_mul_f32_e32 v152, v152, v152
	v_mul_f32_e32 v150, v150, v150
	v_fmac_f32_e32 v144, v135, v135
	v_fmac_f32_e32 v134, v133, v133
	v_fmac_f32_e32 v148, v147, v147
	v_fmac_f32_e32 v146, v145, v145
	v_fmamk_f32 v153, v132, 0xbc800000, v82
	v_fmamk_f32 v155, v132, 0xbc800000, v80
	v_mul_f32_e32 v156, v156, v156
	v_mul_f32_e32 v154, v154, v154
	v_fmac_f32_e32 v152, v151, v151
	v_fmac_f32_e32 v150, v149, v149
	v_add_f32_e32 v133, v144, v134
	v_add_f32_e32 v134, v148, v146
	v_fmac_f32_e32 v156, v155, v155
	v_fmac_f32_e32 v154, v153, v153
	v_add_f32_e32 v135, v152, v150
	v_add_f32_e32 v133, v133, v134
	v_add_f32_e32 v144, v156, v154
	v_add_f32_e32 v133, v135, v133
	v_add_f32_e32 v133, v144, v133
	ds_bpermute_b32 v134, v130, v133
	s_waitcnt lgkmcnt(0)
	v_add_f32_e32 v133, v133, v134
	ds_bpermute_b32 v134, v131, v133
	s_waitcnt vmcnt(1)
	v_mov_b32_e32 v136, v232
	v_mov_b32_e32 v137, v233
	v_mov_b32_e32 v138, v234
	v_mov_b32_e32 v139, v235
	v_lshlrev_b32_e32 v144, 16, v136
	v_and_b32_e32 v145, 0xffff0000, v136
	v_lshlrev_b32_e32 v136, 16, v137
	v_and_b32_e32 v137, 0xffff0000, v137
	v_lshlrev_b32_e32 v146, 16, v138
	v_and_b32_e32 v147, 0xffff0000, v138
	v_lshlrev_b32_e32 v138, 16, v139
	v_and_b32_e32 v139, 0xffff0000, v139
	s_waitcnt vmcnt(0)
	v_mov_b32_e32 v140, v236
	v_mov_b32_e32 v141, v237
	v_mov_b32_e32 v142, v238
	v_mov_b32_e32 v143, v239
	v_lshlrev_b32_e32 v148, 16, v140
	v_and_b32_e32 v149, 0xffff0000, v140
	v_lshlrev_b32_e32 v140, 16, v141
	v_and_b32_e32 v141, 0xffff0000, v141
	v_lshlrev_b32_e32 v150, 16, v142
	v_and_b32_e32 v151, 0xffff0000, v142
	v_lshlrev_b32_e32 v142, 16, v143
	v_and_b32_e32 v143, 0xffff0000, v143
	v_pk_fma_f32 v[14:15], v[136:137], s[26:27], v[14:15] op_sel_hi:[1,0,1]
	v_pk_fma_f32 v[12:13], v[144:145], s[26:27], v[12:13] op_sel_hi:[1,0,1]
	v_pk_fma_f32 v[10:11], v[138:139], s[26:27], v[10:11] op_sel_hi:[1,0,1]
	v_pk_fma_f32 v[8:9], v[146:147], s[26:27], v[8:9] op_sel_hi:[1,0,1]
	v_pk_fma_f32 v[6:7], v[140:141], s[26:27], v[6:7] op_sel_hi:[1,0,1]
	v_pk_fma_f32 v[4:5], v[148:149], s[26:27], v[4:5] op_sel_hi:[1,0,1]
	v_pk_fma_f32 v[2:3], v[142:143], s[26:27], v[2:3] op_sel_hi:[1,0,1]
	v_pk_fma_f32 v[0:1], v[150:151], s[26:27], v[0:1] op_sel_hi:[1,0,1]
	s_nop 0
	s_and_saveexec_b64 s[30:31], s[0:1]
	s_cbranch_execz .LBB0_991
	s_lshl_b32 s29, s66, 11
	s_add_i32 s29, s11, s29
	v_mul_f32_e32 v132, 0x3c800000, v132
	v_add_u32_e32 v135, s29, v184
	s_waitcnt lgkmcnt(0)
	v_add_f32_e32 v133, v133, v134
	ds_write_b64 v135, v[132:133]

.LBB0_1284:
	s_lshl_b32 s8, s60, 5
	s_lshl_b32 s9, s26, 8
	s_or_b32 s8, s9, s8
	s_lshl_b32 s18, s58, 8
	v_or_b32_e32 v128, s8, v180
	s_add_i32 s8, s18, s70
	v_or_b32_e32 v130, s8, v181
	v_ashrrev_i32_e32 v131, 31, v130
	v_lshlrev_b64 v[132:133], 11, v[130:131]
	v_ashrrev_i32_e32 v129, 31, v128
	v_lshl_add_u64 v[134:135], s[16:17], 0, v[132:133]
	v_lshlrev_b64 v[132:133], 1, v[128:129]
	v_lshl_add_u64 v[138:139], v[134:135], 0, v[132:133]
	s_barrier
	v_lshlrev_b32_e32 v241, 11, v130
	v_add_u32_e32 v241, v241, v132
	global_load_dwordx4 v[208:211], v241, s[16:17] nt
	global_load_dwordx4 v[212:215], v241, s[16:17] offset:256 nt
	v_add_u32_e32 v242, 0x8000, v241
	global_load_dwordx4 v[216:219], v242, s[16:17] nt
	global_load_dwordx4 v[220:223], v242, s[16:17] offset:256 nt
	v_add_u32_e32 v242, 0x10000, v241
	global_load_dwordx4 v[224:227], v242, s[16:17] nt
	global_load_dwordx4 v[228:231], v242, s[16:17] offset:256 nt
	v_add_u32_e32 v242, 0x18000, v241
	global_load_dwordx4 v[232:235], v242, s[16:17] nt
	global_load_dwordx4 v[236:239], v242, s[16:17] offset:256 nt
	s_nop 0
	v_or_b32_e32 v142, 16, v130
	v_ashrrev_i32_e32 v143, 31, v142
	v_lshlrev_b64 v[142:143], 11, v[142:143]
	v_lshl_add_u64 v[142:143], s[16:17], 0, v[142:143]
	v_lshl_add_u64 v[142:143], v[142:143], 0, v[132:133]
	v_xor_b32_e32 v131, 16, v191
	s_lshl_b32 s8, s60, 3
	s_add_i32 s28, s8, 0
	s_waitcnt vmcnt(6)
	v_mov_b32_e32 v134, v208
	v_mov_b32_e32 v135, v209
	v_mov_b32_e32 v136, v210
	v_mov_b32_e32 v137, v211
	v_mov_b32_e32 v138, v212
	v_mov_b32_e32 v139, v213
	v_mov_b32_e32 v140, v214
	v_mov_b32_e32 v141, v215
	v_add_u32_e32 v242, 0x40000, v241
	global_load_dwordx4 v[208:211], v242, s[16:17] nt
	global_load_dwordx4 v[212:215], v242, s[16:17] offset:256 nt
	v_lshlrev_b32_e32 v144, 16, v134
	v_and_b32_e32 v145, 0xffff0000, v134
	v_lshlrev_b32_e32 v134, 16, v135
	v_and_b32_e32 v135, 0xffff0000, v135
	v_lshlrev_b32_e32 v146, 16, v136
	v_and_b32_e32 v147, 0xffff0000, v136
	v_lshlrev_b32_e32 v136, 16, v137
	v_and_b32_e32 v137, 0xffff0000, v137
	v_lshlrev_b32_e32 v148, 16, v138
	v_and_b32_e32 v149, 0xffff0000, v138
	v_lshlrev_b32_e32 v138, 16, v139
	v_and_b32_e32 v139, 0xffff0000, v139
	v_lshlrev_b32_e32 v150, 16, v140
	v_and_b32_e32 v151, 0xffff0000, v140
	v_lshlrev_b32_e32 v140, 16, v141
	v_and_b32_e32 v141, 0xffff0000, v141
	v_pk_fma_f32 v[82:83], v[134:135], s[24:25], v[82:83] op_sel_hi:[1,0,1]
	v_pk_fma_f32 v[80:81], v[144:145], s[24:25], v[80:81] op_sel_hi:[1,0,1]
	v_pk_fma_f32 v[78:79], v[136:137], s[24:25], v[78:79] op_sel_hi:[1,0,1]
	v_pk_fma_f32 v[76:77], v[146:147], s[24:25], v[76:77] op_sel_hi:[1,0,1]
	v_pk_fma_f32 v[74:75], v[138:139], s[24:25], v[74:75] op_sel_hi:[1,0,1]
	v_pk_fma_f32 v[72:73], v[148:149], s[24:25], v[72:73] op_sel_hi:[1,0,1]
	v_pk_fma_f32 v[66:67], v[140:141], s[24:25], v[66:67] op_sel_hi:[1,0,1]
	v_pk_fma_f32 v[64:65], v[150:151], s[24:25], v[64:65] op_sel_hi:[1,0,1]
	s_nop 0
	v_or_b32_e32 v142, 32, v130
	v_ashrrev_i32_e32 v143, 31, v142
	v_lshlrev_b64 v[142:143], 11, v[142:143]
	v_lshl_add_u64 v[142:143], s[16:17], 0, v[142:143]
	v_lshl_add_u64 v[142:143], v[142:143], 0, v[132:133]
	s_waitcnt vmcnt(7)
	v_mov_b32_e32 v134, v216
	v_mov_b32_e32 v135, v217
	v_mov_b32_e32 v136, v218
	v_mov_b32_e32 v137, v219
	v_lshlrev_b32_e32 v144, 16, v134
	v_and_b32_e32 v145, 0xffff0000, v134
	v_lshlrev_b32_e32 v134, 16, v135
	v_and_b32_e32 v135, 0xffff0000, v135
	v_lshlrev_b32_e32 v146, 16, v136
	v_and_b32_e32 v147, 0xffff0000, v136
	v_lshlrev_b32_e32 v136, 16, v137
	v_and_b32_e32 v137, 0xffff0000, v137
	s_waitcnt vmcnt(6)
	v_mov_b32_e32 v138, v220
	v_mov_b32_e32 v139, v221
	v_mov_b32_e32 v140, v222
	v_mov_b32_e32 v141, v223
	v_add_u32_e32 v242, 0x48000, v241
	global_load_dwordx4 v[216:219], v242, s[16:17] nt
	global_load_dwordx4 v[220:223], v242, s[16:17] offset:256 nt
	v_lshlrev_b32_e32 v148, 16, v138
	v_and_b32_e32 v149, 0xffff0000, v138
	v_lshlrev_b32_e32 v138, 16, v139
	v_and_b32_e32 v139, 0xffff0000, v139
	v_lshlrev_b32_e32 v150, 16, v140
	v_and_b32_e32 v151, 0xffff0000, v140
	v_lshlrev_b32_e32 v140, 16, v141
	v_and_b32_e32 v141, 0xffff0000, v141
	v_pk_fma_f32 v[126:127], v[134:135], s[24:25], v[126:127] op_sel_hi:[1,0,1]
	v_pk_fma_f32 v[124:125], v[144:145], s[24:25], v[124:125] op_sel_hi:[1,0,1]
	v_pk_fma_f32 v[106:107], v[136:137], s[24:25], v[106:107] op_sel_hi:[1,0,1]
	v_pk_fma_f32 v[104:105], v[146:147], s[24:25], v[104:105] op_sel_hi:[1,0,1]
	v_pk_fma_f32 v[94:95], v[138:139], s[24:25], v[94:95] op_sel_hi:[1,0,1]
	v_pk_fma_f32 v[92:93], v[148:149], s[24:25], v[92:93] op_sel_hi:[1,0,1]
	v_pk_fma_f32 v[90:91], v[140:141], s[24:25], v[90:91] op_sel_hi:[1,0,1]
	v_pk_fma_f32 v[88:89], v[150:151], s[24:25], v[88:89] op_sel_hi:[1,0,1]
	s_nop 0
	v_or_b32_e32 v142, 48, v130
	v_ashrrev_i32_e32 v143, 31, v142
	v_lshlrev_b64 v[142:143], 11, v[142:143]
	v_lshl_add_u64 v[142:143], s[16:17], 0, v[142:143]
	v_lshl_add_u64 v[142:143], v[142:143], 0, v[132:133]
	s_waitcnt vmcnt(7)
	v_mov_b32_e32 v134, v224
	v_mov_b32_e32 v135, v225
	v_mov_b32_e32 v136, v226
	v_mov_b32_e32 v137, v227
	v_lshlrev_b32_e32 v144, 16, v134
	v_and_b32_e32 v145, 0xffff0000, v134
	v_lshlrev_b32_e32 v134, 16, v135
	v_and_b32_e32 v135, 0xffff0000, v135
	v_lshlrev_b32_e32 v146, 16, v136
	v_and_b32_e32 v147, 0xffff0000, v136
	v_lshlrev_b32_e32 v136, 16, v137
	v_and_b32_e32 v137, 0xffff0000, v137
	s_waitcnt vmcnt(6)
	v_mov_b32_e32 v138, v228
	v_mov_b32_e32 v139, v229
	v_mov_b32_e32 v140, v230
	v_mov_b32_e32 v141, v231
	v_add_u32_e32 v242, 0x50000, v241
	global_load_dwordx4 v[224:227], v242, s[16:17] nt
	global_load_dwordx4 v[228:231], v242, s[16:17] offset:256 nt
	v_lshlrev_b32_e32 v148, 16, v138
	v_and_b32_e32 v149, 0xffff0000, v138
	v_lshlrev_b32_e32 v138, 16, v139
	v_and_b32_e32 v139, 0xffff0000, v139
	v_lshlrev_b32_e32 v150, 16, v140
	v_and_b32_e32 v151, 0xffff0000, v140
	v_lshlrev_b32_e32 v140, 16, v141
	v_and_b32_e32 v141, 0xffff0000, v141
	v_pk_fma_f32 v[118:119], v[134:135], s[24:25], v[118:119] op_sel_hi:[1,0,1]
	v_pk_fma_f32 v[116:117], v[144:145], s[24:25], v[116:117] op_sel_hi:[1,0,1]
	v_pk_fma_f32 v[110:111], v[136:137], s[24:25], v[110:111] op_sel_hi:[1,0,1]
	v_pk_fma_f32 v[108:109], v[146:147], s[24:25], v[108:109] op_sel_hi:[1,0,1]
	v_pk_fma_f32 v[102:103], v[138:139], s[24:25], v[102:103] op_sel_hi:[1,0,1]
	v_pk_fma_f32 v[100:101], v[148:149], s[24:25], v[100:101] op_sel_hi:[1,0,1]
	v_pk_fma_f32 v[98:99], v[140:141], s[24:25], v[98:99] op_sel_hi:[1,0,1]
	v_pk_fma_f32 v[96:97], v[150:151], s[24:25], v[96:97] op_sel_hi:[1,0,1]
	s_nop 0
	v_add_u32_e32 v142, 0x80, v130
	v_ashrrev_i32_e32 v143, 31, v142
	v_lshlrev_b64 v[142:143], 11, v[142:143]
	v_lshl_add_u64 v[142:143], s[16:17], 0, v[142:143]
	v_lshl_add_u64 v[142:143], v[142:143], 0, v[132:133]
	s_waitcnt vmcnt(7)
	v_mov_b32_e32 v134, v232
	v_mov_b32_e32 v135, v233
	v_mov_b32_e32 v136, v234
	v_mov_b32_e32 v137, v235
	v_lshlrev_b32_e32 v144, 16, v134
	v_and_b32_e32 v145, 0xffff0000, v134
	v_lshlrev_b32_e32 v134, 16, v135
	v_and_b32_e32 v135, 0xffff0000, v135
	v_lshlrev_b32_e32 v146, 16, v136
	v_and_b32_e32 v147, 0xffff0000, v136
	v_lshlrev_b32_e32 v136, 16, v137
	v_and_b32_e32 v137, 0xffff0000, v137
	s_waitcnt vmcnt(6)
	v_mov_b32_e32 v138, v236
	v_mov_b32_e32 v139, v237
	v_mov_b32_e32 v140, v238
	v_mov_b32_e32 v141, v239
	v_add_u32_e32 v242, 0x58000, v241
	global_load_dwordx4 v[232:235], v242, s[16:17] nt
	global_load_dwordx4 v[236:239], v242, s[16:17] offset:256 nt
	v_lshlrev_b32_e32 v148, 16, v138
	v_and_b32_e32 v149, 0xffff0000, v138
	v_lshlrev_b32_e32 v138, 16, v139
	v_and_b32_e32 v139, 0xffff0000, v139
	v_lshlrev_b32_e32 v150, 16, v140
	v_and_b32_e32 v151, 0xffff0000, v140
	v_lshlrev_b32_e32 v140, 16, v141
	v_and_b32_e32 v141, 0xffff0000, v141
	v_pk_fma_f32 v[122:123], v[134:135], s[24:25], v[122:123] op_sel_hi:[1,0,1]
	v_pk_fma_f32 v[120:121], v[144:145], s[24:25], v[120:121] op_sel_hi:[1,0,1]
	v_pk_fma_f32 v[114:115], v[136:137], s[24:25], v[114:115] op_sel_hi:[1,0,1]
	v_pk_fma_f32 v[112:113], v[146:147], s[24:25], v[112:113] op_sel_hi:[1,0,1]
	v_pk_fma_f32 v[86:87], v[138:139], s[24:25], v[86:87] op_sel_hi:[1,0,1]
	v_pk_fma_f32 v[84:85], v[148:149], s[24:25], v[84:85] op_sel_hi:[1,0,1]
	v_pk_fma_f32 v[70:71], v[140:141], s[24:25], v[70:71] op_sel_hi:[1,0,1]
	v_pk_fma_f32 v[68:69], v[150:151], s[24:25], v[68:69] op_sel_hi:[1,0,1]
	s_nop 0
	v_add_u32_e32 v142, 0x90, v130
	v_ashrrev_i32_e32 v143, 31, v142
	v_lshlrev_b64 v[142:143], 11, v[142:143]
	v_lshl_add_u64 v[142:143], s[16:17], 0, v[142:143]
	v_lshl_add_u64 v[142:143], v[142:143], 0, v[132:133]
	s_waitcnt vmcnt(7)
	v_mov_b32_e32 v134, v208
	v_mov_b32_e32 v135, v209
	v_mov_b32_e32 v136, v210
	v_mov_b32_e32 v137, v211
	v_lshlrev_b32_e32 v144, 16, v134
	v_and_b32_e32 v145, 0xffff0000, v134
	v_lshlrev_b32_e32 v134, 16, v135
	v_and_b32_e32 v135, 0xffff0000, v135
	v_lshlrev_b32_e32 v146, 16, v136
	v_and_b32_e32 v147, 0xffff0000, v136
	v_lshlrev_b32_e32 v136, 16, v137
	v_and_b32_e32 v137, 0xffff0000, v137
	s_waitcnt vmcnt(6)
	v_mov_b32_e32 v138, v212
	v_mov_b32_e32 v139, v213
	v_mov_b32_e32 v140, v214
	v_mov_b32_e32 v141, v215
	v_lshlrev_b32_e32 v148, 16, v138
	v_and_b32_e32 v149, 0xffff0000, v138
	v_lshlrev_b32_e32 v138, 16, v139
	v_and_b32_e32 v139, 0xffff0000, v139
	v_lshlrev_b32_e32 v150, 16, v140
	v_and_b32_e32 v151, 0xffff0000, v140
	v_lshlrev_b32_e32 v140, 16, v141
	v_and_b32_e32 v141, 0xffff0000, v141
	v_pk_fma_f32 v[62:63], v[134:135], s[24:25], v[62:63] op_sel_hi:[1,0,1]
	v_pk_fma_f32 v[60:61], v[144:145], s[24:25], v[60:61] op_sel_hi:[1,0,1]
	v_pk_fma_f32 v[58:59], v[136:137], s[24:25], v[58:59] op_sel_hi:[1,0,1]
	v_pk_fma_f32 v[56:57], v[146:147], s[24:25], v[56:57] op_sel_hi:[1,0,1]
	v_pk_fma_f32 v[54:55], v[138:139], s[24:25], v[54:55] op_sel_hi:[1,0,1]
	v_pk_fma_f32 v[52:53], v[148:149], s[24:25], v[52:53] op_sel_hi:[1,0,1]
	v_pk_fma_f32 v[50:51], v[140:141], s[24:25], v[50:51] op_sel_hi:[1,0,1]
	v_pk_fma_f32 v[48:49], v[150:151], s[24:25], v[48:49] op_sel_hi:[1,0,1]
	s_nop 0
	v_add_u32_e32 v142, 0xa0, v130
	v_ashrrev_i32_e32 v143, 31, v142
	v_lshlrev_b64 v[142:143], 11, v[142:143]
	v_lshl_add_u64 v[142:143], s[16:17], 0, v[142:143]
	v_lshl_add_u64 v[142:143], v[142:143], 0, v[132:133]
	s_waitcnt vmcnt(5)
	v_mov_b32_e32 v134, v216
	v_mov_b32_e32 v135, v217
	v_mov_b32_e32 v136, v218
	v_mov_b32_e32 v137, v219
	v_lshlrev_b32_e32 v144, 16, v134
	v_and_b32_e32 v145, 0xffff0000, v134
	v_lshlrev_b32_e32 v134, 16, v135
	v_and_b32_e32 v135, 0xffff0000, v135
	v_lshlrev_b32_e32 v146, 16, v136
	v_and_b32_e32 v147, 0xffff0000, v136
	v_lshlrev_b32_e32 v136, 16, v137
	v_and_b32_e32 v137, 0xffff0000, v137
	s_waitcnt vmcnt(4)
	v_mov_b32_e32 v138, v220
	v_mov_b32_e32 v139, v221
	v_mov_b32_e32 v140, v222
	v_mov_b32_e32 v141, v223
	v_lshlrev_b32_e32 v148, 16, v138
	v_and_b32_e32 v149, 0xffff0000, v138
	v_lshlrev_b32_e32 v138, 16, v139
	v_and_b32_e32 v139, 0xffff0000, v139
	v_lshlrev_b32_e32 v150, 16, v140
	v_and_b32_e32 v151, 0xffff0000, v140
	v_lshlrev_b32_e32 v140, 16, v141
	v_and_b32_e32 v141, 0xffff0000, v141
	v_pk_fma_f32 v[46:47], v[134:135], s[24:25], v[46:47] op_sel_hi:[1,0,1]
	v_pk_fma_f32 v[44:45], v[144:145], s[24:25], v[44:45] op_sel_hi:[1,0,1]
	v_pk_fma_f32 v[42:43], v[136:137], s[24:25], v[42:43] op_sel_hi:[1,0,1]
	v_pk_fma_f32 v[40:41], v[146:147], s[24:25], v[40:41] op_sel_hi:[1,0,1]
	v_pk_fma_f32 v[38:39], v[138:139], s[24:25], v[38:39] op_sel_hi:[1,0,1]
	v_pk_fma_f32 v[36:37], v[148:149], s[24:25], v[36:37] op_sel_hi:[1,0,1]
	v_pk_fma_f32 v[34:35], v[140:141], s[24:25], v[34:35] op_sel_hi:[1,0,1]
	v_pk_fma_f32 v[32:33], v[150:151], s[24:25], v[32:33] op_sel_hi:[1,0,1]
	v_mov_b32_e32 v144, v81
	v_and_b32_e32 v142, 64, v191
	v_add_u32_e32 v154, 64, v142
	v_add_u32_e32 v142, 0xb0, v130
	v_ashrrev_i32_e32 v143, 31, v142
	v_lshlrev_b64 v[142:143], 11, v[142:143]
	v_lshl_add_u64 v[142:143], s[16:17], 0, v[142:143]
	v_lshl_add_u64 v[132:133], v[142:143], 0, v[132:133]
	v_cmp_lt_i32_e32 vcc, v131, v154
	v_mov_b32_e32 v145, v82
	v_mov_b32_e32 v146, v80
	v_mov_b32_e32 v147, v83
	v_cndmask_b32_e32 v131, v191, v131, vcc
	v_pk_add_f32 v[144:145], v[144:145], v[146:147]
	v_lshlrev_b32_e32 v130, 2, v131
	v_add_f32_e32 v131, v144, v145
	s_waitcnt vmcnt(3)
	v_mov_b32_e32 v134, v224
	v_mov_b32_e32 v135, v225
	v_mov_b32_e32 v136, v226
	v_mov_b32_e32 v137, v227
	v_lshlrev_b32_e32 v142, 16, v134
	v_and_b32_e32 v143, 0xffff0000, v134
	v_lshlrev_b32_e32 v134, 16, v135
	v_and_b32_e32 v135, 0xffff0000, v135
	v_lshlrev_b32_e32 v148, 16, v136
	v_and_b32_e32 v149, 0xffff0000, v136
	v_lshlrev_b32_e32 v136, 16, v137
	v_and_b32_e32 v137, 0xffff0000, v137
	s_waitcnt vmcnt(2)
	v_mov_b32_e32 v138, v228
	v_mov_b32_e32 v139, v229
	v_mov_b32_e32 v140, v230
	v_mov_b32_e32 v141, v231
	v_lshlrev_b32_e32 v150, 16, v138
	v_and_b32_e32 v151, 0xffff0000, v138
	v_lshlrev_b32_e32 v138, 16, v139
	v_and_b32_e32 v139, 0xffff0000, v139
	v_lshlrev_b32_e32 v152, 16, v140
	v_and_b32_e32 v153, 0xffff0000, v140
	v_lshlrev_b32_e32 v140, 16, v141
	v_and_b32_e32 v141, 0xffff0000, v141
	v_pk_fma_f32 v[30:31], v[134:135], s[24:25], v[30:31] op_sel_hi:[1,0,1]
	v_pk_fma_f32 v[28:29], v[142:143], s[24:25], v[28:29] op_sel_hi:[1,0,1]
	v_pk_fma_f32 v[26:27], v[136:137], s[24:25], v[26:27] op_sel_hi:[1,0,1]
	v_pk_fma_f32 v[24:25], v[148:149], s[24:25], v[24:25] op_sel_hi:[1,0,1]
	v_pk_fma_f32 v[22:23], v[138:139], s[24:25], v[22:23] op_sel_hi:[1,0,1]
	v_pk_fma_f32 v[20:21], v[150:151], s[24:25], v[20:21] op_sel_hi:[1,0,1]
	v_pk_fma_f32 v[18:19], v[140:141], s[24:25], v[18:19] op_sel_hi:[1,0,1]
	v_pk_fma_f32 v[16:17], v[152:153], s[24:25], v[16:17] op_sel_hi:[1,0,1]
	v_mov_b32_e32 v134, v77
	v_mov_b32_e32 v135, v78
	v_mov_b32_e32 v148, v76
	v_mov_b32_e32 v149, v79
	v_pk_add_f32 v[134:135], v[134:135], v[148:149]
	v_add_f32_e32 v151, v72, v73
	v_pk_add_f32 v[134:135], v[134:135], v[134:135] op_sel_hi:[0,1]
	v_add_f32_e32 v153, v74, v75
	v_mov_b32_e32 v150, v64
	v_mov_b32_e32 v152, v65
	v_mov_b32_e32 v132, v67
	v_add_f32_e32 v133, 0, v131
	v_mov_b32_e32 v134, v66
	v_pk_add_f32 v[146:147], v[150:151], v[152:153]
	v_pk_add_f32 v[132:133], v[134:135], v[132:133]
	v_xor_b32_e32 v131, 32, v191
	v_pk_add_f32 v[132:133], v[146:147], v[132:133]
	v_cmp_lt_i32_e32 vcc, v131, v154
	v_add_f32_e32 v132, v132, v133
	ds_bpermute_b32 v133, v130, v132
	v_cndmask_b32_e32 v131, v191, v131, vcc
	v_lshlrev_b32_e32 v131, 2, v131
	s_waitcnt lgkmcnt(0)
	v_add_f32_e32 v132, v132, v133
	ds_bpermute_b32 v133, v131, v132
	s_waitcnt lgkmcnt(0)
	v_add_f32_e32 v132, v132, v133
	v_fmamk_f32 v134, v132, 0xbc800000, v83
	v_fmamk_f32 v144, v132, 0xbc800000, v81
	v_fmamk_f32 v146, v132, 0xbc800000, v79
	v_fmamk_f32 v148, v132, 0xbc800000, v77
	v_fmamk_f32 v133, v132, 0xbc800000, v82
	v_fmamk_f32 v135, v132, 0xbc800000, v80
	v_fmamk_f32 v145, v132, 0xbc800000, v78
	v_fmamk_f32 v147, v132, 0xbc800000, v76
	v_fmamk_f32 v150, v132, 0xbc800000, v75
	v_fmamk_f32 v152, v132, 0xbc800000, v73
	v_mul_f32_e32 v144, v144, v144
	v_mul_f32_e32 v134, v134, v134
	v_mul_f32_e32 v148, v148, v148
	v_mul_f32_e32 v146, v146, v146
	v_fmamk_f32 v149, v132, 0xbc800000, v74
	v_fmamk_f32 v151, v132, 0xbc800000, v72
	v_fmamk_f32 v154, v132, 0xbc800000, v67
	v_fmamk_f32 v156, v132, 0xbc800000, v65
	v_mul_f32_e32 v152, v152, v152
	v_mul_f32_e32 v150, v150, v150
	v_fmac_f32_e32 v144, v135, v135
	v_fmac_f32_e32 v134, v133, v133
	v_fmac_f32_e32 v148, v147, v147
	v_fmac_f32_e32 v146, v145, v145
	v_fmamk_f32 v153, v132, 0xbc800000, v66
	v_fmamk_f32 v155, v132, 0xbc800000, v64
	v_mul_f32_e32 v156, v156, v156
	v_mul_f32_e32 v154, v154, v154
	v_fmac_f32_e32 v152, v151, v151
	v_fmac_f32_e32 v150, v149, v149
	v_add_f32_e32 v133, v144, v134
	v_add_f32_e32 v134, v148, v146
	v_fmac_f32_e32 v156, v155, v155
	v_fmac_f32_e32 v154, v153, v153
	v_add_f32_e32 v135, v152, v150
	v_add_f32_e32 v133, v133, v134
	v_add_f32_e32 v144, v156, v154
	v_add_f32_e32 v133, v135, v133
	v_add_f32_e32 v133, v144, v133
	ds_bpermute_b32 v134, v130, v133
	s_waitcnt lgkmcnt(0)
	v_add_f32_e32 v133, v133, v134
	ds_bpermute_b32 v134, v131, v133
	s_waitcnt vmcnt(1)
	v_mov_b32_e32 v136, v232
	v_mov_b32_e32 v137, v233
	v_mov_b32_e32 v138, v234
	v_mov_b32_e32 v139, v235
	v_lshlrev_b32_e32 v144, 16, v136
	v_and_b32_e32 v145, 0xffff0000, v136
	v_lshlrev_b32_e32 v136, 16, v137
	v_and_b32_e32 v137, 0xffff0000, v137
	v_lshlrev_b32_e32 v146, 16, v138
	v_and_b32_e32 v147, 0xffff0000, v138
	v_lshlrev_b32_e32 v138, 16, v139
	v_and_b32_e32 v139, 0xffff0000, v139
	s_waitcnt vmcnt(0)
	v_mov_b32_e32 v140, v236
	v_mov_b32_e32 v141, v237
	v_mov_b32_e32 v142, v238
	v_mov_b32_e32 v143, v239
	v_lshlrev_b32_e32 v148, 16, v140
	v_and_b32_e32 v149, 0xffff0000, v140
	v_lshlrev_b32_e32 v140, 16, v141
	v_and_b32_e32 v141, 0xffff0000, v141
	v_lshlrev_b32_e32 v150, 16, v142
	v_and_b32_e32 v151, 0xffff0000, v142
	v_lshlrev_b32_e32 v142, 16, v143
	v_and_b32_e32 v143, 0xffff0000, v143
	v_pk_fma_f32 v[14:15], v[136:137], s[24:25], v[14:15] op_sel_hi:[1,0,1]
	v_pk_fma_f32 v[12:13], v[144:145], s[24:25], v[12:13] op_sel_hi:[1,0,1]
	v_pk_fma_f32 v[10:11], v[138:139], s[24:25], v[10:11] op_sel_hi:[1,0,1]
	v_pk_fma_f32 v[8:9], v[146:147], s[24:25], v[8:9] op_sel_hi:[1,0,1]
	v_pk_fma_f32 v[6:7], v[140:141], s[24:25], v[6:7] op_sel_hi:[1,0,1]
	v_pk_fma_f32 v[4:5], v[148:149], s[24:25], v[4:5] op_sel_hi:[1,0,1]
	v_pk_fma_f32 v[2:3], v[142:143], s[24:25], v[2:3] op_sel_hi:[1,0,1]
	v_pk_fma_f32 v[0:1], v[150:151], s[24:25], v[0:1] op_sel_hi:[1,0,1]
	s_nop 0
	s_and_saveexec_b64 s[8:9], s[0:1]
	s_cbranch_execz .LBB0_1286
	s_lshl_b32 s29, s59, 11
	s_add_i32 s29, s28, s29
	v_mul_f32_e32 v132, 0x3c800000, v132
	v_add_u32_e32 v135, s29, v183
	s_waitcnt lgkmcnt(0)
	v_add_f32_e32 v133, v133, v134
	ds_write_b64 v135, v[132:133]
